# GEMM mainloop: LDS-DMA issue spread over two MFMA groups (5+5) instead of a burst after the barrier
# speedup vs baseline: 1.0105x; 1.0105x over previous
.LBB0_150:
	s_ashr_i32 s4, s35, 31
	s_lshr_b32 s4, s4, 26
	s_add_i32 s4, s35, s4
	s_ashr_i32 s6, s4, 6
	s_and_b32 s4, s4, 0x3ffffc0
	s_sub_i32 s4, s35, s4
	s_mulk_i32 s4, 0xc0
	v_add_u32_e32 v2, s4, v1
	s_lshr_b32 s7, s4, 6
	s_lshl_b32 s5, s6, 7
	v_ashrrev_i32_e32 v3, 31, v2
	s_add_i32 s7, s7, s6
	v_lshlrev_b64 v[2:3], 11, v[2:3]
	v_or_b32_e32 v4, s5, v1
	s_lshl_b32 s6, s7, 6
	s_lshl_b32 s7, s7, 7
	v_ashrrev_i32_e32 v5, 31, v4
	v_lshl_add_u64 v[104:105], v[100:101], 0, v[2:3]
	s_and_b32 s14, s7, 0x780
	v_readfirstlane_b32 s7, v112
	v_lshlrev_b64 v[4:5], 11, v[4:5]
	v_lshl_add_u64 v[2:3], v[104:105], 0, s[14:15]
	s_mov_b32 m0, s7
	v_readfirstlane_b32 s7, v124
	v_lshl_add_u64 v[106:107], v[102:103], 0, v[4:5]
	s_waitcnt vmcnt(0)
	s_barrier
	s_load_dwordx2 s[66:67], s[0:1], 0x90
	s_load_dwordx2 s[68:69], s[0:1], 0xc0
	v_and_b32_e32 v201, 0x3ff, v0
	v_readfirstlane_b32 s80, v0
	v_and_b32_e32 v200, 31, v201
	v_bfe_u32 v214, v201, 1, 3
	v_bfe_u32 v213, v201, 5, 1
	v_xor_b32_e32 v214, v214, v213
	v_lshlrev_b32_e32 v214, 4, v214
	s_and_b32 s80, s80, 0x3ff
	s_lshr_b32 s83, s80, 6
	s_lshl_b32 s80, s80, 4
	s_lshr_b32 s84, s83, 1
	s_and_b32 s83, s83, 1
	s_mul_i32 s84, s84, 0x3000
	s_lshl_b32 s83, s83, 13
	s_add_u32 s83, s83, 0xc000
	v_lshlrev_b32_e32 v200, 7, v200
	v_or_b32_e32 v200, v200, v214
	v_add_u32_e32 v215, s84, v200
	v_add_u32_e32 v211, s83, v200
	v_xor_b32_e32 v214, 0x20, v215
	v_xor_b32_e32 v210, 0x20, v211
	v_xor_b32_e32 v213, 0x40, v215
	v_xor_b32_e32 v209, 0x40, v211
	v_xor_b32_e32 v212, 0x60, v215
	v_xor_b32_e32 v208, 0x60, v211
	v_bfe_u32 v200, v201, 4, 3
	v_and_b32_e32 v206, 7, v201
	v_xor_b32_e32 v200, v200, v206
	v_lshlrev_b32_e32 v200, 4, v200
	v_lshrrev_b32_e32 v206, 3, v201
	v_lshl_or_b32 v207, v206, 11, v200
	v_add_u32_e32 v206, 0x10000, v207
	v_add_u32_e32 v205, 0x20000, v207
	v_add_u32_e32 v204, 0x30000, v207
	v_add_u32_e32 v203, 0x40000, v207
	v_add_u32_e32 v202, 0x50000, v207
	s_lshr_b32 s83, s35, 6
	s_and_b32 s84, s35, 63
	s_mov_b32 s79, 0
	s_mul_i32 s84, s84, 0x60000
	s_lshl_b32 s83, s83, 18
	s_waitcnt lgkmcnt(0)
	s_add_u32 s66, s66, s84
	s_addc_u32 s67, s67, 0
	s_add_u32 s68, s68, s83
	s_addc_u32 s69, s69, 0
	s_add_u32 s83, s79, 0
	s_and_b32 s83, s83, 15
	s_lshl_b32 s83, s83, 7
	s_add_u32 s70, s66, s83
	s_addc_u32 s71, s67, 0
	s_add_u32 s72, s68, s83
	s_addc_u32 s73, s69, 0
	s_add_u32 s81, s80, 0x0
	s_add_u32 s82, s80, 0xc000
	s_add_u32 m0, s81, 0x0
	s_nop 0
	global_load_lds_dwordx4 v207, s[70:71]
	s_add_u32 m0, s81, 0x1000
	s_nop 0
	global_load_lds_dwordx4 v206, s[70:71]
	s_add_u32 m0, s81, 0x2000
	s_nop 0
	global_load_lds_dwordx4 v205, s[70:71]
	s_add_u32 m0, s81, 0x3000
	s_nop 0
	global_load_lds_dwordx4 v204, s[70:71]
	s_add_u32 m0, s81, 0x4000
	s_nop 0
	global_load_lds_dwordx4 v203, s[70:71]
	s_add_u32 m0, s81, 0x5000
	s_nop 0
	global_load_lds_dwordx4 v202, s[70:71]
	s_add_u32 m0, s82, 0x0
	s_nop 0
	global_load_lds_dwordx4 v207, s[72:73]
	s_add_u32 m0, s82, 0x1000
	s_nop 0
	global_load_lds_dwordx4 v206, s[72:73]
	s_add_u32 m0, s82, 0x2000
	s_nop 0
	global_load_lds_dwordx4 v205, s[72:73]
	s_add_u32 m0, s82, 0x3000
	s_nop 0
	global_load_lds_dwordx4 v204, s[72:73]
	s_add_u32 s83, s79, 1
	s_and_b32 s83, s83, 15
	s_lshl_b32 s83, s83, 7
	s_add_u32 s70, s66, s83
	s_addc_u32 s71, s67, 0
	s_add_u32 s72, s68, s83
	s_addc_u32 s73, s69, 0
	s_add_u32 s81, s80, 0x6000
	s_add_u32 s82, s80, 0x10000
	s_add_u32 m0, s81, 0x0
	s_nop 0
	global_load_lds_dwordx4 v207, s[70:71]
	s_add_u32 m0, s81, 0x1000
	s_nop 0
	global_load_lds_dwordx4 v206, s[70:71]
	s_add_u32 m0, s81, 0x2000
	s_nop 0
	global_load_lds_dwordx4 v205, s[70:71]
	s_add_u32 m0, s81, 0x3000
	s_nop 0
	global_load_lds_dwordx4 v204, s[70:71]
	s_add_u32 m0, s81, 0x4000
	s_nop 0
	global_load_lds_dwordx4 v203, s[70:71]
	v_mov_b32_e32 v2, 0
	v_mov_b32_e32 v3, 0
	v_mov_b32_e32 v4, 0
	v_mov_b32_e32 v5, 0
	v_mov_b32_e32 v6, 0
	v_mov_b32_e32 v7, 0
	v_mov_b32_e32 v8, 0
	v_mov_b32_e32 v9, 0
	v_mov_b32_e32 v10, 0
	v_mov_b32_e32 v11, 0
	v_mov_b32_e32 v12, 0
	v_mov_b32_e32 v13, 0
	v_mov_b32_e32 v14, 0
	v_mov_b32_e32 v15, 0
	v_mov_b32_e32 v16, 0
	v_mov_b32_e32 v17, 0
	v_mov_b32_e32 v18, 0
	v_mov_b32_e32 v19, 0
	v_mov_b32_e32 v20, 0
	v_mov_b32_e32 v21, 0
	v_mov_b32_e32 v22, 0
	v_mov_b32_e32 v23, 0
	v_mov_b32_e32 v24, 0
	v_mov_b32_e32 v25, 0
	v_mov_b32_e32 v26, 0
	v_mov_b32_e32 v27, 0
	v_mov_b32_e32 v28, 0
	v_mov_b32_e32 v29, 0
	v_mov_b32_e32 v30, 0
	v_mov_b32_e32 v31, 0
	v_mov_b32_e32 v32, 0
	v_mov_b32_e32 v33, 0
	v_mov_b32_e32 v34, 0
	v_mov_b32_e32 v35, 0
	v_mov_b32_e32 v36, 0
	v_mov_b32_e32 v37, 0
	v_mov_b32_e32 v38, 0
	v_mov_b32_e32 v39, 0
	v_mov_b32_e32 v40, 0
	v_mov_b32_e32 v41, 0
	v_mov_b32_e32 v42, 0
	v_mov_b32_e32 v43, 0
	v_mov_b32_e32 v44, 0
	v_mov_b32_e32 v45, 0
	v_mov_b32_e32 v46, 0
	v_mov_b32_e32 v47, 0
	v_mov_b32_e32 v48, 0
	v_mov_b32_e32 v49, 0
	v_mov_b32_e32 v50, 0
	v_mov_b32_e32 v51, 0
	v_mov_b32_e32 v52, 0
	v_mov_b32_e32 v53, 0
	v_mov_b32_e32 v54, 0
	v_mov_b32_e32 v55, 0
	v_mov_b32_e32 v56, 0
	v_mov_b32_e32 v57, 0
	v_mov_b32_e32 v58, 0
	v_mov_b32_e32 v59, 0
	v_mov_b32_e32 v60, 0
	v_mov_b32_e32 v61, 0
	v_mov_b32_e32 v62, 0
	v_mov_b32_e32 v63, 0
	v_mov_b32_e32 v64, 0
	v_mov_b32_e32 v65, 0
	v_mov_b32_e32 v66, 0
	v_mov_b32_e32 v67, 0
	v_mov_b32_e32 v68, 0
	v_mov_b32_e32 v69, 0
	v_mov_b32_e32 v70, 0
	v_mov_b32_e32 v71, 0
	v_mov_b32_e32 v72, 0
	v_mov_b32_e32 v73, 0
	v_mov_b32_e32 v74, 0
	v_mov_b32_e32 v75, 0
	v_mov_b32_e32 v76, 0
	v_mov_b32_e32 v77, 0
	v_mov_b32_e32 v78, 0
	v_mov_b32_e32 v79, 0
	v_mov_b32_e32 v80, 0
	v_mov_b32_e32 v81, 0
	v_mov_b32_e32 v82, 0
	v_mov_b32_e32 v83, 0
	v_mov_b32_e32 v84, 0
	v_mov_b32_e32 v85, 0
	v_mov_b32_e32 v86, 0
	v_mov_b32_e32 v87, 0
	v_mov_b32_e32 v88, 0
	v_mov_b32_e32 v89, 0
	v_mov_b32_e32 v90, 0
	v_mov_b32_e32 v91, 0
	v_mov_b32_e32 v92, 0
	v_mov_b32_e32 v93, 0
	v_mov_b32_e32 v94, 0
	v_mov_b32_e32 v95, 0
	v_mov_b32_e32 v96, 0
	v_mov_b32_e32 v97, 0
	s_waitcnt vmcnt(5)
	s_barrier
	ds_read_b128 v[240:243], v211 offset:0
	ds_read_b128 v[252:255], v215 offset:0
	ds_read_b128 v[236:239], v211 offset:4096
	ds_read_b128 v[248:251], v215 offset:4096
	ds_read_b128 v[244:247], v215 offset:8192
	s_mov_b32 s78, 0
.Lgm_ph2_loop:
	s_waitcnt lgkmcnt(1)
	v_mfma_f32_32x32x16_bf16 v[82:97], v[240:243], v[252:255], v[82:97]
	ds_read_b128 v[220:223], v210 offset:0
	s_add_u32 m0, s81, 0x5000
	s_nop 0
	global_load_lds_dwordx4 v202, s[70:71]
	v_mfma_f32_32x32x16_bf16 v[66:81], v[236:239], v[252:255], v[66:81]
	ds_read_b128 v[232:235], v214 offset:0
	s_add_u32 m0, s82, 0x0
	s_nop 0
	global_load_lds_dwordx4 v207, s[72:73]
	v_mfma_f32_32x32x16_bf16 v[50:65], v[240:243], v[248:251], v[50:65]
	ds_read_b128 v[216:219], v210 offset:4096
	s_add_u32 m0, s82, 0x1000
	s_nop 0
	global_load_lds_dwordx4 v206, s[72:73]
	v_mfma_f32_32x32x16_bf16 v[34:49], v[236:239], v[248:251], v[34:49]
	ds_read_b128 v[228:231], v214 offset:4096
	s_add_u32 m0, s82, 0x2000
	s_nop 0
	global_load_lds_dwordx4 v205, s[72:73]
	s_waitcnt lgkmcnt(4)
	v_mfma_f32_32x32x16_bf16 v[18:33], v[240:243], v[244:247], v[18:33]
	ds_read_b128 v[224:227], v214 offset:8192
	v_mfma_f32_32x32x16_bf16 v[2:17], v[236:239], v[244:247], v[2:17]
	s_add_u32 m0, s82, 0x3000
	s_nop 0
	global_load_lds_dwordx4 v204, s[72:73]
	s_waitcnt lgkmcnt(1)
	v_mfma_f32_32x32x16_bf16 v[82:97], v[220:223], v[232:235], v[82:97]
	ds_read_b128 v[240:243], v209 offset:0
	v_mfma_f32_32x32x16_bf16 v[66:81], v[216:219], v[232:235], v[66:81]
	ds_read_b128 v[252:255], v213 offset:0
	v_mfma_f32_32x32x16_bf16 v[50:65], v[220:223], v[228:231], v[50:65]
	ds_read_b128 v[236:239], v209 offset:4096
	v_mfma_f32_32x32x16_bf16 v[34:49], v[216:219], v[228:231], v[34:49]
	ds_read_b128 v[248:251], v213 offset:4096
	s_waitcnt lgkmcnt(4)
	v_mfma_f32_32x32x16_bf16 v[18:33], v[220:223], v[224:227], v[18:33]
	ds_read_b128 v[244:247], v213 offset:8192
	v_mfma_f32_32x32x16_bf16 v[2:17], v[216:219], v[224:227], v[2:17]
	s_waitcnt lgkmcnt(1)
	v_mfma_f32_32x32x16_bf16 v[82:97], v[240:243], v[252:255], v[82:97]
	ds_read_b128 v[220:223], v208 offset:0
	s_add_u32 s83, s79, s78
	s_add_u32 s83, s83, 2
	s_and_b32 s83, s83, 15
	v_mfma_f32_32x32x16_bf16 v[66:81], v[236:239], v[252:255], v[66:81]
	ds_read_b128 v[232:235], v212 offset:0
	s_lshl_b32 s83, s83, 7
	s_add_u32 s70, s66, s83
	v_mfma_f32_32x32x16_bf16 v[50:65], v[240:243], v[248:251], v[50:65]
	ds_read_b128 v[216:219], v208 offset:4096
	s_addc_u32 s71, s67, 0
	s_add_u32 s72, s68, s83
	v_mfma_f32_32x32x16_bf16 v[34:49], v[236:239], v[248:251], v[34:49]
	ds_read_b128 v[228:231], v212 offset:4096
	s_addc_u32 s73, s69, 0
	s_add_u32 s81, s80, 0x0
	s_add_u32 s82, s80, 0xc000
	s_waitcnt lgkmcnt(4)
	v_mfma_f32_32x32x16_bf16 v[18:33], v[240:243], v[244:247], v[18:33]
	ds_read_b128 v[224:227], v212 offset:8192
	v_mfma_f32_32x32x16_bf16 v[2:17], v[236:239], v[244:247], v[2:17]
	s_waitcnt vmcnt(0) lgkmcnt(0)
	s_barrier
	v_mfma_f32_32x32x16_bf16 v[82:97], v[220:223], v[232:235], v[82:97]
	s_add_u32 m0, s81, 0x0
	ds_read_b128 v[240:243], v211 offset:16384
	global_load_lds_dwordx4 v207, s[70:71]
	v_mfma_f32_32x32x16_bf16 v[66:81], v[216:219], v[232:235], v[66:81]
	s_add_u32 m0, s81, 0x1000
	ds_read_b128 v[252:255], v215 offset:24576
	global_load_lds_dwordx4 v206, s[70:71]
	v_mfma_f32_32x32x16_bf16 v[50:65], v[220:223], v[228:231], v[50:65]
	s_add_u32 m0, s81, 0x2000
	ds_read_b128 v[236:239], v211 offset:20480
	global_load_lds_dwordx4 v205, s[70:71]
	v_mfma_f32_32x32x16_bf16 v[34:49], v[216:219], v[228:231], v[34:49]
	s_add_u32 m0, s81, 0x3000
	ds_read_b128 v[248:251], v215 offset:28672
	global_load_lds_dwordx4 v204, s[70:71]
	v_mfma_f32_32x32x16_bf16 v[18:33], v[220:223], v[224:227], v[18:33]
	s_add_u32 m0, s81, 0x4000
	ds_read_b128 v[244:247], v215 offset:32768
	global_load_lds_dwordx4 v203, s[70:71]
	v_mfma_f32_32x32x16_bf16 v[2:17], v[216:219], v[224:227], v[2:17]
	s_waitcnt lgkmcnt(1)
	v_mfma_f32_32x32x16_bf16 v[82:97], v[240:243], v[252:255], v[82:97]
	ds_read_b128 v[220:223], v210 offset:16384
	s_add_u32 m0, s81, 0x5000
	s_nop 0
	global_load_lds_dwordx4 v202, s[70:71]
	v_mfma_f32_32x32x16_bf16 v[66:81], v[236:239], v[252:255], v[66:81]
	ds_read_b128 v[232:235], v214 offset:24576
	s_add_u32 m0, s82, 0x0
	s_nop 0
	global_load_lds_dwordx4 v207, s[72:73]
	v_mfma_f32_32x32x16_bf16 v[50:65], v[240:243], v[248:251], v[50:65]
	ds_read_b128 v[216:219], v210 offset:20480
	s_add_u32 m0, s82, 0x1000
	s_nop 0
	global_load_lds_dwordx4 v206, s[72:73]
	v_mfma_f32_32x32x16_bf16 v[34:49], v[236:239], v[248:251], v[34:49]
	ds_read_b128 v[228:231], v214 offset:28672
	s_add_u32 m0, s82, 0x2000
	s_nop 0
	global_load_lds_dwordx4 v205, s[72:73]
	s_waitcnt lgkmcnt(4)
	v_mfma_f32_32x32x16_bf16 v[18:33], v[240:243], v[244:247], v[18:33]
	ds_read_b128 v[224:227], v214 offset:32768
	v_mfma_f32_32x32x16_bf16 v[2:17], v[236:239], v[244:247], v[2:17]
	s_add_u32 m0, s82, 0x3000
	s_nop 0
	global_load_lds_dwordx4 v204, s[72:73]
	s_waitcnt lgkmcnt(1)
	v_mfma_f32_32x32x16_bf16 v[82:97], v[220:223], v[232:235], v[82:97]
	ds_read_b128 v[240:243], v209 offset:16384
	v_mfma_f32_32x32x16_bf16 v[66:81], v[216:219], v[232:235], v[66:81]
	ds_read_b128 v[252:255], v213 offset:24576
	v_mfma_f32_32x32x16_bf16 v[50:65], v[220:223], v[228:231], v[50:65]
	ds_read_b128 v[236:239], v209 offset:20480
	v_mfma_f32_32x32x16_bf16 v[34:49], v[216:219], v[228:231], v[34:49]
	ds_read_b128 v[248:251], v213 offset:28672
	s_waitcnt lgkmcnt(4)
	v_mfma_f32_32x32x16_bf16 v[18:33], v[220:223], v[224:227], v[18:33]
	ds_read_b128 v[244:247], v213 offset:32768
	v_mfma_f32_32x32x16_bf16 v[2:17], v[216:219], v[224:227], v[2:17]
	s_waitcnt lgkmcnt(1)
	v_mfma_f32_32x32x16_bf16 v[82:97], v[240:243], v[252:255], v[82:97]
	ds_read_b128 v[220:223], v208 offset:16384
	s_add_u32 s83, s79, s78
	s_add_u32 s83, s83, 3
	s_and_b32 s83, s83, 15
	v_mfma_f32_32x32x16_bf16 v[66:81], v[236:239], v[252:255], v[66:81]
	ds_read_b128 v[232:235], v212 offset:24576
	s_lshl_b32 s83, s83, 7
	s_add_u32 s70, s66, s83
	v_mfma_f32_32x32x16_bf16 v[50:65], v[240:243], v[248:251], v[50:65]
	ds_read_b128 v[216:219], v208 offset:20480
	s_addc_u32 s71, s67, 0
	s_add_u32 s72, s68, s83
	v_mfma_f32_32x32x16_bf16 v[34:49], v[236:239], v[248:251], v[34:49]
	ds_read_b128 v[228:231], v212 offset:28672
	s_addc_u32 s73, s69, 0
	s_add_u32 s81, s80, 0x6000
	s_add_u32 s82, s80, 0x10000
	s_waitcnt lgkmcnt(4)
	v_mfma_f32_32x32x16_bf16 v[18:33], v[240:243], v[244:247], v[18:33]
	ds_read_b128 v[224:227], v212 offset:32768
	v_mfma_f32_32x32x16_bf16 v[2:17], v[236:239], v[244:247], v[2:17]
	s_waitcnt vmcnt(0) lgkmcnt(0)
	s_barrier
	v_mfma_f32_32x32x16_bf16 v[82:97], v[220:223], v[232:235], v[82:97]
	s_add_u32 m0, s81, 0x0
	ds_read_b128 v[240:243], v211 offset:0
	global_load_lds_dwordx4 v207, s[70:71]
	v_mfma_f32_32x32x16_bf16 v[66:81], v[216:219], v[232:235], v[66:81]
	s_add_u32 m0, s81, 0x1000
	ds_read_b128 v[252:255], v215 offset:0
	global_load_lds_dwordx4 v206, s[70:71]
	v_mfma_f32_32x32x16_bf16 v[50:65], v[220:223], v[228:231], v[50:65]
	s_add_u32 m0, s81, 0x2000
	ds_read_b128 v[236:239], v211 offset:4096
	global_load_lds_dwordx4 v205, s[70:71]
	v_mfma_f32_32x32x16_bf16 v[34:49], v[216:219], v[228:231], v[34:49]
	s_add_u32 m0, s81, 0x3000
	ds_read_b128 v[248:251], v215 offset:4096
	global_load_lds_dwordx4 v204, s[70:71]
	v_mfma_f32_32x32x16_bf16 v[18:33], v[220:223], v[224:227], v[18:33]
	s_add_u32 m0, s81, 0x4000
	ds_read_b128 v[244:247], v215 offset:8192
	global_load_lds_dwordx4 v203, s[70:71]
	v_mfma_f32_32x32x16_bf16 v[2:17], v[216:219], v[224:227], v[2:17]
	s_add_u32 s78, s78, 2
	s_cmp_lt_u32 s78, 14
	s_cbranch_scc1 .Lgm_ph2_loop
	s_waitcnt lgkmcnt(1)
	v_mfma_f32_32x32x16_bf16 v[82:97], v[240:243], v[252:255], v[82:97]
	ds_read_b128 v[220:223], v210 offset:0
	s_add_u32 m0, s81, 0x5000
	s_nop 0
	global_load_lds_dwordx4 v202, s[70:71]
	v_mfma_f32_32x32x16_bf16 v[66:81], v[236:239], v[252:255], v[66:81]
	ds_read_b128 v[232:235], v214 offset:0
	s_add_u32 m0, s82, 0x0
	s_nop 0
	global_load_lds_dwordx4 v207, s[72:73]
	v_mfma_f32_32x32x16_bf16 v[50:65], v[240:243], v[248:251], v[50:65]
	ds_read_b128 v[216:219], v210 offset:4096
	s_add_u32 m0, s82, 0x1000
	s_nop 0
	global_load_lds_dwordx4 v206, s[72:73]
	v_mfma_f32_32x32x16_bf16 v[34:49], v[236:239], v[248:251], v[34:49]
	ds_read_b128 v[228:231], v214 offset:4096
	s_add_u32 m0, s82, 0x2000
	s_nop 0
	global_load_lds_dwordx4 v205, s[72:73]
	s_waitcnt lgkmcnt(4)
	v_mfma_f32_32x32x16_bf16 v[18:33], v[240:243], v[244:247], v[18:33]
	ds_read_b128 v[224:227], v214 offset:8192
	v_mfma_f32_32x32x16_bf16 v[2:17], v[236:239], v[244:247], v[2:17]
	s_add_u32 m0, s82, 0x3000
	s_nop 0
	global_load_lds_dwordx4 v204, s[72:73]
	s_waitcnt lgkmcnt(1)
	v_mfma_f32_32x32x16_bf16 v[82:97], v[220:223], v[232:235], v[82:97]
	ds_read_b128 v[240:243], v209 offset:0
	v_mfma_f32_32x32x16_bf16 v[66:81], v[216:219], v[232:235], v[66:81]
	ds_read_b128 v[252:255], v213 offset:0
	v_mfma_f32_32x32x16_bf16 v[50:65], v[220:223], v[228:231], v[50:65]
	ds_read_b128 v[236:239], v209 offset:4096
	v_mfma_f32_32x32x16_bf16 v[34:49], v[216:219], v[228:231], v[34:49]
	ds_read_b128 v[248:251], v213 offset:4096
	s_waitcnt lgkmcnt(4)
	v_mfma_f32_32x32x16_bf16 v[18:33], v[220:223], v[224:227], v[18:33]
	ds_read_b128 v[244:247], v213 offset:8192
	v_mfma_f32_32x32x16_bf16 v[2:17], v[216:219], v[224:227], v[2:17]
	s_waitcnt lgkmcnt(1)
	v_mfma_f32_32x32x16_bf16 v[82:97], v[240:243], v[252:255], v[82:97]
	ds_read_b128 v[220:223], v208 offset:0
	v_mfma_f32_32x32x16_bf16 v[66:81], v[236:239], v[252:255], v[66:81]
	ds_read_b128 v[232:235], v212 offset:0
	v_mfma_f32_32x32x16_bf16 v[50:65], v[240:243], v[248:251], v[50:65]
	ds_read_b128 v[216:219], v208 offset:4096
	v_mfma_f32_32x32x16_bf16 v[34:49], v[236:239], v[248:251], v[34:49]
	ds_read_b128 v[228:231], v212 offset:4096
	s_waitcnt lgkmcnt(4)
	v_mfma_f32_32x32x16_bf16 v[18:33], v[240:243], v[244:247], v[18:33]
	ds_read_b128 v[224:227], v212 offset:8192
	v_mfma_f32_32x32x16_bf16 v[2:17], v[236:239], v[244:247], v[2:17]
	s_waitcnt vmcnt(0) lgkmcnt(0)
	s_barrier
	v_mfma_f32_32x32x16_bf16 v[82:97], v[220:223], v[232:235], v[82:97]
	ds_read_b128 v[240:243], v211 offset:16384
	v_mfma_f32_32x32x16_bf16 v[66:81], v[216:219], v[232:235], v[66:81]
	ds_read_b128 v[252:255], v215 offset:24576
	v_mfma_f32_32x32x16_bf16 v[50:65], v[220:223], v[228:231], v[50:65]
	ds_read_b128 v[236:239], v211 offset:20480
	v_mfma_f32_32x32x16_bf16 v[34:49], v[216:219], v[228:231], v[34:49]
	ds_read_b128 v[248:251], v215 offset:28672
	v_mfma_f32_32x32x16_bf16 v[18:33], v[220:223], v[224:227], v[18:33]
	ds_read_b128 v[244:247], v215 offset:32768
	v_mfma_f32_32x32x16_bf16 v[2:17], v[216:219], v[224:227], v[2:17]
	s_waitcnt lgkmcnt(1)
	v_mfma_f32_32x32x16_bf16 v[82:97], v[240:243], v[252:255], v[82:97]
	ds_read_b128 v[220:223], v210 offset:16384
	v_mfma_f32_32x32x16_bf16 v[66:81], v[236:239], v[252:255], v[66:81]
	ds_read_b128 v[232:235], v214 offset:24576
	v_mfma_f32_32x32x16_bf16 v[50:65], v[240:243], v[248:251], v[50:65]
	ds_read_b128 v[216:219], v210 offset:20480
	v_mfma_f32_32x32x16_bf16 v[34:49], v[236:239], v[248:251], v[34:49]
	ds_read_b128 v[228:231], v214 offset:28672
	s_waitcnt lgkmcnt(4)
	v_mfma_f32_32x32x16_bf16 v[18:33], v[240:243], v[244:247], v[18:33]
	ds_read_b128 v[224:227], v214 offset:32768
	v_mfma_f32_32x32x16_bf16 v[2:17], v[236:239], v[244:247], v[2:17]
	s_waitcnt lgkmcnt(1)
	v_mfma_f32_32x32x16_bf16 v[82:97], v[220:223], v[232:235], v[82:97]
	ds_read_b128 v[240:243], v209 offset:16384
	v_mfma_f32_32x32x16_bf16 v[66:81], v[216:219], v[232:235], v[66:81]
	ds_read_b128 v[252:255], v213 offset:24576
	v_mfma_f32_32x32x16_bf16 v[50:65], v[220:223], v[228:231], v[50:65]
	ds_read_b128 v[236:239], v209 offset:20480
	v_mfma_f32_32x32x16_bf16 v[34:49], v[216:219], v[228:231], v[34:49]
	ds_read_b128 v[248:251], v213 offset:28672
	s_waitcnt lgkmcnt(4)
	v_mfma_f32_32x32x16_bf16 v[18:33], v[220:223], v[224:227], v[18:33]
	ds_read_b128 v[244:247], v213 offset:32768
	v_mfma_f32_32x32x16_bf16 v[2:17], v[216:219], v[224:227], v[2:17]
	s_waitcnt lgkmcnt(1)
	v_mfma_f32_32x32x16_bf16 v[82:97], v[240:243], v[252:255], v[82:97]
	ds_read_b128 v[220:223], v208 offset:16384
	v_mfma_f32_32x32x16_bf16 v[66:81], v[236:239], v[252:255], v[66:81]
	ds_read_b128 v[232:235], v212 offset:24576
	v_mfma_f32_32x32x16_bf16 v[50:65], v[240:243], v[248:251], v[50:65]
	ds_read_b128 v[216:219], v208 offset:20480
	v_mfma_f32_32x32x16_bf16 v[34:49], v[236:239], v[248:251], v[34:49]
	ds_read_b128 v[228:231], v212 offset:28672
	s_waitcnt lgkmcnt(4)
	v_mfma_f32_32x32x16_bf16 v[18:33], v[240:243], v[244:247], v[18:33]
	ds_read_b128 v[224:227], v212 offset:32768
	v_mfma_f32_32x32x16_bf16 v[2:17], v[236:239], v[244:247], v[2:17]
	s_waitcnt vmcnt(0) lgkmcnt(0)
	s_barrier
	v_mfma_f32_32x32x16_bf16 v[82:97], v[220:223], v[232:235], v[82:97]
	v_mfma_f32_32x32x16_bf16 v[66:81], v[216:219], v[232:235], v[66:81]
	v_mfma_f32_32x32x16_bf16 v[50:65], v[220:223], v[228:231], v[50:65]
	v_mfma_f32_32x32x16_bf16 v[34:49], v[216:219], v[228:231], v[34:49]
	v_mfma_f32_32x32x16_bf16 v[18:33], v[220:223], v[224:227], v[18:33]
	v_mfma_f32_32x32x16_bf16 v[2:17], v[216:219], v[224:227], v[2:17]
	s_nop 7
	s_nop 7
	v_add_u32_e32 v147, v115, v118
	s_nop 4
	v_add_u32_e32 v98, v117, v121
	s_nop 4
	s_waitcnt lgkmcnt(0)
	v_or_b32_e32 v142, s5, v122
	v_cmp_lt_i32_e64 s[6:7], s3, v142
	v_add_u32_e32 v106, s4, v114
	v_ashrrev_i32_e32 v107, 31, v106
	v_lshlrev_b64 v[110:111], 11, v[106:107]
	v_or_b32_e32 v104, v142, v123
	v_lshl_add_u64 v[108:109], s[10:11], 0, v[110:111]
	s_and_saveexec_b64 s[4:5], s[6:7]
	s_xor_b64 s[4:5], exec, s[4:5]
	s_cbranch_execz .LBB0_154
	v_mul_f32_e32 v98, 0xbfb8aa3b, v82
	v_exp_f32_e32 v144, v98
	v_mul_f32_e32 v98, 0xbfb8aa3b, v83
	v_exp_f32_e32 v145, v98
	s_nop 0
	v_pk_add_f32 v[144:145], v[144:145], 1.0 op_sel_hi:[1,0]
	s_nop 0
	v_div_scale_f32 v98, s[30:31], v145, v145, v83
	v_rcp_f32_e32 v105, v98
	v_div_scale_f32 v107, vcc, v83, v145, v83
	v_fma_f32 v143, -v98, v105, 1.0
	v_fmac_f32_e32 v105, v143, v105
	v_mul_f32_e32 v143, v107, v105
	v_fma_f32 v147, -v98, v143, v107
	v_fmac_f32_e32 v143, v147, v105
	v_fma_f32 v98, -v98, v143, v107
	v_div_scale_f32 v107, s[30:31], v144, v144, v82
	v_rcp_f32_e32 v147, v107
	v_div_fmas_f32 v98, v98, v105, v143
	v_div_fixup_f32 v98, v98, v145, v83
	v_mul_f32_e32 v145, 0xbfb8aa3b, v84
	v_exp_f32_e32 v150, v145
	v_mul_f32_e32 v145, 0xbfb8aa3b, v85
	v_fma_f32 v105, -v107, v147, 1.0
	v_exp_f32_e32 v151, v145
	v_fmac_f32_e32 v147, v105, v147
	v_div_scale_f32 v105, vcc, v82, v144, v82
	v_mul_f32_e32 v143, v105, v147
	v_fma_f32 v145, -v107, v143, v105
	v_fmac_f32_e32 v143, v145, v147
	v_pk_add_f32 v[150:151], v[150:151], 1.0 op_sel_hi:[1,0]
	v_fma_f32 v105, -v107, v143, v105
	v_div_scale_f32 v107, s[30:31], v151, v151, v85
	v_rcp_f32_e32 v145, v107
	v_div_fmas_f32 v105, v105, v147, v143
	v_div_fixup_f32 v105, v105, v144, v82
	v_cvt_pk_bf16_f32 v144, v105, v98
	v_fma_f32 v98, -v107, v145, 1.0
	v_fmac_f32_e32 v145, v98, v145
	v_div_scale_f32 v98, vcc, v85, v151, v85
	v_mul_f32_e32 v105, v98, v145
	v_fma_f32 v143, -v107, v105, v98
	v_fmac_f32_e32 v105, v143, v145
	v_fma_f32 v98, -v107, v105, v98
	v_div_scale_f32 v107, s[30:31], v150, v150, v84
	v_rcp_f32_e32 v143, v107
	v_div_fmas_f32 v98, v98, v145, v105
	v_div_fixup_f32 v98, v98, v151, v85
	v_fma_f32 v105, -v107, v143, 1.0
	v_fmac_f32_e32 v143, v105, v143
	v_div_scale_f32 v105, vcc, v84, v150, v84
	v_mul_f32_e32 v145, v105, v143
	v_fma_f32 v147, -v107, v145, v105
	v_fmac_f32_e32 v145, v147, v143
	v_fma_f32 v105, -v107, v145, v105
	v_div_fmas_f32 v105, v105, v143, v145
	v_div_fixup_f32 v105, v105, v150, v84
	v_cvt_pk_bf16_f32 v145, v105, v98
	v_mov_b32_e32 v105, v99
	v_lshl_add_u64 v[150:151], v[104:105], 1, v[108:109]
	global_store_dwordx2 v[150:151], v[144:145], off offset:-2048

.LBB0_489:
	s_ashr_i32 s10, s28, 31
	s_lshr_b32 s10, s10, 26
	s_add_i32 s10, s28, s10
	s_ashr_i32 s31, s10, 6
	s_and_b32 s10, s10, 0x3ffffc0
	s_sub_i32 s29, s28, s10
	s_mulk_i32 s29, 0xc0
	v_add_u32_e32 v2, s29, v108
	s_lshr_b32 s10, s29, 6
	s_lshl_b32 s30, s31, 7
	v_ashrrev_i32_e32 v3, 31, v2
	s_add_i32 s10, s10, s31
	v_lshlrev_b64 v[2:3], 11, v[2:3]
	v_or_b32_e32 v4, s30, v108
	s_lshl_b32 s31, s10, 6
	s_lshl_b32 s10, s10, 7
	v_ashrrev_i32_e32 v5, 31, v4
	v_lshl_add_u64 v[104:105], v[100:101], 0, v[2:3]
	s_and_b32 s10, s10, 0x780
	v_readfirstlane_b32 s34, v109
	v_lshlrev_b64 v[4:5], 11, v[4:5]
	v_lshl_add_u64 v[2:3], v[104:105], 0, s[10:11]
	s_mov_b32 m0, s34
	v_readfirstlane_b32 s34, v128
	v_lshl_add_u64 v[106:107], v[102:103], 0, v[4:5]
	s_waitcnt vmcnt(0)
	s_barrier
	s_load_dwordx2 s[66:67], s[0:1], 0x118
	s_load_dwordx2 s[68:69], s[0:1], 0xd0
	v_and_b32_e32 v201, 0x3ff, v0
	v_readfirstlane_b32 s80, v0
	v_and_b32_e32 v200, 31, v201
	v_bfe_u32 v214, v201, 1, 3
	v_bfe_u32 v213, v201, 5, 1
	v_xor_b32_e32 v214, v214, v213
	v_lshlrev_b32_e32 v214, 4, v214
	s_and_b32 s80, s80, 0x3ff
	s_lshr_b32 s83, s80, 6
	s_lshl_b32 s80, s80, 4
	s_lshr_b32 s84, s83, 1
	s_and_b32 s83, s83, 1
	s_mul_i32 s84, s84, 0x3000
	s_lshl_b32 s83, s83, 13
	s_add_u32 s83, s83, 0xc000
	v_lshlrev_b32_e32 v200, 7, v200
	v_or_b32_e32 v200, v200, v214
	v_add_u32_e32 v215, s84, v200
	v_add_u32_e32 v211, s83, v200
	v_xor_b32_e32 v214, 0x20, v215
	v_xor_b32_e32 v210, 0x20, v211
	v_xor_b32_e32 v213, 0x40, v215
	v_xor_b32_e32 v209, 0x40, v211
	v_xor_b32_e32 v212, 0x60, v215
	v_xor_b32_e32 v208, 0x60, v211
	v_bfe_u32 v200, v201, 4, 3
	v_and_b32_e32 v206, 7, v201
	v_xor_b32_e32 v200, v200, v206
	v_lshlrev_b32_e32 v200, 4, v200
	v_lshrrev_b32_e32 v206, 3, v201
	v_lshl_or_b32 v207, v206, 11, v200
	v_add_u32_e32 v206, 0x10000, v207
	v_add_u32_e32 v205, 0x20000, v207
	v_add_u32_e32 v204, 0x30000, v207
	v_add_u32_e32 v203, 0x40000, v207
	v_add_u32_e32 v202, 0x50000, v207
	s_lshr_b32 s83, s28, 6
	s_and_b32 s84, s28, 63
	s_mov_b32 s79, 0
	s_mul_i32 s84, s84, 0x60000
	s_lshl_b32 s83, s83, 18
	s_waitcnt lgkmcnt(0)
	s_add_u32 s66, s66, s84
	s_addc_u32 s67, s67, 0
	s_add_u32 s68, s68, s83
	s_addc_u32 s69, s69, 0
	s_add_u32 s83, s79, 0
	s_and_b32 s83, s83, 15
	s_lshl_b32 s83, s83, 7
	s_add_u32 s70, s66, s83
	s_addc_u32 s71, s67, 0
	s_add_u32 s72, s68, s83
	s_addc_u32 s73, s69, 0
	s_add_u32 s81, s80, 0x0
	s_add_u32 s82, s80, 0xc000
	s_add_u32 m0, s81, 0x0
	s_nop 0
	global_load_lds_dwordx4 v207, s[70:71]
	s_add_u32 m0, s81, 0x1000
	s_nop 0
	global_load_lds_dwordx4 v206, s[70:71]
	s_add_u32 m0, s81, 0x2000
	s_nop 0
	global_load_lds_dwordx4 v205, s[70:71]
	s_add_u32 m0, s81, 0x3000
	s_nop 0
	global_load_lds_dwordx4 v204, s[70:71]
	s_add_u32 m0, s81, 0x4000
	s_nop 0
	global_load_lds_dwordx4 v203, s[70:71]
	s_add_u32 m0, s81, 0x5000
	s_nop 0
	global_load_lds_dwordx4 v202, s[70:71]
	s_add_u32 m0, s82, 0x0
	s_nop 0
	global_load_lds_dwordx4 v207, s[72:73]
	s_add_u32 m0, s82, 0x1000
	s_nop 0
	global_load_lds_dwordx4 v206, s[72:73]
	s_add_u32 m0, s82, 0x2000
	s_nop 0
	global_load_lds_dwordx4 v205, s[72:73]
	s_add_u32 m0, s82, 0x3000
	s_nop 0
	global_load_lds_dwordx4 v204, s[72:73]
	s_add_u32 s83, s79, 1
	s_and_b32 s83, s83, 15
	s_lshl_b32 s83, s83, 7
	s_add_u32 s70, s66, s83
	s_addc_u32 s71, s67, 0
	s_add_u32 s72, s68, s83
	s_addc_u32 s73, s69, 0
	s_add_u32 s81, s80, 0x6000
	s_add_u32 s82, s80, 0x10000
	s_add_u32 m0, s81, 0x0
	s_nop 0
	global_load_lds_dwordx4 v207, s[70:71]
	s_add_u32 m0, s81, 0x1000
	s_nop 0
	global_load_lds_dwordx4 v206, s[70:71]
	s_add_u32 m0, s81, 0x2000
	s_nop 0
	global_load_lds_dwordx4 v205, s[70:71]
	s_add_u32 m0, s81, 0x3000
	s_nop 0
	global_load_lds_dwordx4 v204, s[70:71]
	s_add_u32 m0, s81, 0x4000
	s_nop 0
	global_load_lds_dwordx4 v203, s[70:71]
	v_mov_b32_e32 v2, 0
	v_mov_b32_e32 v3, 0
	v_mov_b32_e32 v4, 0
	v_mov_b32_e32 v5, 0
	v_mov_b32_e32 v6, 0
	v_mov_b32_e32 v7, 0
	v_mov_b32_e32 v8, 0
	v_mov_b32_e32 v9, 0
	v_mov_b32_e32 v10, 0
	v_mov_b32_e32 v11, 0
	v_mov_b32_e32 v12, 0
	v_mov_b32_e32 v13, 0
	v_mov_b32_e32 v14, 0
	v_mov_b32_e32 v15, 0
	v_mov_b32_e32 v16, 0
	v_mov_b32_e32 v17, 0
	v_mov_b32_e32 v18, 0
	v_mov_b32_e32 v19, 0
	v_mov_b32_e32 v20, 0
	v_mov_b32_e32 v21, 0
	v_mov_b32_e32 v22, 0
	v_mov_b32_e32 v23, 0
	v_mov_b32_e32 v24, 0
	v_mov_b32_e32 v25, 0
	v_mov_b32_e32 v26, 0
	v_mov_b32_e32 v27, 0
	v_mov_b32_e32 v28, 0
	v_mov_b32_e32 v29, 0
	v_mov_b32_e32 v30, 0
	v_mov_b32_e32 v31, 0
	v_mov_b32_e32 v32, 0
	v_mov_b32_e32 v33, 0
	v_mov_b32_e32 v34, 0
	v_mov_b32_e32 v35, 0
	v_mov_b32_e32 v36, 0
	v_mov_b32_e32 v37, 0
	v_mov_b32_e32 v38, 0
	v_mov_b32_e32 v39, 0
	v_mov_b32_e32 v40, 0
	v_mov_b32_e32 v41, 0
	v_mov_b32_e32 v42, 0
	v_mov_b32_e32 v43, 0
	v_mov_b32_e32 v44, 0
	v_mov_b32_e32 v45, 0
	v_mov_b32_e32 v46, 0
	v_mov_b32_e32 v47, 0
	v_mov_b32_e32 v48, 0
	v_mov_b32_e32 v49, 0
	v_mov_b32_e32 v50, 0
	v_mov_b32_e32 v51, 0
	v_mov_b32_e32 v52, 0
	v_mov_b32_e32 v53, 0
	v_mov_b32_e32 v54, 0
	v_mov_b32_e32 v55, 0
	v_mov_b32_e32 v56, 0
	v_mov_b32_e32 v57, 0
	v_mov_b32_e32 v58, 0
	v_mov_b32_e32 v59, 0
	v_mov_b32_e32 v60, 0
	v_mov_b32_e32 v61, 0
	v_mov_b32_e32 v62, 0
	v_mov_b32_e32 v63, 0
	v_mov_b32_e32 v64, 0
	v_mov_b32_e32 v65, 0
	v_mov_b32_e32 v66, 0
	v_mov_b32_e32 v67, 0
	v_mov_b32_e32 v68, 0
	v_mov_b32_e32 v69, 0
	v_mov_b32_e32 v70, 0
	v_mov_b32_e32 v71, 0
	v_mov_b32_e32 v72, 0
	v_mov_b32_e32 v73, 0
	v_mov_b32_e32 v74, 0
	v_mov_b32_e32 v75, 0
	v_mov_b32_e32 v76, 0
	v_mov_b32_e32 v77, 0
	v_mov_b32_e32 v78, 0
	v_mov_b32_e32 v79, 0
	v_mov_b32_e32 v80, 0
	v_mov_b32_e32 v81, 0
	v_mov_b32_e32 v82, 0
	v_mov_b32_e32 v83, 0
	v_mov_b32_e32 v84, 0
	v_mov_b32_e32 v85, 0
	v_mov_b32_e32 v86, 0
	v_mov_b32_e32 v87, 0
	v_mov_b32_e32 v88, 0
	v_mov_b32_e32 v89, 0
	v_mov_b32_e32 v90, 0
	v_mov_b32_e32 v91, 0
	v_mov_b32_e32 v92, 0
	v_mov_b32_e32 v93, 0
	v_mov_b32_e32 v94, 0
	v_mov_b32_e32 v95, 0
	v_mov_b32_e32 v96, 0
	v_mov_b32_e32 v97, 0
	s_waitcnt vmcnt(5)
	s_barrier
	ds_read_b128 v[240:243], v211 offset:0
	ds_read_b128 v[252:255], v215 offset:0
	ds_read_b128 v[236:239], v211 offset:4096
	ds_read_b128 v[248:251], v215 offset:4096
	ds_read_b128 v[244:247], v215 offset:8192
	s_mov_b32 s78, 0
.Lgm_ph5_loop:
	s_waitcnt lgkmcnt(1)
	v_mfma_f32_32x32x16_bf16 v[82:97], v[240:243], v[252:255], v[82:97]
	ds_read_b128 v[220:223], v210 offset:0
	s_add_u32 m0, s81, 0x5000
	s_nop 0
	global_load_lds_dwordx4 v202, s[70:71]
	v_mfma_f32_32x32x16_bf16 v[66:81], v[236:239], v[252:255], v[66:81]
	ds_read_b128 v[232:235], v214 offset:0
	s_add_u32 m0, s82, 0x0
	s_nop 0
	global_load_lds_dwordx4 v207, s[72:73]
	v_mfma_f32_32x32x16_bf16 v[50:65], v[240:243], v[248:251], v[50:65]
	ds_read_b128 v[216:219], v210 offset:4096
	s_add_u32 m0, s82, 0x1000
	s_nop 0
	global_load_lds_dwordx4 v206, s[72:73]
	v_mfma_f32_32x32x16_bf16 v[34:49], v[236:239], v[248:251], v[34:49]
	ds_read_b128 v[228:231], v214 offset:4096
	s_add_u32 m0, s82, 0x2000
	s_nop 0
	global_load_lds_dwordx4 v205, s[72:73]
	s_waitcnt lgkmcnt(4)
	v_mfma_f32_32x32x16_bf16 v[18:33], v[240:243], v[244:247], v[18:33]
	ds_read_b128 v[224:227], v214 offset:8192
	v_mfma_f32_32x32x16_bf16 v[2:17], v[236:239], v[244:247], v[2:17]
	s_add_u32 m0, s82, 0x3000
	s_nop 0
	global_load_lds_dwordx4 v204, s[72:73]
	s_waitcnt lgkmcnt(1)
	v_mfma_f32_32x32x16_bf16 v[82:97], v[220:223], v[232:235], v[82:97]
	ds_read_b128 v[240:243], v209 offset:0
	v_mfma_f32_32x32x16_bf16 v[66:81], v[216:219], v[232:235], v[66:81]
	ds_read_b128 v[252:255], v213 offset:0
	v_mfma_f32_32x32x16_bf16 v[50:65], v[220:223], v[228:231], v[50:65]
	ds_read_b128 v[236:239], v209 offset:4096
	v_mfma_f32_32x32x16_bf16 v[34:49], v[216:219], v[228:231], v[34:49]
	ds_read_b128 v[248:251], v213 offset:4096
	s_waitcnt lgkmcnt(4)
	v_mfma_f32_32x32x16_bf16 v[18:33], v[220:223], v[224:227], v[18:33]
	ds_read_b128 v[244:247], v213 offset:8192
	v_mfma_f32_32x32x16_bf16 v[2:17], v[216:219], v[224:227], v[2:17]
	s_waitcnt lgkmcnt(1)
	v_mfma_f32_32x32x16_bf16 v[82:97], v[240:243], v[252:255], v[82:97]
	ds_read_b128 v[220:223], v208 offset:0
	s_add_u32 s83, s79, s78
	s_add_u32 s83, s83, 2
	s_and_b32 s83, s83, 15
	v_mfma_f32_32x32x16_bf16 v[66:81], v[236:239], v[252:255], v[66:81]
	ds_read_b128 v[232:235], v212 offset:0
	s_lshl_b32 s83, s83, 7
	s_add_u32 s70, s66, s83
	v_mfma_f32_32x32x16_bf16 v[50:65], v[240:243], v[248:251], v[50:65]
	ds_read_b128 v[216:219], v208 offset:4096
	s_addc_u32 s71, s67, 0
	s_add_u32 s72, s68, s83
	v_mfma_f32_32x32x16_bf16 v[34:49], v[236:239], v[248:251], v[34:49]
	ds_read_b128 v[228:231], v212 offset:4096
	s_addc_u32 s73, s69, 0
	s_add_u32 s81, s80, 0x0
	s_add_u32 s82, s80, 0xc000
	s_waitcnt lgkmcnt(4)
	v_mfma_f32_32x32x16_bf16 v[18:33], v[240:243], v[244:247], v[18:33]
	ds_read_b128 v[224:227], v212 offset:8192
	v_mfma_f32_32x32x16_bf16 v[2:17], v[236:239], v[244:247], v[2:17]
	s_waitcnt vmcnt(0) lgkmcnt(0)
	s_barrier
	v_mfma_f32_32x32x16_bf16 v[82:97], v[220:223], v[232:235], v[82:97]
	s_add_u32 m0, s81, 0x0
	ds_read_b128 v[240:243], v211 offset:16384
	global_load_lds_dwordx4 v207, s[70:71]
	v_mfma_f32_32x32x16_bf16 v[66:81], v[216:219], v[232:235], v[66:81]
	s_add_u32 m0, s81, 0x1000
	ds_read_b128 v[252:255], v215 offset:24576
	global_load_lds_dwordx4 v206, s[70:71]
	v_mfma_f32_32x32x16_bf16 v[50:65], v[220:223], v[228:231], v[50:65]
	s_add_u32 m0, s81, 0x2000
	ds_read_b128 v[236:239], v211 offset:20480
	global_load_lds_dwordx4 v205, s[70:71]
	v_mfma_f32_32x32x16_bf16 v[34:49], v[216:219], v[228:231], v[34:49]
	s_add_u32 m0, s81, 0x3000
	ds_read_b128 v[248:251], v215 offset:28672
	global_load_lds_dwordx4 v204, s[70:71]
	v_mfma_f32_32x32x16_bf16 v[18:33], v[220:223], v[224:227], v[18:33]
	s_add_u32 m0, s81, 0x4000
	ds_read_b128 v[244:247], v215 offset:32768
	global_load_lds_dwordx4 v203, s[70:71]
	v_mfma_f32_32x32x16_bf16 v[2:17], v[216:219], v[224:227], v[2:17]
	s_waitcnt lgkmcnt(1)
	v_mfma_f32_32x32x16_bf16 v[82:97], v[240:243], v[252:255], v[82:97]
	ds_read_b128 v[220:223], v210 offset:16384
	s_add_u32 m0, s81, 0x5000
	s_nop 0
	global_load_lds_dwordx4 v202, s[70:71]
	v_mfma_f32_32x32x16_bf16 v[66:81], v[236:239], v[252:255], v[66:81]
	ds_read_b128 v[232:235], v214 offset:24576
	s_add_u32 m0, s82, 0x0
	s_nop 0
	global_load_lds_dwordx4 v207, s[72:73]
	v_mfma_f32_32x32x16_bf16 v[50:65], v[240:243], v[248:251], v[50:65]
	ds_read_b128 v[216:219], v210 offset:20480
	s_add_u32 m0, s82, 0x1000
	s_nop 0
	global_load_lds_dwordx4 v206, s[72:73]
	v_mfma_f32_32x32x16_bf16 v[34:49], v[236:239], v[248:251], v[34:49]
	ds_read_b128 v[228:231], v214 offset:28672
	s_add_u32 m0, s82, 0x2000
	s_nop 0
	global_load_lds_dwordx4 v205, s[72:73]
	s_waitcnt lgkmcnt(4)
	v_mfma_f32_32x32x16_bf16 v[18:33], v[240:243], v[244:247], v[18:33]
	ds_read_b128 v[224:227], v214 offset:32768
	v_mfma_f32_32x32x16_bf16 v[2:17], v[236:239], v[244:247], v[2:17]
	s_add_u32 m0, s82, 0x3000
	s_nop 0
	global_load_lds_dwordx4 v204, s[72:73]
	s_waitcnt lgkmcnt(1)
	v_mfma_f32_32x32x16_bf16 v[82:97], v[220:223], v[232:235], v[82:97]
	ds_read_b128 v[240:243], v209 offset:16384
	v_mfma_f32_32x32x16_bf16 v[66:81], v[216:219], v[232:235], v[66:81]
	ds_read_b128 v[252:255], v213 offset:24576
	v_mfma_f32_32x32x16_bf16 v[50:65], v[220:223], v[228:231], v[50:65]
	ds_read_b128 v[236:239], v209 offset:20480
	v_mfma_f32_32x32x16_bf16 v[34:49], v[216:219], v[228:231], v[34:49]
	ds_read_b128 v[248:251], v213 offset:28672
	s_waitcnt lgkmcnt(4)
	v_mfma_f32_32x32x16_bf16 v[18:33], v[220:223], v[224:227], v[18:33]
	ds_read_b128 v[244:247], v213 offset:32768
	v_mfma_f32_32x32x16_bf16 v[2:17], v[216:219], v[224:227], v[2:17]
	s_waitcnt lgkmcnt(1)
	v_mfma_f32_32x32x16_bf16 v[82:97], v[240:243], v[252:255], v[82:97]
	ds_read_b128 v[220:223], v208 offset:16384
	s_add_u32 s83, s79, s78
	s_add_u32 s83, s83, 3
	s_and_b32 s83, s83, 15
	v_mfma_f32_32x32x16_bf16 v[66:81], v[236:239], v[252:255], v[66:81]
	ds_read_b128 v[232:235], v212 offset:24576
	s_lshl_b32 s83, s83, 7
	s_add_u32 s70, s66, s83
	v_mfma_f32_32x32x16_bf16 v[50:65], v[240:243], v[248:251], v[50:65]
	ds_read_b128 v[216:219], v208 offset:20480
	s_addc_u32 s71, s67, 0
	s_add_u32 s72, s68, s83
	v_mfma_f32_32x32x16_bf16 v[34:49], v[236:239], v[248:251], v[34:49]
	ds_read_b128 v[228:231], v212 offset:28672
	s_addc_u32 s73, s69, 0
	s_add_u32 s81, s80, 0x6000
	s_add_u32 s82, s80, 0x10000
	s_waitcnt lgkmcnt(4)
	v_mfma_f32_32x32x16_bf16 v[18:33], v[240:243], v[244:247], v[18:33]
	ds_read_b128 v[224:227], v212 offset:32768
	v_mfma_f32_32x32x16_bf16 v[2:17], v[236:239], v[244:247], v[2:17]
	s_waitcnt vmcnt(0) lgkmcnt(0)
	s_barrier
	v_mfma_f32_32x32x16_bf16 v[82:97], v[220:223], v[232:235], v[82:97]
	s_add_u32 m0, s81, 0x0
	ds_read_b128 v[240:243], v211 offset:0
	global_load_lds_dwordx4 v207, s[70:71]
	v_mfma_f32_32x32x16_bf16 v[66:81], v[216:219], v[232:235], v[66:81]
	s_add_u32 m0, s81, 0x1000
	ds_read_b128 v[252:255], v215 offset:0
	global_load_lds_dwordx4 v206, s[70:71]
	v_mfma_f32_32x32x16_bf16 v[50:65], v[220:223], v[228:231], v[50:65]
	s_add_u32 m0, s81, 0x2000
	ds_read_b128 v[236:239], v211 offset:4096
	global_load_lds_dwordx4 v205, s[70:71]
	v_mfma_f32_32x32x16_bf16 v[34:49], v[216:219], v[228:231], v[34:49]
	s_add_u32 m0, s81, 0x3000
	ds_read_b128 v[248:251], v215 offset:4096
	global_load_lds_dwordx4 v204, s[70:71]
	v_mfma_f32_32x32x16_bf16 v[18:33], v[220:223], v[224:227], v[18:33]
	s_add_u32 m0, s81, 0x4000
	ds_read_b128 v[244:247], v215 offset:8192
	global_load_lds_dwordx4 v203, s[70:71]
	v_mfma_f32_32x32x16_bf16 v[2:17], v[216:219], v[224:227], v[2:17]
	s_add_u32 s78, s78, 2
	s_cmp_lt_u32 s78, 14
	s_cbranch_scc1 .Lgm_ph5_loop
	s_waitcnt lgkmcnt(1)
	v_mfma_f32_32x32x16_bf16 v[82:97], v[240:243], v[252:255], v[82:97]
	ds_read_b128 v[220:223], v210 offset:0
	s_add_u32 m0, s81, 0x5000
	s_nop 0
	global_load_lds_dwordx4 v202, s[70:71]
	v_mfma_f32_32x32x16_bf16 v[66:81], v[236:239], v[252:255], v[66:81]
	ds_read_b128 v[232:235], v214 offset:0
	s_add_u32 m0, s82, 0x0
	s_nop 0
	global_load_lds_dwordx4 v207, s[72:73]
	v_mfma_f32_32x32x16_bf16 v[50:65], v[240:243], v[248:251], v[50:65]
	ds_read_b128 v[216:219], v210 offset:4096
	s_add_u32 m0, s82, 0x1000
	s_nop 0
	global_load_lds_dwordx4 v206, s[72:73]
	v_mfma_f32_32x32x16_bf16 v[34:49], v[236:239], v[248:251], v[34:49]
	ds_read_b128 v[228:231], v214 offset:4096
	s_add_u32 m0, s82, 0x2000
	s_nop 0
	global_load_lds_dwordx4 v205, s[72:73]
	s_waitcnt lgkmcnt(4)
	v_mfma_f32_32x32x16_bf16 v[18:33], v[240:243], v[244:247], v[18:33]
	ds_read_b128 v[224:227], v214 offset:8192
	v_mfma_f32_32x32x16_bf16 v[2:17], v[236:239], v[244:247], v[2:17]
	s_add_u32 m0, s82, 0x3000
	s_nop 0
	global_load_lds_dwordx4 v204, s[72:73]
	s_waitcnt lgkmcnt(1)
	v_mfma_f32_32x32x16_bf16 v[82:97], v[220:223], v[232:235], v[82:97]
	ds_read_b128 v[240:243], v209 offset:0
	v_mfma_f32_32x32x16_bf16 v[66:81], v[216:219], v[232:235], v[66:81]
	ds_read_b128 v[252:255], v213 offset:0
	v_mfma_f32_32x32x16_bf16 v[50:65], v[220:223], v[228:231], v[50:65]
	ds_read_b128 v[236:239], v209 offset:4096
	v_mfma_f32_32x32x16_bf16 v[34:49], v[216:219], v[228:231], v[34:49]
	ds_read_b128 v[248:251], v213 offset:4096
	s_waitcnt lgkmcnt(4)
	v_mfma_f32_32x32x16_bf16 v[18:33], v[220:223], v[224:227], v[18:33]
	ds_read_b128 v[244:247], v213 offset:8192
	v_mfma_f32_32x32x16_bf16 v[2:17], v[216:219], v[224:227], v[2:17]
	s_waitcnt lgkmcnt(1)
	v_mfma_f32_32x32x16_bf16 v[82:97], v[240:243], v[252:255], v[82:97]
	ds_read_b128 v[220:223], v208 offset:0
	v_mfma_f32_32x32x16_bf16 v[66:81], v[236:239], v[252:255], v[66:81]
	ds_read_b128 v[232:235], v212 offset:0
	v_mfma_f32_32x32x16_bf16 v[50:65], v[240:243], v[248:251], v[50:65]
	ds_read_b128 v[216:219], v208 offset:4096
	v_mfma_f32_32x32x16_bf16 v[34:49], v[236:239], v[248:251], v[34:49]
	ds_read_b128 v[228:231], v212 offset:4096
	s_waitcnt lgkmcnt(4)
	v_mfma_f32_32x32x16_bf16 v[18:33], v[240:243], v[244:247], v[18:33]
	ds_read_b128 v[224:227], v212 offset:8192
	v_mfma_f32_32x32x16_bf16 v[2:17], v[236:239], v[244:247], v[2:17]
	s_waitcnt vmcnt(0) lgkmcnt(0)
	s_barrier
	v_mfma_f32_32x32x16_bf16 v[82:97], v[220:223], v[232:235], v[82:97]
	ds_read_b128 v[240:243], v211 offset:16384
	v_mfma_f32_32x32x16_bf16 v[66:81], v[216:219], v[232:235], v[66:81]
	ds_read_b128 v[252:255], v215 offset:24576
	v_mfma_f32_32x32x16_bf16 v[50:65], v[220:223], v[228:231], v[50:65]
	ds_read_b128 v[236:239], v211 offset:20480
	v_mfma_f32_32x32x16_bf16 v[34:49], v[216:219], v[228:231], v[34:49]
	ds_read_b128 v[248:251], v215 offset:28672
	v_mfma_f32_32x32x16_bf16 v[18:33], v[220:223], v[224:227], v[18:33]
	ds_read_b128 v[244:247], v215 offset:32768
	v_mfma_f32_32x32x16_bf16 v[2:17], v[216:219], v[224:227], v[2:17]
	s_waitcnt lgkmcnt(1)
	v_mfma_f32_32x32x16_bf16 v[82:97], v[240:243], v[252:255], v[82:97]
	ds_read_b128 v[220:223], v210 offset:16384
	v_mfma_f32_32x32x16_bf16 v[66:81], v[236:239], v[252:255], v[66:81]
	ds_read_b128 v[232:235], v214 offset:24576
	v_mfma_f32_32x32x16_bf16 v[50:65], v[240:243], v[248:251], v[50:65]
	ds_read_b128 v[216:219], v210 offset:20480
	v_mfma_f32_32x32x16_bf16 v[34:49], v[236:239], v[248:251], v[34:49]
	ds_read_b128 v[228:231], v214 offset:28672
	s_waitcnt lgkmcnt(4)
	v_mfma_f32_32x32x16_bf16 v[18:33], v[240:243], v[244:247], v[18:33]
	ds_read_b128 v[224:227], v214 offset:32768
	v_mfma_f32_32x32x16_bf16 v[2:17], v[236:239], v[244:247], v[2:17]
	s_waitcnt lgkmcnt(1)
	v_mfma_f32_32x32x16_bf16 v[82:97], v[220:223], v[232:235], v[82:97]
	ds_read_b128 v[240:243], v209 offset:16384
	v_mfma_f32_32x32x16_bf16 v[66:81], v[216:219], v[232:235], v[66:81]
	ds_read_b128 v[252:255], v213 offset:24576
	v_mfma_f32_32x32x16_bf16 v[50:65], v[220:223], v[228:231], v[50:65]
	ds_read_b128 v[236:239], v209 offset:20480
	v_mfma_f32_32x32x16_bf16 v[34:49], v[216:219], v[228:231], v[34:49]
	ds_read_b128 v[248:251], v213 offset:28672
	s_waitcnt lgkmcnt(4)
	v_mfma_f32_32x32x16_bf16 v[18:33], v[220:223], v[224:227], v[18:33]
	ds_read_b128 v[244:247], v213 offset:32768
	v_mfma_f32_32x32x16_bf16 v[2:17], v[216:219], v[224:227], v[2:17]
	s_waitcnt lgkmcnt(1)
	v_mfma_f32_32x32x16_bf16 v[82:97], v[240:243], v[252:255], v[82:97]
	ds_read_b128 v[220:223], v208 offset:16384
	v_mfma_f32_32x32x16_bf16 v[66:81], v[236:239], v[252:255], v[66:81]
	ds_read_b128 v[232:235], v212 offset:24576
	v_mfma_f32_32x32x16_bf16 v[50:65], v[240:243], v[248:251], v[50:65]
	ds_read_b128 v[216:219], v208 offset:20480
	v_mfma_f32_32x32x16_bf16 v[34:49], v[236:239], v[248:251], v[34:49]
	ds_read_b128 v[228:231], v212 offset:28672
	s_waitcnt lgkmcnt(4)
	v_mfma_f32_32x32x16_bf16 v[18:33], v[240:243], v[244:247], v[18:33]
	ds_read_b128 v[224:227], v212 offset:32768
	v_mfma_f32_32x32x16_bf16 v[2:17], v[236:239], v[244:247], v[2:17]
	s_waitcnt vmcnt(0) lgkmcnt(0)
	s_barrier
	v_mfma_f32_32x32x16_bf16 v[82:97], v[220:223], v[232:235], v[82:97]
	v_mfma_f32_32x32x16_bf16 v[66:81], v[216:219], v[232:235], v[66:81]
	v_mfma_f32_32x32x16_bf16 v[50:65], v[220:223], v[228:231], v[50:65]
	v_mfma_f32_32x32x16_bf16 v[34:49], v[216:219], v[228:231], v[34:49]
	v_mfma_f32_32x32x16_bf16 v[18:33], v[220:223], v[224:227], v[18:33]
	v_mfma_f32_32x32x16_bf16 v[2:17], v[216:219], v[224:227], v[2:17]
	s_nop 7
	s_nop 7
	s_waitcnt lgkmcnt(0)
	s_nop 10
	ds_write_b128 v147, v[82:85]
	ds_write_b128 v147, v[86:89] offset:32
	ds_write_b128 v147, v[90:93] offset:64
	ds_write_b128 v147, v[94:97] offset:96
	ds_write_b128 v147, v[66:69] offset:128
	ds_write_b128 v147, v[70:73] offset:160
	ds_write_b128 v147, v[74:77] offset:192
	ds_write_b128 v147, v[78:81] offset:224
	s_waitcnt lgkmcnt(0)
	v_add_u32_e32 v104, s29, v111
	v_or_b32_e32 v244, s30, v120
	v_lshlrev_b32_e32 v242, 2, v244
	v_add_u32_e32 v242, s3, v242
	v_lshlrev_b32_e32 v243, 1, v244
	v_mov_b32_e32 v240, v104
	v_add_u32_e32 v241, 0xfffff000, v240
	v_lshrrev_b32_e32 v241, 11, v241
	v_mad_u32_u24 v241, v241, s26, s26
	v_lshlrev_b32_e32 v241, 2, v241
	v_or_b32_e32 v232, v240, v119
	v_or_b32_e32 v233, v240, v121
	v_or_b32_e32 v234, v240, v122
	v_or_b32_e32 v235, v240, v123
	v_or_b32_e32 v236, v240, v124
	v_or_b32_e32 v237, v240, v125
	v_or_b32_e32 v238, v240, v126
	v_or_b32_e32 v239, v240, v127
	v_cmp_lt_i32_e64 s[82:83], s27, v232
	v_cmp_lt_i32_e64 s[84:85], s27, v233
	v_cmp_lt_i32_e64 s[86:87], s27, v234
	v_cmp_lt_i32_e64 s[88:89], s27, v235
	v_cmp_lt_i32_e64 s[90:91], s27, v236
	v_cmp_lt_i32_e64 s[92:93], s27, v237
	v_cmp_lt_i32_e64 s[94:95], s27, v238
	v_cmp_lt_i32_e64 s[96:97], s27, v239
	s_waitcnt lgkmcnt(0)
	v_cndmask_b32_e64 v200, 0, v241, s[82:83]
	v_cndmask_b32_e64 v204, 0, v241, s[84:85]
	v_cndmask_b32_e64 v208, 0, v241, s[86:87]
	v_cndmask_b32_e64 v212, 0, v241, s[88:89]
	v_cndmask_b32_e64 v216, 0, v241, s[90:91]
	v_cndmask_b32_e64 v220, 0, v241, s[92:93]
	v_cndmask_b32_e64 v224, 0, v241, s[94:95]
	v_cndmask_b32_e64 v228, 0, v241, s[96:97]
	v_add_u32_e32 v200, v200, v242
	v_add_u32_e32 v204, v204, v242
	v_add_u32_e32 v208, v208, v242
	v_add_u32_e32 v212, v212, v242
	v_add_u32_e32 v216, v216, v242
	v_add_u32_e32 v220, v220, v242
	v_add_u32_e32 v224, v224, v242
	v_add_u32_e32 v228, v228, v242
	ds_read_b128 v[82:85], v149
	global_load_dwordx4 v[200:203], v200, s[4:5]
	ds_read_b128 v[86:89], v149 offset:1088
	global_load_dwordx4 v[204:207], v204, s[4:5]
	ds_read_b128 v[90:93], v149 offset:2176
	global_load_dwordx4 v[208:211], v208, s[4:5]
	ds_read_b128 v[94:97], v149 offset:3264
	global_load_dwordx4 v[212:215], v212, s[4:5]
	ds_read_b128 v[66:69], v149 offset:4352
	global_load_dwordx4 v[216:219], v216, s[4:5]
	ds_read_b128 v[70:73], v149 offset:5440
	global_load_dwordx4 v[220:223], v220, s[4:5]
	ds_read_b128 v[74:77], v149 offset:6528
	global_load_dwordx4 v[224:227], v224, s[4:5]
	ds_read_b128 v[78:81], v149 offset:7616
	global_load_dwordx4 v[228:231], v228, s[4:5]
	v_lshl_add_u32 v232, v232, 11, v243
	v_lshl_add_u32 v233, v233, 11, v243
	v_lshl_add_u32 v234, v234, 11, v243
	v_lshl_add_u32 v235, v235, 11, v243
	v_lshl_add_u32 v236, v236, 11, v243
	v_lshl_add_u32 v237, v237, 11, v243
	v_lshl_add_u32 v238, v238, 11, v243
	v_lshl_add_u32 v239, v239, 11, v243
	s_waitcnt vmcnt(7) lgkmcnt(7)
	v_mul_f32_e32 v82, v82, v200
	v_mul_f32_e32 v83, v83, v201
	v_mul_f32_e32 v84, v84, v202
	v_mul_f32_e32 v85, v85, v203
	v_cvt_pk_bf16_f32 v82, v82, v83
	v_cvt_pk_bf16_f32 v83, v84, v85
	global_store_dwordx2 v232, v[82:83], s[6:7] sc1
	s_waitcnt vmcnt(7) lgkmcnt(6)
	v_mul_f32_e32 v86, v86, v204
	v_mul_f32_e32 v87, v87, v205
	v_mul_f32_e32 v88, v88, v206
	v_mul_f32_e32 v89, v89, v207
	v_cvt_pk_bf16_f32 v86, v86, v87
	v_cvt_pk_bf16_f32 v87, v88, v89
	global_store_dwordx2 v233, v[86:87], s[6:7] sc1
	s_waitcnt vmcnt(7) lgkmcnt(5)
	v_mul_f32_e32 v90, v90, v208
	v_mul_f32_e32 v91, v91, v209
	v_mul_f32_e32 v92, v92, v210
	v_mul_f32_e32 v93, v93, v211
	v_cvt_pk_bf16_f32 v90, v90, v91
	v_cvt_pk_bf16_f32 v91, v92, v93
	global_store_dwordx2 v234, v[90:91], s[6:7] sc1
	s_waitcnt vmcnt(7) lgkmcnt(4)
	v_mul_f32_e32 v94, v94, v212
	v_mul_f32_e32 v95, v95, v213
	v_mul_f32_e32 v96, v96, v214
	v_mul_f32_e32 v97, v97, v215
	v_cvt_pk_bf16_f32 v94, v94, v95
	v_cvt_pk_bf16_f32 v95, v96, v97
	global_store_dwordx2 v235, v[94:95], s[6:7] sc1
	s_waitcnt vmcnt(7) lgkmcnt(3)
	v_mul_f32_e32 v66, v66, v216
	v_mul_f32_e32 v67, v67, v217
	v_mul_f32_e32 v68, v68, v218
	v_mul_f32_e32 v69, v69, v219
	v_cvt_pk_bf16_f32 v66, v66, v67
	v_cvt_pk_bf16_f32 v67, v68, v69
	global_store_dwordx2 v236, v[66:67], s[6:7] sc1
	s_waitcnt vmcnt(7) lgkmcnt(2)
	v_mul_f32_e32 v70, v70, v220
	v_mul_f32_e32 v71, v71, v221
	v_mul_f32_e32 v72, v72, v222
	v_mul_f32_e32 v73, v73, v223
	v_cvt_pk_bf16_f32 v70, v70, v71
	v_cvt_pk_bf16_f32 v71, v72, v73
	global_store_dwordx2 v237, v[70:71], s[6:7] sc1
	s_waitcnt vmcnt(7) lgkmcnt(1)
	v_mul_f32_e32 v74, v74, v224
	v_mul_f32_e32 v75, v75, v225
	v_mul_f32_e32 v76, v76, v226
	v_mul_f32_e32 v77, v77, v227
	v_cvt_pk_bf16_f32 v74, v74, v75
	v_cvt_pk_bf16_f32 v75, v76, v77
	global_store_dwordx2 v238, v[74:75], s[6:7] sc1
	s_waitcnt vmcnt(7) lgkmcnt(0)
	v_mul_f32_e32 v78, v78, v228
	v_mul_f32_e32 v79, v79, v229
	v_mul_f32_e32 v80, v80, v230
	v_mul_f32_e32 v81, v81, v231
	v_cvt_pk_bf16_f32 v78, v78, v79
	v_cvt_pk_bf16_f32 v79, v80, v81
	global_store_dwordx2 v239, v[78:79], s[6:7] sc1
	ds_write_b128 v147, v[50:53]
	ds_write_b128 v147, v[54:57] offset:32
	ds_write_b128 v147, v[58:61] offset:64
	ds_write_b128 v147, v[62:65] offset:96
	ds_write_b128 v147, v[34:37] offset:128
	ds_write_b128 v147, v[38:41] offset:160
	ds_write_b128 v147, v[42:45] offset:192
	ds_write_b128 v147, v[46:49] offset:224
	v_add_u32_e32 v240, 0x20, v104
	v_add_u32_e32 v241, 0xfffff000, v240
	v_lshrrev_b32_e32 v241, 11, v241
	v_mad_u32_u24 v241, v241, s26, s26
	v_lshlrev_b32_e32 v241, 2, v241
	v_or_b32_e32 v232, v240, v119
	v_or_b32_e32 v233, v240, v121
	v_or_b32_e32 v234, v240, v122
	v_or_b32_e32 v235, v240, v123
	v_or_b32_e32 v236, v240, v124
	v_or_b32_e32 v237, v240, v125
	v_or_b32_e32 v238, v240, v126
	v_or_b32_e32 v239, v240, v127
	v_cmp_lt_i32_e64 s[82:83], s27, v232
	v_cmp_lt_i32_e64 s[84:85], s27, v233
	v_cmp_lt_i32_e64 s[86:87], s27, v234
	v_cmp_lt_i32_e64 s[88:89], s27, v235
	v_cmp_lt_i32_e64 s[90:91], s27, v236
	v_cmp_lt_i32_e64 s[92:93], s27, v237
	v_cmp_lt_i32_e64 s[94:95], s27, v238
	v_cmp_lt_i32_e64 s[96:97], s27, v239
	s_waitcnt lgkmcnt(0)
	v_cndmask_b32_e64 v200, 0, v241, s[82:83]
	v_cndmask_b32_e64 v204, 0, v241, s[84:85]
	v_cndmask_b32_e64 v208, 0, v241, s[86:87]
	v_cndmask_b32_e64 v212, 0, v241, s[88:89]
	v_cndmask_b32_e64 v216, 0, v241, s[90:91]
	v_cndmask_b32_e64 v220, 0, v241, s[92:93]
	v_cndmask_b32_e64 v224, 0, v241, s[94:95]
	v_cndmask_b32_e64 v228, 0, v241, s[96:97]
	v_add_u32_e32 v200, v200, v242
	v_add_u32_e32 v204, v204, v242
	v_add_u32_e32 v208, v208, v242
	v_add_u32_e32 v212, v212, v242
	v_add_u32_e32 v216, v216, v242
	v_add_u32_e32 v220, v220, v242
	v_add_u32_e32 v224, v224, v242
	v_add_u32_e32 v228, v228, v242
	ds_read_b128 v[50:53], v149
	global_load_dwordx4 v[200:203], v200, s[4:5]
	ds_read_b128 v[54:57], v149 offset:1088
	global_load_dwordx4 v[204:207], v204, s[4:5]
	ds_read_b128 v[58:61], v149 offset:2176
	global_load_dwordx4 v[208:211], v208, s[4:5]
	ds_read_b128 v[62:65], v149 offset:3264
	global_load_dwordx4 v[212:215], v212, s[4:5]
	ds_read_b128 v[34:37], v149 offset:4352
	global_load_dwordx4 v[216:219], v216, s[4:5]
	ds_read_b128 v[38:41], v149 offset:5440
	global_load_dwordx4 v[220:223], v220, s[4:5]
	ds_read_b128 v[42:45], v149 offset:6528
	global_load_dwordx4 v[224:227], v224, s[4:5]
	ds_read_b128 v[46:49], v149 offset:7616
	global_load_dwordx4 v[228:231], v228, s[4:5]
	v_lshl_add_u32 v232, v232, 11, v243
	v_lshl_add_u32 v233, v233, 11, v243
	v_lshl_add_u32 v234, v234, 11, v243
	v_lshl_add_u32 v235, v235, 11, v243
	v_lshl_add_u32 v236, v236, 11, v243
	v_lshl_add_u32 v237, v237, 11, v243
	v_lshl_add_u32 v238, v238, 11, v243
	v_lshl_add_u32 v239, v239, 11, v243
	s_waitcnt vmcnt(7) lgkmcnt(7)
	v_mul_f32_e32 v50, v50, v200
	v_mul_f32_e32 v51, v51, v201
	v_mul_f32_e32 v52, v52, v202
	v_mul_f32_e32 v53, v53, v203
	v_cvt_pk_bf16_f32 v50, v50, v51
	v_cvt_pk_bf16_f32 v51, v52, v53
	global_store_dwordx2 v232, v[50:51], s[6:7] sc1
	s_waitcnt vmcnt(7) lgkmcnt(6)
	v_mul_f32_e32 v54, v54, v204
	v_mul_f32_e32 v55, v55, v205
	v_mul_f32_e32 v56, v56, v206
	v_mul_f32_e32 v57, v57, v207
	v_cvt_pk_bf16_f32 v54, v54, v55
	v_cvt_pk_bf16_f32 v55, v56, v57
	global_store_dwordx2 v233, v[54:55], s[6:7] sc1
	s_waitcnt vmcnt(7) lgkmcnt(5)
	v_mul_f32_e32 v58, v58, v208
	v_mul_f32_e32 v59, v59, v209
	v_mul_f32_e32 v60, v60, v210
	v_mul_f32_e32 v61, v61, v211
	v_cvt_pk_bf16_f32 v58, v58, v59
	v_cvt_pk_bf16_f32 v59, v60, v61
	global_store_dwordx2 v234, v[58:59], s[6:7] sc1
	s_waitcnt vmcnt(7) lgkmcnt(4)
	v_mul_f32_e32 v62, v62, v212
	v_mul_f32_e32 v63, v63, v213
	v_mul_f32_e32 v64, v64, v214
	v_mul_f32_e32 v65, v65, v215
	v_cvt_pk_bf16_f32 v62, v62, v63
	v_cvt_pk_bf16_f32 v63, v64, v65
	global_store_dwordx2 v235, v[62:63], s[6:7] sc1
	s_waitcnt vmcnt(7) lgkmcnt(3)
	v_mul_f32_e32 v34, v34, v216
	v_mul_f32_e32 v35, v35, v217
	v_mul_f32_e32 v36, v36, v218
	v_mul_f32_e32 v37, v37, v219
	v_cvt_pk_bf16_f32 v34, v34, v35
	v_cvt_pk_bf16_f32 v35, v36, v37
	global_store_dwordx2 v236, v[34:35], s[6:7] sc1
	s_waitcnt vmcnt(7) lgkmcnt(2)
	v_mul_f32_e32 v38, v38, v220
	v_mul_f32_e32 v39, v39, v221
	v_mul_f32_e32 v40, v40, v222
	v_mul_f32_e32 v41, v41, v223
	v_cvt_pk_bf16_f32 v38, v38, v39
	v_cvt_pk_bf16_f32 v39, v40, v41
	global_store_dwordx2 v237, v[38:39], s[6:7] sc1
	s_waitcnt vmcnt(7) lgkmcnt(1)
	v_mul_f32_e32 v42, v42, v224
	v_mul_f32_e32 v43, v43, v225
	v_mul_f32_e32 v44, v44, v226
	v_mul_f32_e32 v45, v45, v227
	v_cvt_pk_bf16_f32 v42, v42, v43
	v_cvt_pk_bf16_f32 v43, v44, v45
	global_store_dwordx2 v238, v[42:43], s[6:7] sc1
	s_waitcnt vmcnt(7) lgkmcnt(0)
	v_mul_f32_e32 v46, v46, v228
	v_mul_f32_e32 v47, v47, v229
	v_mul_f32_e32 v48, v48, v230
	v_mul_f32_e32 v49, v49, v231
	v_cvt_pk_bf16_f32 v46, v46, v47
	v_cvt_pk_bf16_f32 v47, v48, v49
	global_store_dwordx2 v239, v[46:47], s[6:7] sc1
	ds_write_b128 v147, v[18:21]
	ds_write_b128 v147, v[22:25] offset:32
	ds_write_b128 v147, v[26:29] offset:64
	ds_write_b128 v147, v[30:33] offset:96
	ds_write_b128 v147, v[2:5] offset:128
	ds_write_b128 v147, v[6:9] offset:160
	ds_write_b128 v147, v[10:13] offset:192
	ds_write_b128 v147, v[14:17] offset:224
	v_add_u32_e32 v240, 0x40, v104
	v_add_u32_e32 v241, 0xfffff000, v240
	v_lshrrev_b32_e32 v241, 11, v241
	v_mad_u32_u24 v241, v241, s26, s26
	v_lshlrev_b32_e32 v241, 2, v241
	v_or_b32_e32 v232, v240, v119
	v_or_b32_e32 v233, v240, v121
	v_or_b32_e32 v234, v240, v122
	v_or_b32_e32 v235, v240, v123
	v_or_b32_e32 v236, v240, v124
	v_or_b32_e32 v237, v240, v125
	v_or_b32_e32 v238, v240, v126
	v_or_b32_e32 v239, v240, v127
	v_cmp_lt_i32_e64 s[82:83], s27, v232
	v_cmp_lt_i32_e64 s[84:85], s27, v233
	v_cmp_lt_i32_e64 s[86:87], s27, v234
	v_cmp_lt_i32_e64 s[88:89], s27, v235
	v_cmp_lt_i32_e64 s[90:91], s27, v236
	v_cmp_lt_i32_e64 s[92:93], s27, v237
	v_cmp_lt_i32_e64 s[94:95], s27, v238
	v_cmp_lt_i32_e64 s[96:97], s27, v239
	s_waitcnt lgkmcnt(0)
	v_cndmask_b32_e64 v200, 0, v241, s[82:83]
	v_cndmask_b32_e64 v204, 0, v241, s[84:85]
	v_cndmask_b32_e64 v208, 0, v241, s[86:87]
	v_cndmask_b32_e64 v212, 0, v241, s[88:89]
	v_cndmask_b32_e64 v216, 0, v241, s[90:91]
	v_cndmask_b32_e64 v220, 0, v241, s[92:93]
	v_cndmask_b32_e64 v224, 0, v241, s[94:95]
	v_cndmask_b32_e64 v228, 0, v241, s[96:97]
	v_add_u32_e32 v200, v200, v242
	v_add_u32_e32 v204, v204, v242
	v_add_u32_e32 v208, v208, v242
	v_add_u32_e32 v212, v212, v242
	v_add_u32_e32 v216, v216, v242
	v_add_u32_e32 v220, v220, v242
	v_add_u32_e32 v224, v224, v242
	v_add_u32_e32 v228, v228, v242
	ds_read_b128 v[18:21], v149
	global_load_dwordx4 v[200:203], v200, s[4:5]
	ds_read_b128 v[22:25], v149 offset:1088
	global_load_dwordx4 v[204:207], v204, s[4:5]
	ds_read_b128 v[26:29], v149 offset:2176
	global_load_dwordx4 v[208:211], v208, s[4:5]
	ds_read_b128 v[30:33], v149 offset:3264
	global_load_dwordx4 v[212:215], v212, s[4:5]
	ds_read_b128 v[2:5], v149 offset:4352
	global_load_dwordx4 v[216:219], v216, s[4:5]
	ds_read_b128 v[6:9], v149 offset:5440
	global_load_dwordx4 v[220:223], v220, s[4:5]
	ds_read_b128 v[10:13], v149 offset:6528
	global_load_dwordx4 v[224:227], v224, s[4:5]
	ds_read_b128 v[14:17], v149 offset:7616
	global_load_dwordx4 v[228:231], v228, s[4:5]
	v_lshl_add_u32 v232, v232, 11, v243
	v_lshl_add_u32 v233, v233, 11, v243
	v_lshl_add_u32 v234, v234, 11, v243
	v_lshl_add_u32 v235, v235, 11, v243
	v_lshl_add_u32 v236, v236, 11, v243
	v_lshl_add_u32 v237, v237, 11, v243
	v_lshl_add_u32 v238, v238, 11, v243
	v_lshl_add_u32 v239, v239, 11, v243
	s_waitcnt vmcnt(7) lgkmcnt(7)
	v_mul_f32_e32 v18, v18, v200
	v_mul_f32_e32 v19, v19, v201
	v_mul_f32_e32 v20, v20, v202
	v_mul_f32_e32 v21, v21, v203
	v_cvt_pk_bf16_f32 v18, v18, v19
	v_cvt_pk_bf16_f32 v19, v20, v21
	global_store_dwordx2 v232, v[18:19], s[6:7] sc1
	s_waitcnt vmcnt(7) lgkmcnt(6)
	v_mul_f32_e32 v22, v22, v204
	v_mul_f32_e32 v23, v23, v205
	v_mul_f32_e32 v24, v24, v206
	v_mul_f32_e32 v25, v25, v207
	v_cvt_pk_bf16_f32 v22, v22, v23
	v_cvt_pk_bf16_f32 v23, v24, v25
	global_store_dwordx2 v233, v[22:23], s[6:7] sc1
	s_waitcnt vmcnt(7) lgkmcnt(5)
	v_mul_f32_e32 v26, v26, v208
	v_mul_f32_e32 v27, v27, v209
	v_mul_f32_e32 v28, v28, v210
	v_mul_f32_e32 v29, v29, v211
	v_cvt_pk_bf16_f32 v26, v26, v27
	v_cvt_pk_bf16_f32 v27, v28, v29
	global_store_dwordx2 v234, v[26:27], s[6:7] sc1
	s_waitcnt vmcnt(7) lgkmcnt(4)
	v_mul_f32_e32 v30, v30, v212
	v_mul_f32_e32 v31, v31, v213
	v_mul_f32_e32 v32, v32, v214
	v_mul_f32_e32 v33, v33, v215
	v_cvt_pk_bf16_f32 v30, v30, v31
	v_cvt_pk_bf16_f32 v31, v32, v33
	global_store_dwordx2 v235, v[30:31], s[6:7] sc1
	s_waitcnt vmcnt(7) lgkmcnt(3)
	v_mul_f32_e32 v2, v2, v216
	v_mul_f32_e32 v3, v3, v217
	v_mul_f32_e32 v4, v4, v218
	v_mul_f32_e32 v5, v5, v219
	v_cvt_pk_bf16_f32 v2, v2, v3
	v_cvt_pk_bf16_f32 v3, v4, v5
	global_store_dwordx2 v236, v[2:3], s[6:7] sc1
	s_waitcnt vmcnt(7) lgkmcnt(2)
	v_mul_f32_e32 v6, v6, v220
	v_mul_f32_e32 v7, v7, v221
	v_mul_f32_e32 v8, v8, v222
	v_mul_f32_e32 v9, v9, v223
	v_cvt_pk_bf16_f32 v6, v6, v7
	v_cvt_pk_bf16_f32 v7, v8, v9
	global_store_dwordx2 v237, v[6:7], s[6:7] sc1
	s_waitcnt vmcnt(7) lgkmcnt(1)
	v_mul_f32_e32 v10, v10, v224
	v_mul_f32_e32 v11, v11, v225
	v_mul_f32_e32 v12, v12, v226
	v_mul_f32_e32 v13, v13, v227
	v_cvt_pk_bf16_f32 v10, v10, v11
	v_cvt_pk_bf16_f32 v11, v12, v13
	global_store_dwordx2 v238, v[10:11], s[6:7] sc1
	s_waitcnt vmcnt(7) lgkmcnt(0)
	v_mul_f32_e32 v14, v14, v228
	v_mul_f32_e32 v15, v15, v229
	v_mul_f32_e32 v16, v16, v230
	v_mul_f32_e32 v17, v17, v231
	v_cvt_pk_bf16_f32 v14, v14, v15
	v_cvt_pk_bf16_f32 v15, v16, v17
	global_store_dwordx2 v239, v[14:15], s[6:7] sc1
	s_waitcnt lgkmcnt(0)
	s_load_dword s10, s[8:9], 0x0
	s_waitcnt lgkmcnt(0)
	s_add_i32 s28, s10, s28
	s_cmpk_lt_i32 s28, 0x200
	s_cbranch_scc1 .LBB0_489

.LBB0_626:
	s_ashr_i32 s4, s56, 31
	s_lshr_b32 s4, s4, 26
	s_add_i32 s4, s56, s4
	s_ashr_i32 s6, s4, 6
	s_and_b32 s4, s4, 0x3ffffc0
	s_sub_i32 s4, s56, s4
	s_mulk_i32 s4, 0xc0
	v_add_u32_e32 v2, s4, v147
	s_lshr_b32 s7, s4, 6
	s_lshl_b32 s5, s6, 7
	v_ashrrev_i32_e32 v3, 31, v2
	s_add_i32 s7, s7, s6
	v_lshlrev_b64 v[2:3], 11, v[2:3]
	v_or_b32_e32 v4, s5, v147
	s_lshl_b32 s6, s7, 6
	s_lshl_b32 s7, s7, 7
	v_ashrrev_i32_e32 v5, 31, v4
	v_lshl_add_u64 v[138:139], v[100:101], 0, v[2:3]
	s_and_b32 s12, s7, 0x780
	v_readfirstlane_b32 s7, v149
	v_lshlrev_b64 v[4:5], 11, v[4:5]
	v_lshl_add_u64 v[2:3], v[138:139], 0, s[12:13]
	s_mov_b32 m0, s7
	v_readfirstlane_b32 s7, v172
	v_lshl_add_u64 v[140:141], v[102:103], 0, v[4:5]
	s_waitcnt vmcnt(0)
	s_barrier
	s_load_dwordx2 s[66:67], s[0:1], 0x90
	s_load_dwordx2 s[68:69], s[0:1], 0xd8
	v_and_b32_e32 v201, 0x3ff, v0
	v_readfirstlane_b32 s80, v0
	v_and_b32_e32 v200, 31, v201
	v_bfe_u32 v214, v201, 1, 3
	v_bfe_u32 v213, v201, 5, 1
	v_xor_b32_e32 v214, v214, v213
	v_lshlrev_b32_e32 v214, 4, v214
	s_and_b32 s80, s80, 0x3ff
	s_lshr_b32 s83, s80, 6
	s_lshl_b32 s80, s80, 4
	s_lshr_b32 s84, s83, 1
	s_and_b32 s83, s83, 1
	s_mul_i32 s84, s84, 0x3000
	s_lshl_b32 s83, s83, 13
	s_add_u32 s83, s83, 0xc000
	v_lshlrev_b32_e32 v200, 7, v200
	v_or_b32_e32 v200, v200, v214
	v_add_u32_e32 v215, s84, v200
	v_add_u32_e32 v211, s83, v200
	v_xor_b32_e32 v214, 0x20, v215
	v_xor_b32_e32 v210, 0x20, v211
	v_xor_b32_e32 v213, 0x40, v215
	v_xor_b32_e32 v209, 0x40, v211
	v_xor_b32_e32 v212, 0x60, v215
	v_xor_b32_e32 v208, 0x60, v211
	v_bfe_u32 v200, v201, 4, 3
	v_and_b32_e32 v206, 7, v201
	v_xor_b32_e32 v200, v200, v206
	v_lshlrev_b32_e32 v200, 4, v200
	v_lshrrev_b32_e32 v206, 3, v201
	v_lshl_or_b32 v207, v206, 11, v200
	v_add_u32_e32 v206, 0x10000, v207
	v_add_u32_e32 v205, 0x20000, v207
	v_add_u32_e32 v204, 0x30000, v207
	v_add_u32_e32 v203, 0x40000, v207
	v_add_u32_e32 v202, 0x50000, v207
	s_lshr_b32 s83, s56, 6
	s_and_b32 s84, s56, 63
	s_mov_b32 s79, 0
	s_mul_i32 s84, s84, 0x60000
	s_lshl_b32 s83, s83, 18
	s_waitcnt lgkmcnt(0)
	s_add_u32 s66, s66, s84
	s_addc_u32 s67, s67, 0
	s_add_u32 s68, s68, s83
	s_addc_u32 s69, s69, 0
	s_add_u32 s83, s79, 0
	s_and_b32 s83, s83, 15
	s_lshl_b32 s83, s83, 7
	s_add_u32 s70, s66, s83
	s_addc_u32 s71, s67, 0
	s_add_u32 s72, s68, s83
	s_addc_u32 s73, s69, 0
	s_add_u32 s81, s80, 0x0
	s_add_u32 s82, s80, 0xc000
	s_add_u32 m0, s81, 0x0
	s_nop 0
	global_load_lds_dwordx4 v207, s[70:71]
	s_add_u32 m0, s81, 0x1000
	s_nop 0
	global_load_lds_dwordx4 v206, s[70:71]
	s_add_u32 m0, s81, 0x2000
	s_nop 0
	global_load_lds_dwordx4 v205, s[70:71]
	s_add_u32 m0, s81, 0x3000
	s_nop 0
	global_load_lds_dwordx4 v204, s[70:71]
	s_add_u32 m0, s81, 0x4000
	s_nop 0
	global_load_lds_dwordx4 v203, s[70:71]
	s_add_u32 m0, s81, 0x5000
	s_nop 0
	global_load_lds_dwordx4 v202, s[70:71]
	s_add_u32 m0, s82, 0x0
	s_nop 0
	global_load_lds_dwordx4 v207, s[72:73]
	s_add_u32 m0, s82, 0x1000
	s_nop 0
	global_load_lds_dwordx4 v206, s[72:73]
	s_add_u32 m0, s82, 0x2000
	s_nop 0
	global_load_lds_dwordx4 v205, s[72:73]
	s_add_u32 m0, s82, 0x3000
	s_nop 0
	global_load_lds_dwordx4 v204, s[72:73]
	s_add_u32 s83, s79, 1
	s_and_b32 s83, s83, 15
	s_lshl_b32 s83, s83, 7
	s_add_u32 s70, s66, s83
	s_addc_u32 s71, s67, 0
	s_add_u32 s72, s68, s83
	s_addc_u32 s73, s69, 0
	s_add_u32 s81, s80, 0x6000
	s_add_u32 s82, s80, 0x10000
	s_add_u32 m0, s81, 0x0
	s_nop 0
	global_load_lds_dwordx4 v207, s[70:71]
	s_add_u32 m0, s81, 0x1000
	s_nop 0
	global_load_lds_dwordx4 v206, s[70:71]
	s_add_u32 m0, s81, 0x2000
	s_nop 0
	global_load_lds_dwordx4 v205, s[70:71]
	s_add_u32 m0, s81, 0x3000
	s_nop 0
	global_load_lds_dwordx4 v204, s[70:71]
	s_add_u32 m0, s81, 0x4000
	s_nop 0
	global_load_lds_dwordx4 v203, s[70:71]
	v_mov_b32_e32 v2, 0
	v_mov_b32_e32 v3, 0
	v_mov_b32_e32 v4, 0
	v_mov_b32_e32 v5, 0
	v_mov_b32_e32 v6, 0
	v_mov_b32_e32 v7, 0
	v_mov_b32_e32 v8, 0
	v_mov_b32_e32 v9, 0
	v_mov_b32_e32 v10, 0
	v_mov_b32_e32 v11, 0
	v_mov_b32_e32 v12, 0
	v_mov_b32_e32 v13, 0
	v_mov_b32_e32 v14, 0
	v_mov_b32_e32 v15, 0
	v_mov_b32_e32 v16, 0
	v_mov_b32_e32 v17, 0
	v_mov_b32_e32 v18, 0
	v_mov_b32_e32 v19, 0
	v_mov_b32_e32 v20, 0
	v_mov_b32_e32 v21, 0
	v_mov_b32_e32 v22, 0
	v_mov_b32_e32 v23, 0
	v_mov_b32_e32 v24, 0
	v_mov_b32_e32 v25, 0
	v_mov_b32_e32 v26, 0
	v_mov_b32_e32 v27, 0
	v_mov_b32_e32 v28, 0
	v_mov_b32_e32 v29, 0
	v_mov_b32_e32 v30, 0
	v_mov_b32_e32 v31, 0
	v_mov_b32_e32 v32, 0
	v_mov_b32_e32 v33, 0
	v_mov_b32_e32 v34, 0
	v_mov_b32_e32 v35, 0
	v_mov_b32_e32 v36, 0
	v_mov_b32_e32 v37, 0
	v_mov_b32_e32 v38, 0
	v_mov_b32_e32 v39, 0
	v_mov_b32_e32 v40, 0
	v_mov_b32_e32 v41, 0
	v_mov_b32_e32 v42, 0
	v_mov_b32_e32 v43, 0
	v_mov_b32_e32 v44, 0
	v_mov_b32_e32 v45, 0
	v_mov_b32_e32 v46, 0
	v_mov_b32_e32 v47, 0
	v_mov_b32_e32 v48, 0
	v_mov_b32_e32 v49, 0
	v_mov_b32_e32 v50, 0
	v_mov_b32_e32 v51, 0
	v_mov_b32_e32 v52, 0
	v_mov_b32_e32 v53, 0
	v_mov_b32_e32 v54, 0
	v_mov_b32_e32 v55, 0
	v_mov_b32_e32 v56, 0
	v_mov_b32_e32 v57, 0
	v_mov_b32_e32 v58, 0
	v_mov_b32_e32 v59, 0
	v_mov_b32_e32 v60, 0
	v_mov_b32_e32 v61, 0
	v_mov_b32_e32 v62, 0
	v_mov_b32_e32 v63, 0
	v_mov_b32_e32 v64, 0
	v_mov_b32_e32 v65, 0
	v_mov_b32_e32 v66, 0
	v_mov_b32_e32 v67, 0
	v_mov_b32_e32 v68, 0
	v_mov_b32_e32 v69, 0
	v_mov_b32_e32 v70, 0
	v_mov_b32_e32 v71, 0
	v_mov_b32_e32 v72, 0
	v_mov_b32_e32 v73, 0
	v_mov_b32_e32 v74, 0
	v_mov_b32_e32 v75, 0
	v_mov_b32_e32 v76, 0
	v_mov_b32_e32 v77, 0
	v_mov_b32_e32 v78, 0
	v_mov_b32_e32 v79, 0
	v_mov_b32_e32 v80, 0
	v_mov_b32_e32 v81, 0
	v_mov_b32_e32 v82, 0
	v_mov_b32_e32 v83, 0
	v_mov_b32_e32 v84, 0
	v_mov_b32_e32 v85, 0
	v_mov_b32_e32 v86, 0
	v_mov_b32_e32 v87, 0
	v_mov_b32_e32 v88, 0
	v_mov_b32_e32 v89, 0
	v_mov_b32_e32 v90, 0
	v_mov_b32_e32 v91, 0
	v_mov_b32_e32 v92, 0
	v_mov_b32_e32 v93, 0
	v_mov_b32_e32 v94, 0
	v_mov_b32_e32 v95, 0
	v_mov_b32_e32 v96, 0
	v_mov_b32_e32 v97, 0
	s_waitcnt vmcnt(5)
	s_barrier
	ds_read_b128 v[240:243], v211 offset:0
	ds_read_b128 v[252:255], v215 offset:0
	ds_read_b128 v[236:239], v211 offset:4096
	ds_read_b128 v[248:251], v215 offset:4096
	ds_read_b128 v[244:247], v215 offset:8192
	s_mov_b32 s78, 0
.Lgm_ph7_loop:
	s_waitcnt lgkmcnt(1)
	v_mfma_f32_32x32x16_bf16 v[82:97], v[240:243], v[252:255], v[82:97]
	ds_read_b128 v[220:223], v210 offset:0
	s_add_u32 m0, s81, 0x5000
	s_nop 0
	global_load_lds_dwordx4 v202, s[70:71]
	v_mfma_f32_32x32x16_bf16 v[66:81], v[236:239], v[252:255], v[66:81]
	ds_read_b128 v[232:235], v214 offset:0
	s_add_u32 m0, s82, 0x0
	s_nop 0
	global_load_lds_dwordx4 v207, s[72:73]
	v_mfma_f32_32x32x16_bf16 v[50:65], v[240:243], v[248:251], v[50:65]
	ds_read_b128 v[216:219], v210 offset:4096
	s_add_u32 m0, s82, 0x1000
	s_nop 0
	global_load_lds_dwordx4 v206, s[72:73]
	v_mfma_f32_32x32x16_bf16 v[34:49], v[236:239], v[248:251], v[34:49]
	ds_read_b128 v[228:231], v214 offset:4096
	s_add_u32 m0, s82, 0x2000
	s_nop 0
	global_load_lds_dwordx4 v205, s[72:73]
	s_waitcnt lgkmcnt(4)
	v_mfma_f32_32x32x16_bf16 v[18:33], v[240:243], v[244:247], v[18:33]
	ds_read_b128 v[224:227], v214 offset:8192
	v_mfma_f32_32x32x16_bf16 v[2:17], v[236:239], v[244:247], v[2:17]
	s_add_u32 m0, s82, 0x3000
	s_nop 0
	global_load_lds_dwordx4 v204, s[72:73]
	s_waitcnt lgkmcnt(1)
	v_mfma_f32_32x32x16_bf16 v[82:97], v[220:223], v[232:235], v[82:97]
	ds_read_b128 v[240:243], v209 offset:0
	v_mfma_f32_32x32x16_bf16 v[66:81], v[216:219], v[232:235], v[66:81]
	ds_read_b128 v[252:255], v213 offset:0
	v_mfma_f32_32x32x16_bf16 v[50:65], v[220:223], v[228:231], v[50:65]
	ds_read_b128 v[236:239], v209 offset:4096
	v_mfma_f32_32x32x16_bf16 v[34:49], v[216:219], v[228:231], v[34:49]
	ds_read_b128 v[248:251], v213 offset:4096
	s_waitcnt lgkmcnt(4)
	v_mfma_f32_32x32x16_bf16 v[18:33], v[220:223], v[224:227], v[18:33]
	ds_read_b128 v[244:247], v213 offset:8192
	v_mfma_f32_32x32x16_bf16 v[2:17], v[216:219], v[224:227], v[2:17]
	s_waitcnt lgkmcnt(1)
	v_mfma_f32_32x32x16_bf16 v[82:97], v[240:243], v[252:255], v[82:97]
	ds_read_b128 v[220:223], v208 offset:0
	s_add_u32 s83, s79, s78
	s_add_u32 s83, s83, 2
	s_and_b32 s83, s83, 15
	v_mfma_f32_32x32x16_bf16 v[66:81], v[236:239], v[252:255], v[66:81]
	ds_read_b128 v[232:235], v212 offset:0
	s_lshl_b32 s83, s83, 7
	s_add_u32 s70, s66, s83
	v_mfma_f32_32x32x16_bf16 v[50:65], v[240:243], v[248:251], v[50:65]
	ds_read_b128 v[216:219], v208 offset:4096
	s_addc_u32 s71, s67, 0
	s_add_u32 s72, s68, s83
	v_mfma_f32_32x32x16_bf16 v[34:49], v[236:239], v[248:251], v[34:49]
	ds_read_b128 v[228:231], v212 offset:4096
	s_addc_u32 s73, s69, 0
	s_add_u32 s81, s80, 0x0
	s_add_u32 s82, s80, 0xc000
	s_waitcnt lgkmcnt(4)
	v_mfma_f32_32x32x16_bf16 v[18:33], v[240:243], v[244:247], v[18:33]
	ds_read_b128 v[224:227], v212 offset:8192
	v_mfma_f32_32x32x16_bf16 v[2:17], v[236:239], v[244:247], v[2:17]
	s_waitcnt vmcnt(0) lgkmcnt(0)
	s_barrier
	v_mfma_f32_32x32x16_bf16 v[82:97], v[220:223], v[232:235], v[82:97]
	s_add_u32 m0, s81, 0x0
	ds_read_b128 v[240:243], v211 offset:16384
	global_load_lds_dwordx4 v207, s[70:71]
	v_mfma_f32_32x32x16_bf16 v[66:81], v[216:219], v[232:235], v[66:81]
	s_add_u32 m0, s81, 0x1000
	ds_read_b128 v[252:255], v215 offset:24576
	global_load_lds_dwordx4 v206, s[70:71]
	v_mfma_f32_32x32x16_bf16 v[50:65], v[220:223], v[228:231], v[50:65]
	s_add_u32 m0, s81, 0x2000
	ds_read_b128 v[236:239], v211 offset:20480
	global_load_lds_dwordx4 v205, s[70:71]
	v_mfma_f32_32x32x16_bf16 v[34:49], v[216:219], v[228:231], v[34:49]
	s_add_u32 m0, s81, 0x3000
	ds_read_b128 v[248:251], v215 offset:28672
	global_load_lds_dwordx4 v204, s[70:71]
	v_mfma_f32_32x32x16_bf16 v[18:33], v[220:223], v[224:227], v[18:33]
	s_add_u32 m0, s81, 0x4000
	ds_read_b128 v[244:247], v215 offset:32768
	global_load_lds_dwordx4 v203, s[70:71]
	v_mfma_f32_32x32x16_bf16 v[2:17], v[216:219], v[224:227], v[2:17]
	s_waitcnt lgkmcnt(1)
	v_mfma_f32_32x32x16_bf16 v[82:97], v[240:243], v[252:255], v[82:97]
	ds_read_b128 v[220:223], v210 offset:16384
	s_add_u32 m0, s81, 0x5000
	s_nop 0
	global_load_lds_dwordx4 v202, s[70:71]
	v_mfma_f32_32x32x16_bf16 v[66:81], v[236:239], v[252:255], v[66:81]
	ds_read_b128 v[232:235], v214 offset:24576
	s_add_u32 m0, s82, 0x0
	s_nop 0
	global_load_lds_dwordx4 v207, s[72:73]
	v_mfma_f32_32x32x16_bf16 v[50:65], v[240:243], v[248:251], v[50:65]
	ds_read_b128 v[216:219], v210 offset:20480
	s_add_u32 m0, s82, 0x1000
	s_nop 0
	global_load_lds_dwordx4 v206, s[72:73]
	v_mfma_f32_32x32x16_bf16 v[34:49], v[236:239], v[248:251], v[34:49]
	ds_read_b128 v[228:231], v214 offset:28672
	s_add_u32 m0, s82, 0x2000
	s_nop 0
	global_load_lds_dwordx4 v205, s[72:73]
	s_waitcnt lgkmcnt(4)
	v_mfma_f32_32x32x16_bf16 v[18:33], v[240:243], v[244:247], v[18:33]
	ds_read_b128 v[224:227], v214 offset:32768
	v_mfma_f32_32x32x16_bf16 v[2:17], v[236:239], v[244:247], v[2:17]
	s_add_u32 m0, s82, 0x3000
	s_nop 0
	global_load_lds_dwordx4 v204, s[72:73]
	s_waitcnt lgkmcnt(1)
	v_mfma_f32_32x32x16_bf16 v[82:97], v[220:223], v[232:235], v[82:97]
	ds_read_b128 v[240:243], v209 offset:16384
	v_mfma_f32_32x32x16_bf16 v[66:81], v[216:219], v[232:235], v[66:81]
	ds_read_b128 v[252:255], v213 offset:24576
	v_mfma_f32_32x32x16_bf16 v[50:65], v[220:223], v[228:231], v[50:65]
	ds_read_b128 v[236:239], v209 offset:20480
	v_mfma_f32_32x32x16_bf16 v[34:49], v[216:219], v[228:231], v[34:49]
	ds_read_b128 v[248:251], v213 offset:28672
	s_waitcnt lgkmcnt(4)
	v_mfma_f32_32x32x16_bf16 v[18:33], v[220:223], v[224:227], v[18:33]
	ds_read_b128 v[244:247], v213 offset:32768
	v_mfma_f32_32x32x16_bf16 v[2:17], v[216:219], v[224:227], v[2:17]
	s_waitcnt lgkmcnt(1)
	v_mfma_f32_32x32x16_bf16 v[82:97], v[240:243], v[252:255], v[82:97]
	ds_read_b128 v[220:223], v208 offset:16384
	s_add_u32 s83, s79, s78
	s_add_u32 s83, s83, 3
	s_and_b32 s83, s83, 15
	v_mfma_f32_32x32x16_bf16 v[66:81], v[236:239], v[252:255], v[66:81]
	ds_read_b128 v[232:235], v212 offset:24576
	s_lshl_b32 s83, s83, 7
	s_add_u32 s70, s66, s83
	v_mfma_f32_32x32x16_bf16 v[50:65], v[240:243], v[248:251], v[50:65]
	ds_read_b128 v[216:219], v208 offset:20480
	s_addc_u32 s71, s67, 0
	s_add_u32 s72, s68, s83
	v_mfma_f32_32x32x16_bf16 v[34:49], v[236:239], v[248:251], v[34:49]
	ds_read_b128 v[228:231], v212 offset:28672
	s_addc_u32 s73, s69, 0
	s_add_u32 s81, s80, 0x6000
	s_add_u32 s82, s80, 0x10000
	s_waitcnt lgkmcnt(4)
	v_mfma_f32_32x32x16_bf16 v[18:33], v[240:243], v[244:247], v[18:33]
	ds_read_b128 v[224:227], v212 offset:32768
	v_mfma_f32_32x32x16_bf16 v[2:17], v[236:239], v[244:247], v[2:17]
	s_waitcnt vmcnt(0) lgkmcnt(0)
	s_barrier
	v_mfma_f32_32x32x16_bf16 v[82:97], v[220:223], v[232:235], v[82:97]
	s_add_u32 m0, s81, 0x0
	ds_read_b128 v[240:243], v211 offset:0
	global_load_lds_dwordx4 v207, s[70:71]
	v_mfma_f32_32x32x16_bf16 v[66:81], v[216:219], v[232:235], v[66:81]
	s_add_u32 m0, s81, 0x1000
	ds_read_b128 v[252:255], v215 offset:0
	global_load_lds_dwordx4 v206, s[70:71]
	v_mfma_f32_32x32x16_bf16 v[50:65], v[220:223], v[228:231], v[50:65]
	s_add_u32 m0, s81, 0x2000
	ds_read_b128 v[236:239], v211 offset:4096
	global_load_lds_dwordx4 v205, s[70:71]
	v_mfma_f32_32x32x16_bf16 v[34:49], v[216:219], v[228:231], v[34:49]
	s_add_u32 m0, s81, 0x3000
	ds_read_b128 v[248:251], v215 offset:4096
	global_load_lds_dwordx4 v204, s[70:71]
	v_mfma_f32_32x32x16_bf16 v[18:33], v[220:223], v[224:227], v[18:33]
	s_add_u32 m0, s81, 0x4000
	ds_read_b128 v[244:247], v215 offset:8192
	global_load_lds_dwordx4 v203, s[70:71]
	v_mfma_f32_32x32x16_bf16 v[2:17], v[216:219], v[224:227], v[2:17]
	s_add_u32 s78, s78, 2
	s_cmp_lt_u32 s78, 14
	s_cbranch_scc1 .Lgm_ph7_loop
	s_waitcnt lgkmcnt(1)
	v_mfma_f32_32x32x16_bf16 v[82:97], v[240:243], v[252:255], v[82:97]
	ds_read_b128 v[220:223], v210 offset:0
	s_add_u32 m0, s81, 0x5000
	s_nop 0
	global_load_lds_dwordx4 v202, s[70:71]
	v_mfma_f32_32x32x16_bf16 v[66:81], v[236:239], v[252:255], v[66:81]
	ds_read_b128 v[232:235], v214 offset:0
	s_add_u32 m0, s82, 0x0
	s_nop 0
	global_load_lds_dwordx4 v207, s[72:73]
	v_mfma_f32_32x32x16_bf16 v[50:65], v[240:243], v[248:251], v[50:65]
	ds_read_b128 v[216:219], v210 offset:4096
	s_add_u32 m0, s82, 0x1000
	s_nop 0
	global_load_lds_dwordx4 v206, s[72:73]
	v_mfma_f32_32x32x16_bf16 v[34:49], v[236:239], v[248:251], v[34:49]
	ds_read_b128 v[228:231], v214 offset:4096
	s_add_u32 m0, s82, 0x2000
	s_nop 0
	global_load_lds_dwordx4 v205, s[72:73]
	s_waitcnt lgkmcnt(4)
	v_mfma_f32_32x32x16_bf16 v[18:33], v[240:243], v[244:247], v[18:33]
	ds_read_b128 v[224:227], v214 offset:8192
	v_mfma_f32_32x32x16_bf16 v[2:17], v[236:239], v[244:247], v[2:17]
	s_add_u32 m0, s82, 0x3000
	s_nop 0
	global_load_lds_dwordx4 v204, s[72:73]
	s_waitcnt lgkmcnt(1)
	v_mfma_f32_32x32x16_bf16 v[82:97], v[220:223], v[232:235], v[82:97]
	ds_read_b128 v[240:243], v209 offset:0
	v_mfma_f32_32x32x16_bf16 v[66:81], v[216:219], v[232:235], v[66:81]
	ds_read_b128 v[252:255], v213 offset:0
	v_mfma_f32_32x32x16_bf16 v[50:65], v[220:223], v[228:231], v[50:65]
	ds_read_b128 v[236:239], v209 offset:4096
	v_mfma_f32_32x32x16_bf16 v[34:49], v[216:219], v[228:231], v[34:49]
	ds_read_b128 v[248:251], v213 offset:4096
	s_waitcnt lgkmcnt(4)
	v_mfma_f32_32x32x16_bf16 v[18:33], v[220:223], v[224:227], v[18:33]
	ds_read_b128 v[244:247], v213 offset:8192
	v_mfma_f32_32x32x16_bf16 v[2:17], v[216:219], v[224:227], v[2:17]
	s_waitcnt lgkmcnt(1)
	v_mfma_f32_32x32x16_bf16 v[82:97], v[240:243], v[252:255], v[82:97]
	ds_read_b128 v[220:223], v208 offset:0
	v_mfma_f32_32x32x16_bf16 v[66:81], v[236:239], v[252:255], v[66:81]
	ds_read_b128 v[232:235], v212 offset:0
	v_mfma_f32_32x32x16_bf16 v[50:65], v[240:243], v[248:251], v[50:65]
	ds_read_b128 v[216:219], v208 offset:4096
	v_mfma_f32_32x32x16_bf16 v[34:49], v[236:239], v[248:251], v[34:49]
	ds_read_b128 v[228:231], v212 offset:4096
	s_waitcnt lgkmcnt(4)
	v_mfma_f32_32x32x16_bf16 v[18:33], v[240:243], v[244:247], v[18:33]
	ds_read_b128 v[224:227], v212 offset:8192
	v_mfma_f32_32x32x16_bf16 v[2:17], v[236:239], v[244:247], v[2:17]
	s_waitcnt vmcnt(0) lgkmcnt(0)
	s_barrier
	v_mfma_f32_32x32x16_bf16 v[82:97], v[220:223], v[232:235], v[82:97]
	ds_read_b128 v[240:243], v211 offset:16384
	v_mfma_f32_32x32x16_bf16 v[66:81], v[216:219], v[232:235], v[66:81]
	ds_read_b128 v[252:255], v215 offset:24576
	v_mfma_f32_32x32x16_bf16 v[50:65], v[220:223], v[228:231], v[50:65]
	ds_read_b128 v[236:239], v211 offset:20480
	v_mfma_f32_32x32x16_bf16 v[34:49], v[216:219], v[228:231], v[34:49]
	ds_read_b128 v[248:251], v215 offset:28672
	v_mfma_f32_32x32x16_bf16 v[18:33], v[220:223], v[224:227], v[18:33]
	ds_read_b128 v[244:247], v215 offset:32768
	v_mfma_f32_32x32x16_bf16 v[2:17], v[216:219], v[224:227], v[2:17]
	s_waitcnt lgkmcnt(1)
	v_mfma_f32_32x32x16_bf16 v[82:97], v[240:243], v[252:255], v[82:97]
	ds_read_b128 v[220:223], v210 offset:16384
	v_mfma_f32_32x32x16_bf16 v[66:81], v[236:239], v[252:255], v[66:81]
	ds_read_b128 v[232:235], v214 offset:24576
	v_mfma_f32_32x32x16_bf16 v[50:65], v[240:243], v[248:251], v[50:65]
	ds_read_b128 v[216:219], v210 offset:20480
	v_mfma_f32_32x32x16_bf16 v[34:49], v[236:239], v[248:251], v[34:49]
	ds_read_b128 v[228:231], v214 offset:28672
	s_waitcnt lgkmcnt(4)
	v_mfma_f32_32x32x16_bf16 v[18:33], v[240:243], v[244:247], v[18:33]
	ds_read_b128 v[224:227], v214 offset:32768
	v_mfma_f32_32x32x16_bf16 v[2:17], v[236:239], v[244:247], v[2:17]
	s_waitcnt lgkmcnt(1)
	v_mfma_f32_32x32x16_bf16 v[82:97], v[220:223], v[232:235], v[82:97]
	ds_read_b128 v[240:243], v209 offset:16384
	v_mfma_f32_32x32x16_bf16 v[66:81], v[216:219], v[232:235], v[66:81]
	ds_read_b128 v[252:255], v213 offset:24576
	v_mfma_f32_32x32x16_bf16 v[50:65], v[220:223], v[228:231], v[50:65]
	ds_read_b128 v[236:239], v209 offset:20480
	v_mfma_f32_32x32x16_bf16 v[34:49], v[216:219], v[228:231], v[34:49]
	ds_read_b128 v[248:251], v213 offset:28672
	s_waitcnt lgkmcnt(4)
	v_mfma_f32_32x32x16_bf16 v[18:33], v[220:223], v[224:227], v[18:33]
	ds_read_b128 v[244:247], v213 offset:32768
	v_mfma_f32_32x32x16_bf16 v[2:17], v[216:219], v[224:227], v[2:17]
	s_waitcnt lgkmcnt(1)
	v_mfma_f32_32x32x16_bf16 v[82:97], v[240:243], v[252:255], v[82:97]
	ds_read_b128 v[220:223], v208 offset:16384
	v_mfma_f32_32x32x16_bf16 v[66:81], v[236:239], v[252:255], v[66:81]
	ds_read_b128 v[232:235], v212 offset:24576
	v_mfma_f32_32x32x16_bf16 v[50:65], v[240:243], v[248:251], v[50:65]
	ds_read_b128 v[216:219], v208 offset:20480
	v_mfma_f32_32x32x16_bf16 v[34:49], v[236:239], v[248:251], v[34:49]
	ds_read_b128 v[228:231], v212 offset:28672
	s_waitcnt lgkmcnt(4)
	v_mfma_f32_32x32x16_bf16 v[18:33], v[240:243], v[244:247], v[18:33]
	ds_read_b128 v[224:227], v212 offset:32768
	v_mfma_f32_32x32x16_bf16 v[2:17], v[236:239], v[244:247], v[2:17]
	s_waitcnt vmcnt(0) lgkmcnt(0)
	s_barrier
	v_mfma_f32_32x32x16_bf16 v[82:97], v[220:223], v[232:235], v[82:97]
	v_mfma_f32_32x32x16_bf16 v[66:81], v[216:219], v[232:235], v[66:81]
	v_mfma_f32_32x32x16_bf16 v[50:65], v[220:223], v[228:231], v[50:65]
	v_mfma_f32_32x32x16_bf16 v[34:49], v[216:219], v[228:231], v[34:49]
	v_mfma_f32_32x32x16_bf16 v[18:33], v[220:223], v[224:227], v[18:33]
	v_mfma_f32_32x32x16_bf16 v[2:17], v[216:219], v[224:227], v[2:17]
	s_nop 7
	s_nop 7
	s_waitcnt lgkmcnt(0)
	v_add_u32_e32 v140, s4, v154
	v_add_u32_e32 v98, 0xfffff000, v140
	v_lshrrev_b32_e32 v98, 11, v98
	v_or_b32_e32 v138, s5, v162
	v_ashrrev_i32_e32 v141, 31, v140
	v_mul_u32_u24_e32 v98, 0x900, v98
	v_and_b32_e32 v139, 0x7ff, v140
	v_cmp_lt_i32_e64 s[6:7], s48, v140
	v_cmp_gt_i32_e64 s[8:9], s3, v140
	v_add3_u32 v139, v139, v98, s49
	v_mad_i64_i32 v[152:153], s[4:5], v140, s50, 0
	v_cmp_gt_i32_e64 s[10:11], s51, v138
	v_lshlrev_b64 v[142:143], 11, v[140:141]
	v_lshlrev_b64 v[144:145], 6, v[140:141]
	s_and_saveexec_b64 s[4:5], s[10:11]
	s_cbranch_execz .LBB0_656
	v_cmp_lt_i32_e32 vcc, s52, v138
	s_and_saveexec_b64 s[40:41], vcc
	s_xor_b64 s[40:41], exec, s[40:41]
	s_cbranch_execz .LBB0_654
	v_cmp_lt_u32_e32 vcc, s53, v138
	s_and_saveexec_b64 s[42:43], vcc
	s_xor_b64 s[42:43], exec, s[42:43]
	s_cbranch_execz .LBB0_632
	v_mul_f32_e32 v98, 0xbfb8aa3b, v82
	v_exp_f32_e32 v190, v98
	v_mul_f32_e32 v98, 0xbfb8aa3b, v83
	v_exp_f32_e32 v191, v98
	v_or_b32_e32 v98, v138, v104
	v_pk_add_f32 v[190:191], v[190:191], 1.0 op_sel_hi:[1,0]
	s_nop 0
	v_div_scale_f32 v141, s[44:45], v191, v191, v83
	v_rcp_f32_e32 v192, v141
	v_div_scale_f32 v193, vcc, v83, v191, v83
	v_fma_f32 v194, -v141, v192, 1.0
	v_fmac_f32_e32 v192, v194, v192
	v_mul_f32_e32 v194, v193, v192
	v_fma_f32 v195, -v141, v194, v193
	v_fmac_f32_e32 v194, v195, v192
	v_div_scale_f32 v195, s[44:45], v190, v190, v82
	v_rcp_f32_e32 v196, v195
	v_fma_f32 v141, -v141, v194, v193
	v_div_fmas_f32 v141, v141, v192, v194
	v_mul_f32_e32 v192, 0xbfb8aa3b, v84
	v_mul_f32_e32 v193, 0xbfb8aa3b, v85
	v_exp_f32_e32 v192, v192
	v_exp_f32_e32 v193, v193
	v_div_fixup_f32 v83, v141, v191, v83
	v_fma_f32 v141, -v195, v196, 1.0
	v_fmac_f32_e32 v196, v141, v196
	v_div_scale_f32 v141, vcc, v82, v190, v82
	v_mul_f32_e32 v191, v141, v196
	v_fma_f32 v194, -v195, v191, v141
	v_pk_add_f32 v[192:193], v[192:193], 1.0 op_sel_hi:[1,0]
	v_fmac_f32_e32 v191, v194, v196
	v_div_scale_f32 v194, s[44:45], v193, v193, v85
	v_fma_f32 v141, -v195, v191, v141
	v_rcp_f32_e32 v195, v194
	v_div_fmas_f32 v141, v141, v196, v191
	v_div_fixup_f32 v82, v141, v190, v82
	v_cvt_pk_bf16_f32 v190, v82, v83
	v_fma_f32 v82, -v194, v195, 1.0
	v_fmac_f32_e32 v195, v82, v195
	v_div_scale_f32 v82, vcc, v85, v193, v85
	v_mul_f32_e32 v83, v82, v195
	v_fma_f32 v141, -v194, v83, v82
	v_fmac_f32_e32 v83, v141, v195
	v_div_scale_f32 v141, s[44:45], v192, v192, v84
	v_rcp_f32_e32 v191, v141
	v_fma_f32 v82, -v194, v83, v82
	v_div_fmas_f32 v82, v82, v195, v83
	v_div_fixup_f32 v85, v82, v193, v85
	v_fma_f32 v82, -v141, v191, 1.0
	v_fmac_f32_e32 v191, v82, v191
	v_div_scale_f32 v82, vcc, v84, v192, v84
	v_mul_f32_e32 v193, v82, v191
	v_fma_f32 v83, -v141, v193, v82
	v_fmac_f32_e32 v193, v83, v191
	v_fma_f32 v141, -v141, v193, v82
	v_mul_f32_e32 v82, 0xbfb8aa3b, v86
	v_mul_f32_e32 v83, 0xbfb8aa3b, v87
	v_exp_f32_e32 v82, v82
	v_exp_f32_e32 v83, v83
	v_div_fmas_f32 v141, v141, v191, v193
	v_div_fixup_f32 v84, v141, v192, v84
	v_cvt_pk_bf16_f32 v191, v84, v85
	v_pk_add_f32 v[84:85], v[82:83], 1.0 op_sel_hi:[1,0]
	v_lshl_add_u64 v[82:83], s[14:15], 0, v[142:143]
	v_div_scale_f32 v141, s[44:45], v85, v85, v87
	v_rcp_f32_e32 v192, v141
	v_lshl_add_u64 v[82:83], v[98:99], 1, v[82:83]
	global_store_dwordx2 v[82:83], v[190:191], off offset:-1664
	v_fma_f32 v98, -v141, v192, 1.0
	v_fmac_f32_e32 v192, v98, v192
	v_div_scale_f32 v98, vcc, v87, v85, v87
	v_mul_f32_e32 v190, v98, v192
	v_fma_f32 v191, -v141, v190, v98
	v_fmac_f32_e32 v190, v191, v192
	v_fma_f32 v98, -v141, v190, v98
	v_div_scale_f32 v141, s[44:45], v84, v84, v86
	v_rcp_f32_e32 v193, v141
	v_div_fmas_f32 v98, v98, v192, v190
	v_mul_f32_e32 v190, 0xbfb8aa3b, v88
	v_mul_f32_e32 v191, 0xbfb8aa3b, v89
	v_div_fixup_f32 v85, v98, v85, v87
	v_fma_f32 v87, -v141, v193, 1.0
	v_exp_f32_e32 v190, v190
	v_exp_f32_e32 v191, v191
	v_fmac_f32_e32 v193, v87, v193
	v_div_scale_f32 v87, vcc, v86, v84, v86
	v_mul_f32_e32 v98, v87, v193
	v_fma_f32 v192, -v141, v98, v87
	v_fmac_f32_e32 v98, v192, v193
	v_pk_add_f32 v[190:191], v[190:191], 1.0 op_sel_hi:[1,0]
	v_fma_f32 v87, -v141, v98, v87
	v_div_scale_f32 v141, s[44:45], v191, v191, v89
	v_rcp_f32_e32 v192, v141
	v_div_fmas_f32 v87, v87, v193, v98
	v_div_fixup_f32 v84, v87, v84, v86
	v_cvt_pk_bf16_f32 v84, v84, v85
	v_fma_f32 v85, -v141, v192, 1.0
	v_fmac_f32_e32 v192, v85, v192
	v_div_scale_f32 v85, vcc, v89, v191, v89
	v_mul_f32_e32 v86, v85, v192
	v_fma_f32 v87, -v141, v86, v85
	v_fmac_f32_e32 v86, v87, v192
	v_div_scale_f32 v98, s[44:45], v190, v190, v88
	v_fma_f32 v85, -v141, v86, v85
	v_rcp_f32_e32 v141, v98
	v_div_fmas_f32 v85, v85, v192, v86
	v_div_fixup_f32 v85, v85, v191, v89
	v_div_scale_f32 v89, vcc, v88, v190, v88
	v_fma_f32 v86, -v98, v141, 1.0
	v_fmac_f32_e32 v141, v86, v141
	v_mul_f32_e32 v191, v89, v141
	v_fma_f32 v86, -v98, v191, v89
	v_fmac_f32_e32 v191, v86, v141
	v_mul_f32_e32 v86, 0xbfb8aa3b, v90
	v_mul_f32_e32 v87, 0xbfb8aa3b, v91
	v_exp_f32_e32 v86, v86
	v_exp_f32_e32 v87, v87
	v_fma_f32 v89, -v98, v191, v89
	v_div_fmas_f32 v89, v89, v141, v191
	v_div_fixup_f32 v88, v89, v190, v88
	v_pk_add_f32 v[86:87], v[86:87], 1.0 op_sel_hi:[1,0]
	v_cvt_pk_bf16_f32 v85, v88, v85
	v_div_scale_f32 v98, s[44:45], v87, v87, v91
	v_rcp_f32_e32 v141, v98
	global_store_dwordx2 v[82:83], v[84:85], off offset:-1648
	v_fma_f32 v84, -v98, v141, 1.0
	v_fmac_f32_e32 v141, v84, v141
	v_div_scale_f32 v84, vcc, v91, v87, v91
	v_mul_f32_e32 v85, v84, v141
	v_fma_f32 v88, -v98, v85, v84
	v_fmac_f32_e32 v85, v88, v141
	v_div_scale_f32 v88, s[44:45], v86, v86, v90
	v_rcp_f32_e32 v89, v88
	v_fma_f32 v84, -v98, v85, v84
	v_div_fmas_f32 v84, v84, v141, v85
	v_div_fixup_f32 v87, v84, v87, v91
	v_fma_f32 v84, -v88, v89, 1.0
	v_fmac_f32_e32 v89, v84, v89
	v_mul_f32_e32 v84, 0xbfb8aa3b, v92
	v_mul_f32_e32 v85, 0xbfb8aa3b, v93
	v_exp_f32_e32 v84, v84
	v_exp_f32_e32 v85, v85
	v_div_scale_f32 v91, vcc, v90, v86, v90
	v_mul_f32_e32 v98, v91, v89
	v_fma_f32 v141, -v88, v98, v91
	v_fmac_f32_e32 v98, v141, v89
	v_pk_add_f32 v[84:85], v[84:85], 1.0 op_sel_hi:[1,0]
	v_fma_f32 v88, -v88, v98, v91
	v_div_scale_f32 v91, s[44:45], v85, v85, v93
	v_rcp_f32_e32 v141, v91
	v_div_fmas_f32 v88, v88, v89, v98
	v_div_fixup_f32 v86, v88, v86, v90
	v_cvt_pk_bf16_f32 v86, v86, v87
	v_fma_f32 v87, -v91, v141, 1.0
	v_fmac_f32_e32 v141, v87, v141
	v_div_scale_f32 v87, vcc, v93, v85, v93
	v_mul_f32_e32 v88, v87, v141
	v_fma_f32 v89, -v91, v88, v87
	v_fmac_f32_e32 v88, v89, v141
	v_div_scale_f32 v90, s[44:45], v84, v84, v92
	v_fma_f32 v87, -v91, v88, v87
	v_rcp_f32_e32 v91, v90
	v_div_fmas_f32 v87, v87, v141, v88
	v_div_fixup_f32 v85, v87, v85, v93
	v_mul_f32_e32 v89, 0xbfb8aa3b, v95
	v_fma_f32 v87, -v90, v91, 1.0
	v_fmac_f32_e32 v91, v87, v91
	v_div_scale_f32 v87, vcc, v92, v84, v92
	v_mul_f32_e32 v93, v87, v91
	v_fma_f32 v88, -v90, v93, v87
	v_fmac_f32_e32 v93, v88, v91
	v_mul_f32_e32 v88, 0xbfb8aa3b, v94
	v_exp_f32_e32 v88, v88
	v_exp_f32_e32 v89, v89
	v_fma_f32 v87, -v90, v93, v87
	v_div_fmas_f32 v87, v87, v91, v93
	v_div_fixup_f32 v84, v87, v84, v92
	v_pk_add_f32 v[88:89], v[88:89], 1.0 op_sel_hi:[1,0]
	v_cvt_pk_bf16_f32 v87, v84, v85
	v_div_scale_f32 v90, s[44:45], v89, v89, v95
	v_rcp_f32_e32 v91, v90
	global_store_dwordx2 v[82:83], v[86:87], off offset:-1632
	v_fma_f32 v84, -v90, v91, 1.0
	v_fmac_f32_e32 v91, v84, v91
	v_div_scale_f32 v84, vcc, v95, v89, v95
	v_mul_f32_e32 v85, v84, v91
	v_fma_f32 v86, -v90, v85, v84
	v_fmac_f32_e32 v85, v86, v91
	v_div_scale_f32 v86, s[44:45], v88, v88, v94
	v_rcp_f32_e32 v87, v86
	v_fma_f32 v84, -v90, v85, v84
	v_div_fmas_f32 v84, v84, v91, v85
	v_div_fixup_f32 v89, v84, v89, v95
	v_fma_f32 v84, -v86, v87, 1.0
	v_fmac_f32_e32 v87, v84, v87
	v_mul_f32_e32 v84, 0xbfb8aa3b, v96
	v_mul_f32_e32 v85, 0xbfb8aa3b, v97
	v_exp_f32_e32 v84, v84
	v_exp_f32_e32 v85, v85
	v_div_scale_f32 v90, vcc, v94, v88, v94
	v_mul_f32_e32 v91, v90, v87
	v_fma_f32 v92, -v86, v91, v90
	v_fmac_f32_e32 v91, v92, v87
	v_pk_add_f32 v[84:85], v[84:85], 1.0 op_sel_hi:[1,0]
	v_fma_f32 v86, -v86, v91, v90
	v_div_scale_f32 v90, s[44:45], v85, v85, v97
	v_rcp_f32_e32 v92, v90
	v_div_fmas_f32 v86, v86, v87, v91
	v_div_fixup_f32 v86, v86, v88, v94
	v_cvt_pk_bf16_f32 v86, v86, v89
	v_fma_f32 v87, -v90, v92, 1.0
	v_fmac_f32_e32 v92, v87, v92
	v_div_scale_f32 v87, vcc, v97, v85, v97
	v_mul_f32_e32 v88, v87, v92
	v_fma_f32 v89, -v90, v88, v87
	v_fmac_f32_e32 v88, v89, v92
	v_div_scale_f32 v89, s[44:45], v84, v84, v96
	v_fma_f32 v87, -v90, v88, v87
	v_rcp_f32_e32 v90, v89
	v_div_fmas_f32 v87, v87, v92, v88
	v_div_fixup_f32 v85, v87, v85, v97
	v_fma_f32 v87, -v89, v90, 1.0
	v_fmac_f32_e32 v90, v87, v90
	v_div_scale_f32 v87, vcc, v96, v84, v96
	v_mul_f32_e32 v88, v87, v90
	v_fma_f32 v91, -v89, v88, v87
	v_fmac_f32_e32 v88, v91, v90
	v_fma_f32 v87, -v89, v88, v87
	v_div_fmas_f32 v87, v87, v90, v88
	v_div_fixup_f32 v84, v87, v84, v96
	v_cvt_pk_bf16_f32 v87, v84, v85
	global_store_dwordx2 v[82:83], v[86:87], off offset:-1616

.LBB0_1133:
	s_ashr_i32 s10, s28, 31
	s_lshr_b32 s10, s10, 26
	s_add_i32 s10, s28, s10
	s_ashr_i32 s31, s10, 6
	s_and_b32 s10, s10, 0x3ffffc0
	s_sub_i32 s29, s28, s10
	s_mulk_i32 s29, 0xc0
	v_add_u32_e32 v2, s29, v108
	s_lshr_b32 s10, s29, 6
	s_lshl_b32 s30, s31, 7
	v_ashrrev_i32_e32 v3, 31, v2
	s_add_i32 s10, s10, s31
	v_lshlrev_b64 v[2:3], 11, v[2:3]
	v_or_b32_e32 v4, s30, v108
	s_lshl_b32 s31, s10, 6
	s_lshl_b32 s10, s10, 7
	v_ashrrev_i32_e32 v5, 31, v4
	v_lshl_add_u64 v[104:105], v[100:101], 0, v[2:3]
	s_and_b32 s10, s10, 0x780
	v_readfirstlane_b32 s34, v109
	v_lshlrev_b64 v[4:5], 11, v[4:5]
	v_lshl_add_u64 v[2:3], v[104:105], 0, s[10:11]
	s_mov_b32 m0, s34
	v_readfirstlane_b32 s34, v128
	v_lshl_add_u64 v[106:107], v[102:103], 0, v[4:5]
	s_waitcnt vmcnt(0)
	s_barrier
	s_load_dwordx2 s[66:67], s[0:1], 0x128
	s_load_dwordx2 s[68:69], s[0:1], 0xf0
	v_and_b32_e32 v201, 0x3ff, v0
	v_readfirstlane_b32 s80, v0
	v_and_b32_e32 v200, 31, v201
	v_bfe_u32 v214, v201, 1, 3
	v_bfe_u32 v213, v201, 5, 1
	v_xor_b32_e32 v214, v214, v213
	v_lshlrev_b32_e32 v214, 4, v214
	s_and_b32 s80, s80, 0x3ff
	s_lshr_b32 s83, s80, 6
	s_lshl_b32 s80, s80, 4
	s_lshr_b32 s84, s83, 1
	s_and_b32 s83, s83, 1
	s_mul_i32 s84, s84, 0x3000
	s_lshl_b32 s83, s83, 13
	s_add_u32 s83, s83, 0xc000
	v_lshlrev_b32_e32 v200, 7, v200
	v_or_b32_e32 v200, v200, v214
	v_add_u32_e32 v215, s84, v200
	v_add_u32_e32 v211, s83, v200
	v_xor_b32_e32 v214, 0x20, v215
	v_xor_b32_e32 v210, 0x20, v211
	v_xor_b32_e32 v213, 0x40, v215
	v_xor_b32_e32 v209, 0x40, v211
	v_xor_b32_e32 v212, 0x60, v215
	v_xor_b32_e32 v208, 0x60, v211
	v_bfe_u32 v200, v201, 4, 3
	v_and_b32_e32 v206, 7, v201
	v_xor_b32_e32 v200, v200, v206
	v_lshlrev_b32_e32 v200, 4, v200
	v_lshrrev_b32_e32 v206, 3, v201
	v_lshl_or_b32 v207, v206, 11, v200
	v_add_u32_e32 v206, 0x10000, v207
	v_add_u32_e32 v205, 0x20000, v207
	v_add_u32_e32 v204, 0x30000, v207
	v_add_u32_e32 v203, 0x40000, v207
	v_add_u32_e32 v202, 0x50000, v207
	s_lshr_b32 s83, s28, 6
	s_and_b32 s84, s28, 63
	s_mov_b32 s79, 0
	s_mul_i32 s84, s84, 0x60000
	s_lshl_b32 s83, s83, 18
	s_waitcnt lgkmcnt(0)
	s_add_u32 s66, s66, s84
	s_addc_u32 s67, s67, 0
	s_add_u32 s68, s68, s83
	s_addc_u32 s69, s69, 0
	s_add_u32 s83, s79, 0
	s_and_b32 s83, s83, 15
	s_lshl_b32 s83, s83, 7
	s_add_u32 s70, s66, s83
	s_addc_u32 s71, s67, 0
	s_add_u32 s72, s68, s83
	s_addc_u32 s73, s69, 0
	s_add_u32 s81, s80, 0x0
	s_add_u32 s82, s80, 0xc000
	s_add_u32 m0, s81, 0x0
	s_nop 0
	global_load_lds_dwordx4 v207, s[70:71]
	s_add_u32 m0, s81, 0x1000
	s_nop 0
	global_load_lds_dwordx4 v206, s[70:71]
	s_add_u32 m0, s81, 0x2000
	s_nop 0
	global_load_lds_dwordx4 v205, s[70:71]
	s_add_u32 m0, s81, 0x3000
	s_nop 0
	global_load_lds_dwordx4 v204, s[70:71]
	s_add_u32 m0, s81, 0x4000
	s_nop 0
	global_load_lds_dwordx4 v203, s[70:71]
	s_add_u32 m0, s81, 0x5000
	s_nop 0
	global_load_lds_dwordx4 v202, s[70:71]
	s_add_u32 m0, s82, 0x0
	s_nop 0
	global_load_lds_dwordx4 v207, s[72:73]
	s_add_u32 m0, s82, 0x1000
	s_nop 0
	global_load_lds_dwordx4 v206, s[72:73]
	s_add_u32 m0, s82, 0x2000
	s_nop 0
	global_load_lds_dwordx4 v205, s[72:73]
	s_add_u32 m0, s82, 0x3000
	s_nop 0
	global_load_lds_dwordx4 v204, s[72:73]
	s_add_u32 s83, s79, 1
	s_and_b32 s83, s83, 15
	s_lshl_b32 s83, s83, 7
	s_add_u32 s70, s66, s83
	s_addc_u32 s71, s67, 0
	s_add_u32 s72, s68, s83
	s_addc_u32 s73, s69, 0
	s_add_u32 s81, s80, 0x6000
	s_add_u32 s82, s80, 0x10000
	s_add_u32 m0, s81, 0x0
	s_nop 0
	global_load_lds_dwordx4 v207, s[70:71]
	s_add_u32 m0, s81, 0x1000
	s_nop 0
	global_load_lds_dwordx4 v206, s[70:71]
	s_add_u32 m0, s81, 0x2000
	s_nop 0
	global_load_lds_dwordx4 v205, s[70:71]
	s_add_u32 m0, s81, 0x3000
	s_nop 0
	global_load_lds_dwordx4 v204, s[70:71]
	s_add_u32 m0, s81, 0x4000
	s_nop 0
	global_load_lds_dwordx4 v203, s[70:71]
	v_mov_b32_e32 v2, 0
	v_mov_b32_e32 v3, 0
	v_mov_b32_e32 v4, 0
	v_mov_b32_e32 v5, 0
	v_mov_b32_e32 v6, 0
	v_mov_b32_e32 v7, 0
	v_mov_b32_e32 v8, 0
	v_mov_b32_e32 v9, 0
	v_mov_b32_e32 v10, 0
	v_mov_b32_e32 v11, 0
	v_mov_b32_e32 v12, 0
	v_mov_b32_e32 v13, 0
	v_mov_b32_e32 v14, 0
	v_mov_b32_e32 v15, 0
	v_mov_b32_e32 v16, 0
	v_mov_b32_e32 v17, 0
	v_mov_b32_e32 v18, 0
	v_mov_b32_e32 v19, 0
	v_mov_b32_e32 v20, 0
	v_mov_b32_e32 v21, 0
	v_mov_b32_e32 v22, 0
	v_mov_b32_e32 v23, 0
	v_mov_b32_e32 v24, 0
	v_mov_b32_e32 v25, 0
	v_mov_b32_e32 v26, 0
	v_mov_b32_e32 v27, 0
	v_mov_b32_e32 v28, 0
	v_mov_b32_e32 v29, 0
	v_mov_b32_e32 v30, 0
	v_mov_b32_e32 v31, 0
	v_mov_b32_e32 v32, 0
	v_mov_b32_e32 v33, 0
	v_mov_b32_e32 v34, 0
	v_mov_b32_e32 v35, 0
	v_mov_b32_e32 v36, 0
	v_mov_b32_e32 v37, 0
	v_mov_b32_e32 v38, 0
	v_mov_b32_e32 v39, 0
	v_mov_b32_e32 v40, 0
	v_mov_b32_e32 v41, 0
	v_mov_b32_e32 v42, 0
	v_mov_b32_e32 v43, 0
	v_mov_b32_e32 v44, 0
	v_mov_b32_e32 v45, 0
	v_mov_b32_e32 v46, 0
	v_mov_b32_e32 v47, 0
	v_mov_b32_e32 v48, 0
	v_mov_b32_e32 v49, 0
	v_mov_b32_e32 v50, 0
	v_mov_b32_e32 v51, 0
	v_mov_b32_e32 v52, 0
	v_mov_b32_e32 v53, 0
	v_mov_b32_e32 v54, 0
	v_mov_b32_e32 v55, 0
	v_mov_b32_e32 v56, 0
	v_mov_b32_e32 v57, 0
	v_mov_b32_e32 v58, 0
	v_mov_b32_e32 v59, 0
	v_mov_b32_e32 v60, 0
	v_mov_b32_e32 v61, 0
	v_mov_b32_e32 v62, 0
	v_mov_b32_e32 v63, 0
	v_mov_b32_e32 v64, 0
	v_mov_b32_e32 v65, 0
	v_mov_b32_e32 v66, 0
	v_mov_b32_e32 v67, 0
	v_mov_b32_e32 v68, 0
	v_mov_b32_e32 v69, 0
	v_mov_b32_e32 v70, 0
	v_mov_b32_e32 v71, 0
	v_mov_b32_e32 v72, 0
	v_mov_b32_e32 v73, 0
	v_mov_b32_e32 v74, 0
	v_mov_b32_e32 v75, 0
	v_mov_b32_e32 v76, 0
	v_mov_b32_e32 v77, 0
	v_mov_b32_e32 v78, 0
	v_mov_b32_e32 v79, 0
	v_mov_b32_e32 v80, 0
	v_mov_b32_e32 v81, 0
	v_mov_b32_e32 v82, 0
	v_mov_b32_e32 v83, 0
	v_mov_b32_e32 v84, 0
	v_mov_b32_e32 v85, 0
	v_mov_b32_e32 v86, 0
	v_mov_b32_e32 v87, 0
	v_mov_b32_e32 v88, 0
	v_mov_b32_e32 v89, 0
	v_mov_b32_e32 v90, 0
	v_mov_b32_e32 v91, 0
	v_mov_b32_e32 v92, 0
	v_mov_b32_e32 v93, 0
	v_mov_b32_e32 v94, 0
	v_mov_b32_e32 v95, 0
	v_mov_b32_e32 v96, 0
	v_mov_b32_e32 v97, 0
	s_waitcnt vmcnt(5)
	s_barrier
	ds_read_b128 v[240:243], v211 offset:0
	ds_read_b128 v[252:255], v215 offset:0
	ds_read_b128 v[236:239], v211 offset:4096
	ds_read_b128 v[248:251], v215 offset:4096
	ds_read_b128 v[244:247], v215 offset:8192
	s_mov_b32 s78, 0
.Lgm_ph11_loop:
	s_waitcnt lgkmcnt(1)
	v_mfma_f32_32x32x16_bf16 v[82:97], v[240:243], v[252:255], v[82:97]
	ds_read_b128 v[220:223], v210 offset:0
	s_add_u32 m0, s81, 0x5000
	s_nop 0
	global_load_lds_dwordx4 v202, s[70:71]
	v_mfma_f32_32x32x16_bf16 v[66:81], v[236:239], v[252:255], v[66:81]
	ds_read_b128 v[232:235], v214 offset:0
	s_add_u32 m0, s82, 0x0
	s_nop 0
	global_load_lds_dwordx4 v207, s[72:73]
	v_mfma_f32_32x32x16_bf16 v[50:65], v[240:243], v[248:251], v[50:65]
	ds_read_b128 v[216:219], v210 offset:4096
	s_add_u32 m0, s82, 0x1000
	s_nop 0
	global_load_lds_dwordx4 v206, s[72:73]
	v_mfma_f32_32x32x16_bf16 v[34:49], v[236:239], v[248:251], v[34:49]
	ds_read_b128 v[228:231], v214 offset:4096
	s_add_u32 m0, s82, 0x2000
	s_nop 0
	global_load_lds_dwordx4 v205, s[72:73]
	s_waitcnt lgkmcnt(4)
	v_mfma_f32_32x32x16_bf16 v[18:33], v[240:243], v[244:247], v[18:33]
	ds_read_b128 v[224:227], v214 offset:8192
	v_mfma_f32_32x32x16_bf16 v[2:17], v[236:239], v[244:247], v[2:17]
	s_add_u32 m0, s82, 0x3000
	s_nop 0
	global_load_lds_dwordx4 v204, s[72:73]
	s_waitcnt lgkmcnt(1)
	v_mfma_f32_32x32x16_bf16 v[82:97], v[220:223], v[232:235], v[82:97]
	ds_read_b128 v[240:243], v209 offset:0
	v_mfma_f32_32x32x16_bf16 v[66:81], v[216:219], v[232:235], v[66:81]
	ds_read_b128 v[252:255], v213 offset:0
	v_mfma_f32_32x32x16_bf16 v[50:65], v[220:223], v[228:231], v[50:65]
	ds_read_b128 v[236:239], v209 offset:4096
	v_mfma_f32_32x32x16_bf16 v[34:49], v[216:219], v[228:231], v[34:49]
	ds_read_b128 v[248:251], v213 offset:4096
	s_waitcnt lgkmcnt(4)
	v_mfma_f32_32x32x16_bf16 v[18:33], v[220:223], v[224:227], v[18:33]
	ds_read_b128 v[244:247], v213 offset:8192
	v_mfma_f32_32x32x16_bf16 v[2:17], v[216:219], v[224:227], v[2:17]
	s_waitcnt lgkmcnt(1)
	v_mfma_f32_32x32x16_bf16 v[82:97], v[240:243], v[252:255], v[82:97]
	ds_read_b128 v[220:223], v208 offset:0
	s_add_u32 s83, s79, s78
	s_add_u32 s83, s83, 2
	s_and_b32 s83, s83, 15
	v_mfma_f32_32x32x16_bf16 v[66:81], v[236:239], v[252:255], v[66:81]
	ds_read_b128 v[232:235], v212 offset:0
	s_lshl_b32 s83, s83, 7
	s_add_u32 s70, s66, s83
	v_mfma_f32_32x32x16_bf16 v[50:65], v[240:243], v[248:251], v[50:65]
	ds_read_b128 v[216:219], v208 offset:4096
	s_addc_u32 s71, s67, 0
	s_add_u32 s72, s68, s83
	v_mfma_f32_32x32x16_bf16 v[34:49], v[236:239], v[248:251], v[34:49]
	ds_read_b128 v[228:231], v212 offset:4096
	s_addc_u32 s73, s69, 0
	s_add_u32 s81, s80, 0x0
	s_add_u32 s82, s80, 0xc000
	s_waitcnt lgkmcnt(4)
	v_mfma_f32_32x32x16_bf16 v[18:33], v[240:243], v[244:247], v[18:33]
	ds_read_b128 v[224:227], v212 offset:8192
	v_mfma_f32_32x32x16_bf16 v[2:17], v[236:239], v[244:247], v[2:17]
	s_waitcnt vmcnt(0) lgkmcnt(0)
	s_barrier
	v_mfma_f32_32x32x16_bf16 v[82:97], v[220:223], v[232:235], v[82:97]
	s_add_u32 m0, s81, 0x0
	ds_read_b128 v[240:243], v211 offset:16384
	global_load_lds_dwordx4 v207, s[70:71]
	v_mfma_f32_32x32x16_bf16 v[66:81], v[216:219], v[232:235], v[66:81]
	s_add_u32 m0, s81, 0x1000
	ds_read_b128 v[252:255], v215 offset:24576
	global_load_lds_dwordx4 v206, s[70:71]
	v_mfma_f32_32x32x16_bf16 v[50:65], v[220:223], v[228:231], v[50:65]
	s_add_u32 m0, s81, 0x2000
	ds_read_b128 v[236:239], v211 offset:20480
	global_load_lds_dwordx4 v205, s[70:71]
	v_mfma_f32_32x32x16_bf16 v[34:49], v[216:219], v[228:231], v[34:49]
	s_add_u32 m0, s81, 0x3000
	ds_read_b128 v[248:251], v215 offset:28672
	global_load_lds_dwordx4 v204, s[70:71]
	v_mfma_f32_32x32x16_bf16 v[18:33], v[220:223], v[224:227], v[18:33]
	s_add_u32 m0, s81, 0x4000
	ds_read_b128 v[244:247], v215 offset:32768
	global_load_lds_dwordx4 v203, s[70:71]
	v_mfma_f32_32x32x16_bf16 v[2:17], v[216:219], v[224:227], v[2:17]
	s_waitcnt lgkmcnt(1)
	v_mfma_f32_32x32x16_bf16 v[82:97], v[240:243], v[252:255], v[82:97]
	ds_read_b128 v[220:223], v210 offset:16384
	s_add_u32 m0, s81, 0x5000
	s_nop 0
	global_load_lds_dwordx4 v202, s[70:71]
	v_mfma_f32_32x32x16_bf16 v[66:81], v[236:239], v[252:255], v[66:81]
	ds_read_b128 v[232:235], v214 offset:24576
	s_add_u32 m0, s82, 0x0
	s_nop 0
	global_load_lds_dwordx4 v207, s[72:73]
	v_mfma_f32_32x32x16_bf16 v[50:65], v[240:243], v[248:251], v[50:65]
	ds_read_b128 v[216:219], v210 offset:20480
	s_add_u32 m0, s82, 0x1000
	s_nop 0
	global_load_lds_dwordx4 v206, s[72:73]
	v_mfma_f32_32x32x16_bf16 v[34:49], v[236:239], v[248:251], v[34:49]
	ds_read_b128 v[228:231], v214 offset:28672
	s_add_u32 m0, s82, 0x2000
	s_nop 0
	global_load_lds_dwordx4 v205, s[72:73]
	s_waitcnt lgkmcnt(4)
	v_mfma_f32_32x32x16_bf16 v[18:33], v[240:243], v[244:247], v[18:33]
	ds_read_b128 v[224:227], v214 offset:32768
	v_mfma_f32_32x32x16_bf16 v[2:17], v[236:239], v[244:247], v[2:17]
	s_add_u32 m0, s82, 0x3000
	s_nop 0
	global_load_lds_dwordx4 v204, s[72:73]
	s_waitcnt lgkmcnt(1)
	v_mfma_f32_32x32x16_bf16 v[82:97], v[220:223], v[232:235], v[82:97]
	ds_read_b128 v[240:243], v209 offset:16384
	v_mfma_f32_32x32x16_bf16 v[66:81], v[216:219], v[232:235], v[66:81]
	ds_read_b128 v[252:255], v213 offset:24576
	v_mfma_f32_32x32x16_bf16 v[50:65], v[220:223], v[228:231], v[50:65]
	ds_read_b128 v[236:239], v209 offset:20480
	v_mfma_f32_32x32x16_bf16 v[34:49], v[216:219], v[228:231], v[34:49]
	ds_read_b128 v[248:251], v213 offset:28672
	s_waitcnt lgkmcnt(4)
	v_mfma_f32_32x32x16_bf16 v[18:33], v[220:223], v[224:227], v[18:33]
	ds_read_b128 v[244:247], v213 offset:32768
	v_mfma_f32_32x32x16_bf16 v[2:17], v[216:219], v[224:227], v[2:17]
	s_waitcnt lgkmcnt(1)
	v_mfma_f32_32x32x16_bf16 v[82:97], v[240:243], v[252:255], v[82:97]
	ds_read_b128 v[220:223], v208 offset:16384
	s_add_u32 s83, s79, s78
	s_add_u32 s83, s83, 3
	s_and_b32 s83, s83, 15
	v_mfma_f32_32x32x16_bf16 v[66:81], v[236:239], v[252:255], v[66:81]
	ds_read_b128 v[232:235], v212 offset:24576
	s_lshl_b32 s83, s83, 7
	s_add_u32 s70, s66, s83
	v_mfma_f32_32x32x16_bf16 v[50:65], v[240:243], v[248:251], v[50:65]
	ds_read_b128 v[216:219], v208 offset:20480
	s_addc_u32 s71, s67, 0
	s_add_u32 s72, s68, s83
	v_mfma_f32_32x32x16_bf16 v[34:49], v[236:239], v[248:251], v[34:49]
	ds_read_b128 v[228:231], v212 offset:28672
	s_addc_u32 s73, s69, 0
	s_add_u32 s81, s80, 0x6000
	s_add_u32 s82, s80, 0x10000
	s_waitcnt lgkmcnt(4)
	v_mfma_f32_32x32x16_bf16 v[18:33], v[240:243], v[244:247], v[18:33]
	ds_read_b128 v[224:227], v212 offset:32768
	v_mfma_f32_32x32x16_bf16 v[2:17], v[236:239], v[244:247], v[2:17]
	s_waitcnt vmcnt(0) lgkmcnt(0)
	s_barrier
	v_mfma_f32_32x32x16_bf16 v[82:97], v[220:223], v[232:235], v[82:97]
	s_add_u32 m0, s81, 0x0
	ds_read_b128 v[240:243], v211 offset:0
	global_load_lds_dwordx4 v207, s[70:71]
	v_mfma_f32_32x32x16_bf16 v[66:81], v[216:219], v[232:235], v[66:81]
	s_add_u32 m0, s81, 0x1000
	ds_read_b128 v[252:255], v215 offset:0
	global_load_lds_dwordx4 v206, s[70:71]
	v_mfma_f32_32x32x16_bf16 v[50:65], v[220:223], v[228:231], v[50:65]
	s_add_u32 m0, s81, 0x2000
	ds_read_b128 v[236:239], v211 offset:4096
	global_load_lds_dwordx4 v205, s[70:71]
	v_mfma_f32_32x32x16_bf16 v[34:49], v[216:219], v[228:231], v[34:49]
	s_add_u32 m0, s81, 0x3000
	ds_read_b128 v[248:251], v215 offset:4096
	global_load_lds_dwordx4 v204, s[70:71]
	v_mfma_f32_32x32x16_bf16 v[18:33], v[220:223], v[224:227], v[18:33]
	s_add_u32 m0, s81, 0x4000
	ds_read_b128 v[244:247], v215 offset:8192
	global_load_lds_dwordx4 v203, s[70:71]
	v_mfma_f32_32x32x16_bf16 v[2:17], v[216:219], v[224:227], v[2:17]
	s_add_u32 s78, s78, 2
	s_cmp_lt_u32 s78, 14
	s_cbranch_scc1 .Lgm_ph11_loop
	s_waitcnt lgkmcnt(1)
	v_mfma_f32_32x32x16_bf16 v[82:97], v[240:243], v[252:255], v[82:97]
	ds_read_b128 v[220:223], v210 offset:0
	s_add_u32 m0, s81, 0x5000
	s_nop 0
	global_load_lds_dwordx4 v202, s[70:71]
	v_mfma_f32_32x32x16_bf16 v[66:81], v[236:239], v[252:255], v[66:81]
	ds_read_b128 v[232:235], v214 offset:0
	s_add_u32 m0, s82, 0x0
	s_nop 0
	global_load_lds_dwordx4 v207, s[72:73]
	v_mfma_f32_32x32x16_bf16 v[50:65], v[240:243], v[248:251], v[50:65]
	ds_read_b128 v[216:219], v210 offset:4096
	s_add_u32 m0, s82, 0x1000
	s_nop 0
	global_load_lds_dwordx4 v206, s[72:73]
	v_mfma_f32_32x32x16_bf16 v[34:49], v[236:239], v[248:251], v[34:49]
	ds_read_b128 v[228:231], v214 offset:4096
	s_add_u32 m0, s82, 0x2000
	s_nop 0
	global_load_lds_dwordx4 v205, s[72:73]
	s_waitcnt lgkmcnt(4)
	v_mfma_f32_32x32x16_bf16 v[18:33], v[240:243], v[244:247], v[18:33]
	ds_read_b128 v[224:227], v214 offset:8192
	v_mfma_f32_32x32x16_bf16 v[2:17], v[236:239], v[244:247], v[2:17]
	s_add_u32 m0, s82, 0x3000
	s_nop 0
	global_load_lds_dwordx4 v204, s[72:73]
	s_waitcnt lgkmcnt(1)
	v_mfma_f32_32x32x16_bf16 v[82:97], v[220:223], v[232:235], v[82:97]
	ds_read_b128 v[240:243], v209 offset:0
	v_mfma_f32_32x32x16_bf16 v[66:81], v[216:219], v[232:235], v[66:81]
	ds_read_b128 v[252:255], v213 offset:0
	v_mfma_f32_32x32x16_bf16 v[50:65], v[220:223], v[228:231], v[50:65]
	ds_read_b128 v[236:239], v209 offset:4096
	v_mfma_f32_32x32x16_bf16 v[34:49], v[216:219], v[228:231], v[34:49]
	ds_read_b128 v[248:251], v213 offset:4096
	s_waitcnt lgkmcnt(4)
	v_mfma_f32_32x32x16_bf16 v[18:33], v[220:223], v[224:227], v[18:33]
	ds_read_b128 v[244:247], v213 offset:8192
	v_mfma_f32_32x32x16_bf16 v[2:17], v[216:219], v[224:227], v[2:17]
	s_waitcnt lgkmcnt(1)
	v_mfma_f32_32x32x16_bf16 v[82:97], v[240:243], v[252:255], v[82:97]
	ds_read_b128 v[220:223], v208 offset:0
	v_mfma_f32_32x32x16_bf16 v[66:81], v[236:239], v[252:255], v[66:81]
	ds_read_b128 v[232:235], v212 offset:0
	v_mfma_f32_32x32x16_bf16 v[50:65], v[240:243], v[248:251], v[50:65]
	ds_read_b128 v[216:219], v208 offset:4096
	v_mfma_f32_32x32x16_bf16 v[34:49], v[236:239], v[248:251], v[34:49]
	ds_read_b128 v[228:231], v212 offset:4096
	s_waitcnt lgkmcnt(4)
	v_mfma_f32_32x32x16_bf16 v[18:33], v[240:243], v[244:247], v[18:33]
	ds_read_b128 v[224:227], v212 offset:8192
	v_mfma_f32_32x32x16_bf16 v[2:17], v[236:239], v[244:247], v[2:17]
	s_waitcnt vmcnt(0) lgkmcnt(0)
	s_barrier
	v_mfma_f32_32x32x16_bf16 v[82:97], v[220:223], v[232:235], v[82:97]
	ds_read_b128 v[240:243], v211 offset:16384
	v_mfma_f32_32x32x16_bf16 v[66:81], v[216:219], v[232:235], v[66:81]
	ds_read_b128 v[252:255], v215 offset:24576
	v_mfma_f32_32x32x16_bf16 v[50:65], v[220:223], v[228:231], v[50:65]
	ds_read_b128 v[236:239], v211 offset:20480
	v_mfma_f32_32x32x16_bf16 v[34:49], v[216:219], v[228:231], v[34:49]
	ds_read_b128 v[248:251], v215 offset:28672
	v_mfma_f32_32x32x16_bf16 v[18:33], v[220:223], v[224:227], v[18:33]
	ds_read_b128 v[244:247], v215 offset:32768
	v_mfma_f32_32x32x16_bf16 v[2:17], v[216:219], v[224:227], v[2:17]
	s_waitcnt lgkmcnt(1)
	v_mfma_f32_32x32x16_bf16 v[82:97], v[240:243], v[252:255], v[82:97]
	ds_read_b128 v[220:223], v210 offset:16384
	v_mfma_f32_32x32x16_bf16 v[66:81], v[236:239], v[252:255], v[66:81]
	ds_read_b128 v[232:235], v214 offset:24576
	v_mfma_f32_32x32x16_bf16 v[50:65], v[240:243], v[248:251], v[50:65]
	ds_read_b128 v[216:219], v210 offset:20480
	v_mfma_f32_32x32x16_bf16 v[34:49], v[236:239], v[248:251], v[34:49]
	ds_read_b128 v[228:231], v214 offset:28672
	s_waitcnt lgkmcnt(4)
	v_mfma_f32_32x32x16_bf16 v[18:33], v[240:243], v[244:247], v[18:33]
	ds_read_b128 v[224:227], v214 offset:32768
	v_mfma_f32_32x32x16_bf16 v[2:17], v[236:239], v[244:247], v[2:17]
	s_waitcnt lgkmcnt(1)
	v_mfma_f32_32x32x16_bf16 v[82:97], v[220:223], v[232:235], v[82:97]
	ds_read_b128 v[240:243], v209 offset:16384
	v_mfma_f32_32x32x16_bf16 v[66:81], v[216:219], v[232:235], v[66:81]
	ds_read_b128 v[252:255], v213 offset:24576
	v_mfma_f32_32x32x16_bf16 v[50:65], v[220:223], v[228:231], v[50:65]
	ds_read_b128 v[236:239], v209 offset:20480
	v_mfma_f32_32x32x16_bf16 v[34:49], v[216:219], v[228:231], v[34:49]
	ds_read_b128 v[248:251], v213 offset:28672
	s_waitcnt lgkmcnt(4)
	v_mfma_f32_32x32x16_bf16 v[18:33], v[220:223], v[224:227], v[18:33]
	ds_read_b128 v[244:247], v213 offset:32768
	v_mfma_f32_32x32x16_bf16 v[2:17], v[216:219], v[224:227], v[2:17]
	s_waitcnt lgkmcnt(1)
	v_mfma_f32_32x32x16_bf16 v[82:97], v[240:243], v[252:255], v[82:97]
	ds_read_b128 v[220:223], v208 offset:16384
	v_mfma_f32_32x32x16_bf16 v[66:81], v[236:239], v[252:255], v[66:81]
	ds_read_b128 v[232:235], v212 offset:24576
	v_mfma_f32_32x32x16_bf16 v[50:65], v[240:243], v[248:251], v[50:65]
	ds_read_b128 v[216:219], v208 offset:20480
	v_mfma_f32_32x32x16_bf16 v[34:49], v[236:239], v[248:251], v[34:49]
	ds_read_b128 v[228:231], v212 offset:28672
	s_waitcnt lgkmcnt(4)
	v_mfma_f32_32x32x16_bf16 v[18:33], v[240:243], v[244:247], v[18:33]
	ds_read_b128 v[224:227], v212 offset:32768
	v_mfma_f32_32x32x16_bf16 v[2:17], v[236:239], v[244:247], v[2:17]
	s_waitcnt vmcnt(0) lgkmcnt(0)
	s_barrier
	v_mfma_f32_32x32x16_bf16 v[82:97], v[220:223], v[232:235], v[82:97]
	v_mfma_f32_32x32x16_bf16 v[66:81], v[216:219], v[232:235], v[66:81]
	v_mfma_f32_32x32x16_bf16 v[50:65], v[220:223], v[228:231], v[50:65]
	v_mfma_f32_32x32x16_bf16 v[34:49], v[216:219], v[228:231], v[34:49]
	v_mfma_f32_32x32x16_bf16 v[18:33], v[220:223], v[224:227], v[18:33]
	v_mfma_f32_32x32x16_bf16 v[2:17], v[216:219], v[224:227], v[2:17]
	s_nop 7
	s_nop 7
	s_waitcnt lgkmcnt(0)
	s_nop 10
	ds_write_b128 v147, v[82:85]
	ds_write_b128 v147, v[86:89] offset:32
	ds_write_b128 v147, v[90:93] offset:64
	ds_write_b128 v147, v[94:97] offset:96
	ds_write_b128 v147, v[66:69] offset:128
	ds_write_b128 v147, v[70:73] offset:160
	ds_write_b128 v147, v[74:77] offset:192
	ds_write_b128 v147, v[78:81] offset:224
	s_waitcnt lgkmcnt(0)
	v_add_u32_e32 v104, s29, v111
	v_or_b32_e32 v244, s30, v120
	v_lshlrev_b32_e32 v242, 2, v244
	v_add_u32_e32 v242, s3, v242
	v_lshlrev_b32_e32 v243, 1, v244
	v_mov_b32_e32 v240, v104
	v_add_u32_e32 v241, 0xfffff000, v240
	v_lshrrev_b32_e32 v241, 11, v241
	v_mad_u32_u24 v241, v241, s26, s26
	v_lshlrev_b32_e32 v241, 2, v241
	v_or_b32_e32 v232, v240, v119
	v_or_b32_e32 v233, v240, v121
	v_or_b32_e32 v234, v240, v122
	v_or_b32_e32 v235, v240, v123
	v_or_b32_e32 v236, v240, v124
	v_or_b32_e32 v237, v240, v125
	v_or_b32_e32 v238, v240, v126
	v_or_b32_e32 v239, v240, v127
	v_cmp_lt_i32_e64 s[82:83], s27, v232
	v_cmp_lt_i32_e64 s[84:85], s27, v233
	v_cmp_lt_i32_e64 s[86:87], s27, v234
	v_cmp_lt_i32_e64 s[88:89], s27, v235
	v_cmp_lt_i32_e64 s[90:91], s27, v236
	v_cmp_lt_i32_e64 s[92:93], s27, v237
	v_cmp_lt_i32_e64 s[94:95], s27, v238
	v_cmp_lt_i32_e64 s[96:97], s27, v239
	s_waitcnt lgkmcnt(0)
	v_cndmask_b32_e64 v200, 0, v241, s[82:83]
	v_cndmask_b32_e64 v204, 0, v241, s[84:85]
	v_cndmask_b32_e64 v208, 0, v241, s[86:87]
	v_cndmask_b32_e64 v212, 0, v241, s[88:89]
	v_cndmask_b32_e64 v216, 0, v241, s[90:91]
	v_cndmask_b32_e64 v220, 0, v241, s[92:93]
	v_cndmask_b32_e64 v224, 0, v241, s[94:95]
	v_cndmask_b32_e64 v228, 0, v241, s[96:97]
	v_add_u32_e32 v200, v200, v242
	v_add_u32_e32 v204, v204, v242
	v_add_u32_e32 v208, v208, v242
	v_add_u32_e32 v212, v212, v242
	v_add_u32_e32 v216, v216, v242
	v_add_u32_e32 v220, v220, v242
	v_add_u32_e32 v224, v224, v242
	v_add_u32_e32 v228, v228, v242
	ds_read_b128 v[82:85], v149
	global_load_dwordx4 v[200:203], v200, s[6:7]
	ds_read_b128 v[86:89], v149 offset:1088
	global_load_dwordx4 v[204:207], v204, s[6:7]
	ds_read_b128 v[90:93], v149 offset:2176
	global_load_dwordx4 v[208:211], v208, s[6:7]
	ds_read_b128 v[94:97], v149 offset:3264
	global_load_dwordx4 v[212:215], v212, s[6:7]
	ds_read_b128 v[66:69], v149 offset:4352
	global_load_dwordx4 v[216:219], v216, s[6:7]
	ds_read_b128 v[70:73], v149 offset:5440
	global_load_dwordx4 v[220:223], v220, s[6:7]
	ds_read_b128 v[74:77], v149 offset:6528
	global_load_dwordx4 v[224:227], v224, s[6:7]
	ds_read_b128 v[78:81], v149 offset:7616
	global_load_dwordx4 v[228:231], v228, s[6:7]
	v_lshl_add_u32 v232, v232, 11, v243
	v_lshl_add_u32 v233, v233, 11, v243
	v_lshl_add_u32 v234, v234, 11, v243
	v_lshl_add_u32 v235, v235, 11, v243
	v_lshl_add_u32 v236, v236, 11, v243
	v_lshl_add_u32 v237, v237, 11, v243
	v_lshl_add_u32 v238, v238, 11, v243
	v_lshl_add_u32 v239, v239, 11, v243
	s_waitcnt vmcnt(7) lgkmcnt(7)
	v_mul_f32_e32 v82, v82, v200
	v_mul_f32_e32 v83, v83, v201
	v_mul_f32_e32 v84, v84, v202
	v_mul_f32_e32 v85, v85, v203
	v_cvt_pk_bf16_f32 v82, v82, v83
	v_cvt_pk_bf16_f32 v83, v84, v85
	global_store_dwordx2 v232, v[82:83], s[4:5] sc1
	s_waitcnt vmcnt(7) lgkmcnt(6)
	v_mul_f32_e32 v86, v86, v204
	v_mul_f32_e32 v87, v87, v205
	v_mul_f32_e32 v88, v88, v206
	v_mul_f32_e32 v89, v89, v207
	v_cvt_pk_bf16_f32 v86, v86, v87
	v_cvt_pk_bf16_f32 v87, v88, v89
	global_store_dwordx2 v233, v[86:87], s[4:5] sc1
	s_waitcnt vmcnt(7) lgkmcnt(5)
	v_mul_f32_e32 v90, v90, v208
	v_mul_f32_e32 v91, v91, v209
	v_mul_f32_e32 v92, v92, v210
	v_mul_f32_e32 v93, v93, v211
	v_cvt_pk_bf16_f32 v90, v90, v91
	v_cvt_pk_bf16_f32 v91, v92, v93
	global_store_dwordx2 v234, v[90:91], s[4:5] sc1
	s_waitcnt vmcnt(7) lgkmcnt(4)
	v_mul_f32_e32 v94, v94, v212
	v_mul_f32_e32 v95, v95, v213
	v_mul_f32_e32 v96, v96, v214
	v_mul_f32_e32 v97, v97, v215
	v_cvt_pk_bf16_f32 v94, v94, v95
	v_cvt_pk_bf16_f32 v95, v96, v97
	global_store_dwordx2 v235, v[94:95], s[4:5] sc1
	s_waitcnt vmcnt(7) lgkmcnt(3)
	v_mul_f32_e32 v66, v66, v216
	v_mul_f32_e32 v67, v67, v217
	v_mul_f32_e32 v68, v68, v218
	v_mul_f32_e32 v69, v69, v219
	v_cvt_pk_bf16_f32 v66, v66, v67
	v_cvt_pk_bf16_f32 v67, v68, v69
	global_store_dwordx2 v236, v[66:67], s[4:5] sc1
	s_waitcnt vmcnt(7) lgkmcnt(2)
	v_mul_f32_e32 v70, v70, v220
	v_mul_f32_e32 v71, v71, v221
	v_mul_f32_e32 v72, v72, v222
	v_mul_f32_e32 v73, v73, v223
	v_cvt_pk_bf16_f32 v70, v70, v71
	v_cvt_pk_bf16_f32 v71, v72, v73
	global_store_dwordx2 v237, v[70:71], s[4:5] sc1
	s_waitcnt vmcnt(7) lgkmcnt(1)
	v_mul_f32_e32 v74, v74, v224
	v_mul_f32_e32 v75, v75, v225
	v_mul_f32_e32 v76, v76, v226
	v_mul_f32_e32 v77, v77, v227
	v_cvt_pk_bf16_f32 v74, v74, v75
	v_cvt_pk_bf16_f32 v75, v76, v77
	global_store_dwordx2 v238, v[74:75], s[4:5] sc1
	s_waitcnt vmcnt(7) lgkmcnt(0)
	v_mul_f32_e32 v78, v78, v228
	v_mul_f32_e32 v79, v79, v229
	v_mul_f32_e32 v80, v80, v230
	v_mul_f32_e32 v81, v81, v231
	v_cvt_pk_bf16_f32 v78, v78, v79
	v_cvt_pk_bf16_f32 v79, v80, v81
	global_store_dwordx2 v239, v[78:79], s[4:5] sc1
	ds_write_b128 v147, v[50:53]
	ds_write_b128 v147, v[54:57] offset:32
	ds_write_b128 v147, v[58:61] offset:64
	ds_write_b128 v147, v[62:65] offset:96
	ds_write_b128 v147, v[34:37] offset:128
	ds_write_b128 v147, v[38:41] offset:160
	ds_write_b128 v147, v[42:45] offset:192
	ds_write_b128 v147, v[46:49] offset:224
	v_add_u32_e32 v240, 0x20, v104
	v_add_u32_e32 v241, 0xfffff000, v240
	v_lshrrev_b32_e32 v241, 11, v241
	v_mad_u32_u24 v241, v241, s26, s26
	v_lshlrev_b32_e32 v241, 2, v241
	v_or_b32_e32 v232, v240, v119
	v_or_b32_e32 v233, v240, v121
	v_or_b32_e32 v234, v240, v122
	v_or_b32_e32 v235, v240, v123
	v_or_b32_e32 v236, v240, v124
	v_or_b32_e32 v237, v240, v125
	v_or_b32_e32 v238, v240, v126
	v_or_b32_e32 v239, v240, v127
	v_cmp_lt_i32_e64 s[82:83], s27, v232
	v_cmp_lt_i32_e64 s[84:85], s27, v233
	v_cmp_lt_i32_e64 s[86:87], s27, v234
	v_cmp_lt_i32_e64 s[88:89], s27, v235
	v_cmp_lt_i32_e64 s[90:91], s27, v236
	v_cmp_lt_i32_e64 s[92:93], s27, v237
	v_cmp_lt_i32_e64 s[94:95], s27, v238
	v_cmp_lt_i32_e64 s[96:97], s27, v239
	s_waitcnt lgkmcnt(0)
	v_cndmask_b32_e64 v200, 0, v241, s[82:83]
	v_cndmask_b32_e64 v204, 0, v241, s[84:85]
	v_cndmask_b32_e64 v208, 0, v241, s[86:87]
	v_cndmask_b32_e64 v212, 0, v241, s[88:89]
	v_cndmask_b32_e64 v216, 0, v241, s[90:91]
	v_cndmask_b32_e64 v220, 0, v241, s[92:93]
	v_cndmask_b32_e64 v224, 0, v241, s[94:95]
	v_cndmask_b32_e64 v228, 0, v241, s[96:97]
	v_add_u32_e32 v200, v200, v242
	v_add_u32_e32 v204, v204, v242
	v_add_u32_e32 v208, v208, v242
	v_add_u32_e32 v212, v212, v242
	v_add_u32_e32 v216, v216, v242
	v_add_u32_e32 v220, v220, v242
	v_add_u32_e32 v224, v224, v242
	v_add_u32_e32 v228, v228, v242
	ds_read_b128 v[50:53], v149
	global_load_dwordx4 v[200:203], v200, s[6:7]
	ds_read_b128 v[54:57], v149 offset:1088
	global_load_dwordx4 v[204:207], v204, s[6:7]
	ds_read_b128 v[58:61], v149 offset:2176
	global_load_dwordx4 v[208:211], v208, s[6:7]
	ds_read_b128 v[62:65], v149 offset:3264
	global_load_dwordx4 v[212:215], v212, s[6:7]
	ds_read_b128 v[34:37], v149 offset:4352
	global_load_dwordx4 v[216:219], v216, s[6:7]
	ds_read_b128 v[38:41], v149 offset:5440
	global_load_dwordx4 v[220:223], v220, s[6:7]
	ds_read_b128 v[42:45], v149 offset:6528
	global_load_dwordx4 v[224:227], v224, s[6:7]
	ds_read_b128 v[46:49], v149 offset:7616
	global_load_dwordx4 v[228:231], v228, s[6:7]
	v_lshl_add_u32 v232, v232, 11, v243
	v_lshl_add_u32 v233, v233, 11, v243
	v_lshl_add_u32 v234, v234, 11, v243
	v_lshl_add_u32 v235, v235, 11, v243
	v_lshl_add_u32 v236, v236, 11, v243
	v_lshl_add_u32 v237, v237, 11, v243
	v_lshl_add_u32 v238, v238, 11, v243
	v_lshl_add_u32 v239, v239, 11, v243
	s_waitcnt vmcnt(7) lgkmcnt(7)
	v_mul_f32_e32 v50, v50, v200
	v_mul_f32_e32 v51, v51, v201
	v_mul_f32_e32 v52, v52, v202
	v_mul_f32_e32 v53, v53, v203
	v_cvt_pk_bf16_f32 v50, v50, v51
	v_cvt_pk_bf16_f32 v51, v52, v53
	global_store_dwordx2 v232, v[50:51], s[4:5] sc1
	s_waitcnt vmcnt(7) lgkmcnt(6)
	v_mul_f32_e32 v54, v54, v204
	v_mul_f32_e32 v55, v55, v205
	v_mul_f32_e32 v56, v56, v206
	v_mul_f32_e32 v57, v57, v207
	v_cvt_pk_bf16_f32 v54, v54, v55
	v_cvt_pk_bf16_f32 v55, v56, v57
	global_store_dwordx2 v233, v[54:55], s[4:5] sc1
	s_waitcnt vmcnt(7) lgkmcnt(5)
	v_mul_f32_e32 v58, v58, v208
	v_mul_f32_e32 v59, v59, v209
	v_mul_f32_e32 v60, v60, v210
	v_mul_f32_e32 v61, v61, v211
	v_cvt_pk_bf16_f32 v58, v58, v59
	v_cvt_pk_bf16_f32 v59, v60, v61
	global_store_dwordx2 v234, v[58:59], s[4:5] sc1
	s_waitcnt vmcnt(7) lgkmcnt(4)
	v_mul_f32_e32 v62, v62, v212
	v_mul_f32_e32 v63, v63, v213
	v_mul_f32_e32 v64, v64, v214
	v_mul_f32_e32 v65, v65, v215
	v_cvt_pk_bf16_f32 v62, v62, v63
	v_cvt_pk_bf16_f32 v63, v64, v65
	global_store_dwordx2 v235, v[62:63], s[4:5] sc1
	s_waitcnt vmcnt(7) lgkmcnt(3)
	v_mul_f32_e32 v34, v34, v216
	v_mul_f32_e32 v35, v35, v217
	v_mul_f32_e32 v36, v36, v218
	v_mul_f32_e32 v37, v37, v219
	v_cvt_pk_bf16_f32 v34, v34, v35
	v_cvt_pk_bf16_f32 v35, v36, v37
	global_store_dwordx2 v236, v[34:35], s[4:5] sc1
	s_waitcnt vmcnt(7) lgkmcnt(2)
	v_mul_f32_e32 v38, v38, v220
	v_mul_f32_e32 v39, v39, v221
	v_mul_f32_e32 v40, v40, v222
	v_mul_f32_e32 v41, v41, v223
	v_cvt_pk_bf16_f32 v38, v38, v39
	v_cvt_pk_bf16_f32 v39, v40, v41
	global_store_dwordx2 v237, v[38:39], s[4:5] sc1
	s_waitcnt vmcnt(7) lgkmcnt(1)
	v_mul_f32_e32 v42, v42, v224
	v_mul_f32_e32 v43, v43, v225
	v_mul_f32_e32 v44, v44, v226
	v_mul_f32_e32 v45, v45, v227
	v_cvt_pk_bf16_f32 v42, v42, v43
	v_cvt_pk_bf16_f32 v43, v44, v45
	global_store_dwordx2 v238, v[42:43], s[4:5] sc1
	s_waitcnt vmcnt(7) lgkmcnt(0)
	v_mul_f32_e32 v46, v46, v228
	v_mul_f32_e32 v47, v47, v229
	v_mul_f32_e32 v48, v48, v230
	v_mul_f32_e32 v49, v49, v231
	v_cvt_pk_bf16_f32 v46, v46, v47
	v_cvt_pk_bf16_f32 v47, v48, v49
	global_store_dwordx2 v239, v[46:47], s[4:5] sc1
	ds_write_b128 v147, v[18:21]
	ds_write_b128 v147, v[22:25] offset:32
	ds_write_b128 v147, v[26:29] offset:64
	ds_write_b128 v147, v[30:33] offset:96
	ds_write_b128 v147, v[2:5] offset:128
	ds_write_b128 v147, v[6:9] offset:160
	ds_write_b128 v147, v[10:13] offset:192
	ds_write_b128 v147, v[14:17] offset:224
	v_add_u32_e32 v240, 0x40, v104
	v_add_u32_e32 v241, 0xfffff000, v240
	v_lshrrev_b32_e32 v241, 11, v241
	v_mad_u32_u24 v241, v241, s26, s26
	v_lshlrev_b32_e32 v241, 2, v241
	v_or_b32_e32 v232, v240, v119
	v_or_b32_e32 v233, v240, v121
	v_or_b32_e32 v234, v240, v122
	v_or_b32_e32 v235, v240, v123
	v_or_b32_e32 v236, v240, v124
	v_or_b32_e32 v237, v240, v125
	v_or_b32_e32 v238, v240, v126
	v_or_b32_e32 v239, v240, v127
	v_cmp_lt_i32_e64 s[82:83], s27, v232
	v_cmp_lt_i32_e64 s[84:85], s27, v233
	v_cmp_lt_i32_e64 s[86:87], s27, v234
	v_cmp_lt_i32_e64 s[88:89], s27, v235
	v_cmp_lt_i32_e64 s[90:91], s27, v236
	v_cmp_lt_i32_e64 s[92:93], s27, v237
	v_cmp_lt_i32_e64 s[94:95], s27, v238
	v_cmp_lt_i32_e64 s[96:97], s27, v239
	s_waitcnt lgkmcnt(0)
	v_cndmask_b32_e64 v200, 0, v241, s[82:83]
	v_cndmask_b32_e64 v204, 0, v241, s[84:85]
	v_cndmask_b32_e64 v208, 0, v241, s[86:87]
	v_cndmask_b32_e64 v212, 0, v241, s[88:89]
	v_cndmask_b32_e64 v216, 0, v241, s[90:91]
	v_cndmask_b32_e64 v220, 0, v241, s[92:93]
	v_cndmask_b32_e64 v224, 0, v241, s[94:95]
	v_cndmask_b32_e64 v228, 0, v241, s[96:97]
	v_add_u32_e32 v200, v200, v242
	v_add_u32_e32 v204, v204, v242
	v_add_u32_e32 v208, v208, v242
	v_add_u32_e32 v212, v212, v242
	v_add_u32_e32 v216, v216, v242
	v_add_u32_e32 v220, v220, v242
	v_add_u32_e32 v224, v224, v242
	v_add_u32_e32 v228, v228, v242
	ds_read_b128 v[18:21], v149
	global_load_dwordx4 v[200:203], v200, s[6:7]
	ds_read_b128 v[22:25], v149 offset:1088
	global_load_dwordx4 v[204:207], v204, s[6:7]
	ds_read_b128 v[26:29], v149 offset:2176
	global_load_dwordx4 v[208:211], v208, s[6:7]
	ds_read_b128 v[30:33], v149 offset:3264
	global_load_dwordx4 v[212:215], v212, s[6:7]
	ds_read_b128 v[2:5], v149 offset:4352
	global_load_dwordx4 v[216:219], v216, s[6:7]
	ds_read_b128 v[6:9], v149 offset:5440
	global_load_dwordx4 v[220:223], v220, s[6:7]
	ds_read_b128 v[10:13], v149 offset:6528
	global_load_dwordx4 v[224:227], v224, s[6:7]
	ds_read_b128 v[14:17], v149 offset:7616
	global_load_dwordx4 v[228:231], v228, s[6:7]
	v_lshl_add_u32 v232, v232, 11, v243
	v_lshl_add_u32 v233, v233, 11, v243
	v_lshl_add_u32 v234, v234, 11, v243
	v_lshl_add_u32 v235, v235, 11, v243
	v_lshl_add_u32 v236, v236, 11, v243
	v_lshl_add_u32 v237, v237, 11, v243
	v_lshl_add_u32 v238, v238, 11, v243
	v_lshl_add_u32 v239, v239, 11, v243
	s_waitcnt vmcnt(7) lgkmcnt(7)
	v_mul_f32_e32 v18, v18, v200
	v_mul_f32_e32 v19, v19, v201
	v_mul_f32_e32 v20, v20, v202
	v_mul_f32_e32 v21, v21, v203
	v_cvt_pk_bf16_f32 v18, v18, v19
	v_cvt_pk_bf16_f32 v19, v20, v21
	global_store_dwordx2 v232, v[18:19], s[4:5] sc1
	s_waitcnt vmcnt(7) lgkmcnt(6)
	v_mul_f32_e32 v22, v22, v204
	v_mul_f32_e32 v23, v23, v205
	v_mul_f32_e32 v24, v24, v206
	v_mul_f32_e32 v25, v25, v207
	v_cvt_pk_bf16_f32 v22, v22, v23
	v_cvt_pk_bf16_f32 v23, v24, v25
	global_store_dwordx2 v233, v[22:23], s[4:5] sc1
	s_waitcnt vmcnt(7) lgkmcnt(5)
	v_mul_f32_e32 v26, v26, v208
	v_mul_f32_e32 v27, v27, v209
	v_mul_f32_e32 v28, v28, v210
	v_mul_f32_e32 v29, v29, v211
	v_cvt_pk_bf16_f32 v26, v26, v27
	v_cvt_pk_bf16_f32 v27, v28, v29
	global_store_dwordx2 v234, v[26:27], s[4:5] sc1
	s_waitcnt vmcnt(7) lgkmcnt(4)
	v_mul_f32_e32 v30, v30, v212
	v_mul_f32_e32 v31, v31, v213
	v_mul_f32_e32 v32, v32, v214
	v_mul_f32_e32 v33, v33, v215
	v_cvt_pk_bf16_f32 v30, v30, v31
	v_cvt_pk_bf16_f32 v31, v32, v33
	global_store_dwordx2 v235, v[30:31], s[4:5] sc1
	s_waitcnt vmcnt(7) lgkmcnt(3)
	v_mul_f32_e32 v2, v2, v216
	v_mul_f32_e32 v3, v3, v217
	v_mul_f32_e32 v4, v4, v218
	v_mul_f32_e32 v5, v5, v219
	v_cvt_pk_bf16_f32 v2, v2, v3
	v_cvt_pk_bf16_f32 v3, v4, v5
	global_store_dwordx2 v236, v[2:3], s[4:5] sc1
	s_waitcnt vmcnt(7) lgkmcnt(2)
	v_mul_f32_e32 v6, v6, v220
	v_mul_f32_e32 v7, v7, v221
	v_mul_f32_e32 v8, v8, v222
	v_mul_f32_e32 v9, v9, v223
	v_cvt_pk_bf16_f32 v6, v6, v7
	v_cvt_pk_bf16_f32 v7, v8, v9
	global_store_dwordx2 v237, v[6:7], s[4:5] sc1
	s_waitcnt vmcnt(7) lgkmcnt(1)
	v_mul_f32_e32 v10, v10, v224
	v_mul_f32_e32 v11, v11, v225
	v_mul_f32_e32 v12, v12, v226
	v_mul_f32_e32 v13, v13, v227
	v_cvt_pk_bf16_f32 v10, v10, v11
	v_cvt_pk_bf16_f32 v11, v12, v13
	global_store_dwordx2 v238, v[10:11], s[4:5] sc1
	s_waitcnt vmcnt(7) lgkmcnt(0)
	v_mul_f32_e32 v14, v14, v228
	v_mul_f32_e32 v15, v15, v229
	v_mul_f32_e32 v16, v16, v230
	v_mul_f32_e32 v17, v17, v231
	v_cvt_pk_bf16_f32 v14, v14, v15
	v_cvt_pk_bf16_f32 v15, v16, v17
	global_store_dwordx2 v239, v[14:15], s[4:5] sc1
	s_waitcnt lgkmcnt(0)
	s_load_dword s10, s[8:9], 0x0
	s_waitcnt lgkmcnt(0)
	s_add_i32 s28, s10, s28
	s_cmpk_lt_i32 s28, 0x200
	s_cbranch_scc1 .LBB0_1133

.LBB0_1270:
	s_ashr_i32 s4, s64, 31
	s_lshr_b32 s4, s4, 26
	s_add_i32 s4, s64, s4
	s_ashr_i32 s5, s4, 6
	s_and_b32 s4, s4, 0x3ffffc0
	s_sub_i32 s6, s64, s4
	s_mulk_i32 s6, 0xc0
	v_add_u32_e32 v2, s6, v116
	s_lshr_b32 s7, s6, 6
	s_lshl_b32 s4, s5, 7
	v_ashrrev_i32_e32 v3, 31, v2
	s_add_i32 s7, s7, s5
	v_lshlrev_b64 v[2:3], 11, v[2:3]
	v_or_b32_e32 v4, s4, v116
	s_lshl_b32 s46, s7, 6
	s_lshl_b32 s7, s7, 7
	v_ashrrev_i32_e32 v5, 31, v4
	v_lshl_add_u64 v[112:113], v[104:105], 0, v[2:3]
	s_and_b32 s16, s7, 0x780
	v_readfirstlane_b32 s7, v117
	v_add_u32_e32 v6, 0x1000, v117
	v_lshlrev_b64 v[4:5], 11, v[4:5]
	v_lshl_add_u64 v[2:3], v[112:113], 0, s[16:17]
	s_mov_b32 m0, s7
	v_readfirstlane_b32 s7, v6
	v_add_u32_e32 v6, 0x2000, v117
	v_lshl_add_u64 v[114:115], v[106:107], 0, v[4:5]
	s_waitcnt vmcnt(0)
	s_barrier
	s_load_dwordx2 s[66:67], s[0:1], 0x90
	s_load_dwordx2 s[68:69], s[0:1], 0xf8
	v_and_b32_e32 v201, 0x3ff, v0
	v_readfirstlane_b32 s80, v0
	v_and_b32_e32 v200, 31, v201
	v_bfe_u32 v214, v201, 1, 3
	v_bfe_u32 v213, v201, 5, 1
	v_xor_b32_e32 v214, v214, v213
	v_lshlrev_b32_e32 v214, 4, v214
	s_and_b32 s80, s80, 0x3ff
	s_lshr_b32 s83, s80, 6
	s_lshl_b32 s80, s80, 4
	s_lshr_b32 s84, s83, 1
	s_and_b32 s83, s83, 1
	s_mul_i32 s84, s84, 0x3000
	s_lshl_b32 s83, s83, 13
	s_add_u32 s83, s83, 0xc000
	v_lshlrev_b32_e32 v200, 7, v200
	v_or_b32_e32 v200, v200, v214
	v_add_u32_e32 v215, s84, v200
	v_add_u32_e32 v211, s83, v200
	v_xor_b32_e32 v214, 0x20, v215
	v_xor_b32_e32 v210, 0x20, v211
	v_xor_b32_e32 v213, 0x40, v215
	v_xor_b32_e32 v209, 0x40, v211
	v_xor_b32_e32 v212, 0x60, v215
	v_xor_b32_e32 v208, 0x60, v211
	v_bfe_u32 v200, v201, 4, 3
	v_and_b32_e32 v206, 7, v201
	v_xor_b32_e32 v200, v200, v206
	v_lshlrev_b32_e32 v200, 4, v200
	v_lshrrev_b32_e32 v206, 3, v201
	v_lshl_or_b32 v207, v206, 11, v200
	v_add_u32_e32 v206, 0x10000, v207
	v_add_u32_e32 v205, 0x20000, v207
	v_add_u32_e32 v204, 0x30000, v207
	v_add_u32_e32 v203, 0x40000, v207
	v_add_u32_e32 v202, 0x50000, v207
	s_lshr_b32 s83, s64, 6
	s_and_b32 s84, s64, 63
	s_mov_b32 s79, 0
	s_mul_i32 s84, s84, 0x60000
	s_lshl_b32 s83, s83, 18
	s_waitcnt lgkmcnt(0)
	s_add_u32 s66, s66, s84
	s_addc_u32 s67, s67, 0
	s_add_u32 s68, s68, s83
	s_addc_u32 s69, s69, 0
	s_add_u32 s83, s79, 0
	s_and_b32 s83, s83, 15
	s_lshl_b32 s83, s83, 7
	s_add_u32 s70, s66, s83
	s_addc_u32 s71, s67, 0
	s_add_u32 s72, s68, s83
	s_addc_u32 s73, s69, 0
	s_add_u32 s81, s80, 0x0
	s_add_u32 s82, s80, 0xc000
	s_add_u32 m0, s81, 0x0
	s_nop 0
	global_load_lds_dwordx4 v207, s[70:71]
	s_add_u32 m0, s81, 0x1000
	s_nop 0
	global_load_lds_dwordx4 v206, s[70:71]
	s_add_u32 m0, s81, 0x2000
	s_nop 0
	global_load_lds_dwordx4 v205, s[70:71]
	s_add_u32 m0, s81, 0x3000
	s_nop 0
	global_load_lds_dwordx4 v204, s[70:71]
	s_add_u32 m0, s81, 0x4000
	s_nop 0
	global_load_lds_dwordx4 v203, s[70:71]
	s_add_u32 m0, s81, 0x5000
	s_nop 0
	global_load_lds_dwordx4 v202, s[70:71]
	s_add_u32 m0, s82, 0x0
	s_nop 0
	global_load_lds_dwordx4 v207, s[72:73]
	s_add_u32 m0, s82, 0x1000
	s_nop 0
	global_load_lds_dwordx4 v206, s[72:73]
	s_add_u32 m0, s82, 0x2000
	s_nop 0
	global_load_lds_dwordx4 v205, s[72:73]
	s_add_u32 m0, s82, 0x3000
	s_nop 0
	global_load_lds_dwordx4 v204, s[72:73]
	s_add_u32 s83, s79, 1
	s_and_b32 s83, s83, 15
	s_lshl_b32 s83, s83, 7
	s_add_u32 s70, s66, s83
	s_addc_u32 s71, s67, 0
	s_add_u32 s72, s68, s83
	s_addc_u32 s73, s69, 0
	s_add_u32 s81, s80, 0x6000
	s_add_u32 s82, s80, 0x10000
	s_add_u32 m0, s81, 0x0
	s_nop 0
	global_load_lds_dwordx4 v207, s[70:71]
	s_add_u32 m0, s81, 0x1000
	s_nop 0
	global_load_lds_dwordx4 v206, s[70:71]
	s_add_u32 m0, s81, 0x2000
	s_nop 0
	global_load_lds_dwordx4 v205, s[70:71]
	s_add_u32 m0, s81, 0x3000
	s_nop 0
	global_load_lds_dwordx4 v204, s[70:71]
	s_add_u32 m0, s81, 0x4000
	s_nop 0
	global_load_lds_dwordx4 v203, s[70:71]
	v_mov_b32_e32 v2, 0
	v_mov_b32_e32 v3, 0
	v_mov_b32_e32 v4, 0
	v_mov_b32_e32 v5, 0
	v_mov_b32_e32 v6, 0
	v_mov_b32_e32 v7, 0
	v_mov_b32_e32 v8, 0
	v_mov_b32_e32 v9, 0
	v_mov_b32_e32 v10, 0
	v_mov_b32_e32 v11, 0
	v_mov_b32_e32 v12, 0
	v_mov_b32_e32 v13, 0
	v_mov_b32_e32 v14, 0
	v_mov_b32_e32 v15, 0
	v_mov_b32_e32 v16, 0
	v_mov_b32_e32 v17, 0
	v_mov_b32_e32 v18, 0
	v_mov_b32_e32 v19, 0
	v_mov_b32_e32 v20, 0
	v_mov_b32_e32 v21, 0
	v_mov_b32_e32 v22, 0
	v_mov_b32_e32 v23, 0
	v_mov_b32_e32 v24, 0
	v_mov_b32_e32 v25, 0
	v_mov_b32_e32 v26, 0
	v_mov_b32_e32 v27, 0
	v_mov_b32_e32 v28, 0
	v_mov_b32_e32 v29, 0
	v_mov_b32_e32 v30, 0
	v_mov_b32_e32 v31, 0
	v_mov_b32_e32 v32, 0
	v_mov_b32_e32 v33, 0
	v_mov_b32_e32 v34, 0
	v_mov_b32_e32 v35, 0
	v_mov_b32_e32 v36, 0
	v_mov_b32_e32 v37, 0
	v_mov_b32_e32 v38, 0
	v_mov_b32_e32 v39, 0
	v_mov_b32_e32 v40, 0
	v_mov_b32_e32 v41, 0
	v_mov_b32_e32 v42, 0
	v_mov_b32_e32 v43, 0
	v_mov_b32_e32 v44, 0
	v_mov_b32_e32 v45, 0
	v_mov_b32_e32 v46, 0
	v_mov_b32_e32 v47, 0
	v_mov_b32_e32 v48, 0
	v_mov_b32_e32 v49, 0
	v_mov_b32_e32 v50, 0
	v_mov_b32_e32 v51, 0
	v_mov_b32_e32 v52, 0
	v_mov_b32_e32 v53, 0
	v_mov_b32_e32 v54, 0
	v_mov_b32_e32 v55, 0
	v_mov_b32_e32 v56, 0
	v_mov_b32_e32 v57, 0
	v_mov_b32_e32 v58, 0
	v_mov_b32_e32 v59, 0
	v_mov_b32_e32 v60, 0
	v_mov_b32_e32 v61, 0
	v_mov_b32_e32 v62, 0
	v_mov_b32_e32 v63, 0
	v_mov_b32_e32 v64, 0
	v_mov_b32_e32 v65, 0
	v_mov_b32_e32 v66, 0
	v_mov_b32_e32 v67, 0
	v_mov_b32_e32 v68, 0
	v_mov_b32_e32 v69, 0
	v_mov_b32_e32 v70, 0
	v_mov_b32_e32 v71, 0
	v_mov_b32_e32 v72, 0
	v_mov_b32_e32 v73, 0
	v_mov_b32_e32 v74, 0
	v_mov_b32_e32 v75, 0
	v_mov_b32_e32 v76, 0
	v_mov_b32_e32 v77, 0
	v_mov_b32_e32 v78, 0
	v_mov_b32_e32 v79, 0
	v_mov_b32_e32 v80, 0
	v_mov_b32_e32 v81, 0
	v_mov_b32_e32 v82, 0
	v_mov_b32_e32 v83, 0
	v_mov_b32_e32 v84, 0
	v_mov_b32_e32 v85, 0
	v_mov_b32_e32 v86, 0
	v_mov_b32_e32 v87, 0
	v_mov_b32_e32 v88, 0
	v_mov_b32_e32 v89, 0
	v_mov_b32_e32 v90, 0
	v_mov_b32_e32 v91, 0
	v_mov_b32_e32 v92, 0
	v_mov_b32_e32 v93, 0
	v_mov_b32_e32 v94, 0
	v_mov_b32_e32 v95, 0
	v_mov_b32_e32 v96, 0
	v_mov_b32_e32 v97, 0
	s_waitcnt vmcnt(5)
	s_barrier
	ds_read_b128 v[240:243], v211 offset:0
	ds_read_b128 v[252:255], v215 offset:0
	ds_read_b128 v[236:239], v211 offset:4096
	ds_read_b128 v[248:251], v215 offset:4096
	ds_read_b128 v[244:247], v215 offset:8192
	s_mov_b32 s78, 0
.Lgm_ph13_loop:
	s_waitcnt lgkmcnt(1)
	v_mfma_f32_32x32x16_bf16 v[82:97], v[240:243], v[252:255], v[82:97]
	ds_read_b128 v[220:223], v210 offset:0
	s_add_u32 m0, s81, 0x5000
	s_nop 0
	global_load_lds_dwordx4 v202, s[70:71]
	v_mfma_f32_32x32x16_bf16 v[66:81], v[236:239], v[252:255], v[66:81]
	ds_read_b128 v[232:235], v214 offset:0
	s_add_u32 m0, s82, 0x0
	s_nop 0
	global_load_lds_dwordx4 v207, s[72:73]
	v_mfma_f32_32x32x16_bf16 v[50:65], v[240:243], v[248:251], v[50:65]
	ds_read_b128 v[216:219], v210 offset:4096
	s_add_u32 m0, s82, 0x1000
	s_nop 0
	global_load_lds_dwordx4 v206, s[72:73]
	v_mfma_f32_32x32x16_bf16 v[34:49], v[236:239], v[248:251], v[34:49]
	ds_read_b128 v[228:231], v214 offset:4096
	s_add_u32 m0, s82, 0x2000
	s_nop 0
	global_load_lds_dwordx4 v205, s[72:73]
	s_waitcnt lgkmcnt(4)
	v_mfma_f32_32x32x16_bf16 v[18:33], v[240:243], v[244:247], v[18:33]
	ds_read_b128 v[224:227], v214 offset:8192
	v_mfma_f32_32x32x16_bf16 v[2:17], v[236:239], v[244:247], v[2:17]
	s_add_u32 m0, s82, 0x3000
	s_nop 0
	global_load_lds_dwordx4 v204, s[72:73]
	s_waitcnt lgkmcnt(1)
	v_mfma_f32_32x32x16_bf16 v[82:97], v[220:223], v[232:235], v[82:97]
	ds_read_b128 v[240:243], v209 offset:0
	v_mfma_f32_32x32x16_bf16 v[66:81], v[216:219], v[232:235], v[66:81]
	ds_read_b128 v[252:255], v213 offset:0
	v_mfma_f32_32x32x16_bf16 v[50:65], v[220:223], v[228:231], v[50:65]
	ds_read_b128 v[236:239], v209 offset:4096
	v_mfma_f32_32x32x16_bf16 v[34:49], v[216:219], v[228:231], v[34:49]
	ds_read_b128 v[248:251], v213 offset:4096
	s_waitcnt lgkmcnt(4)
	v_mfma_f32_32x32x16_bf16 v[18:33], v[220:223], v[224:227], v[18:33]
	ds_read_b128 v[244:247], v213 offset:8192
	v_mfma_f32_32x32x16_bf16 v[2:17], v[216:219], v[224:227], v[2:17]
	s_waitcnt lgkmcnt(1)
	v_mfma_f32_32x32x16_bf16 v[82:97], v[240:243], v[252:255], v[82:97]
	ds_read_b128 v[220:223], v208 offset:0
	s_add_u32 s83, s79, s78
	s_add_u32 s83, s83, 2
	s_and_b32 s83, s83, 15
	v_mfma_f32_32x32x16_bf16 v[66:81], v[236:239], v[252:255], v[66:81]
	ds_read_b128 v[232:235], v212 offset:0
	s_lshl_b32 s83, s83, 7
	s_add_u32 s70, s66, s83
	v_mfma_f32_32x32x16_bf16 v[50:65], v[240:243], v[248:251], v[50:65]
	ds_read_b128 v[216:219], v208 offset:4096
	s_addc_u32 s71, s67, 0
	s_add_u32 s72, s68, s83
	v_mfma_f32_32x32x16_bf16 v[34:49], v[236:239], v[248:251], v[34:49]
	ds_read_b128 v[228:231], v212 offset:4096
	s_addc_u32 s73, s69, 0
	s_add_u32 s81, s80, 0x0
	s_add_u32 s82, s80, 0xc000
	s_waitcnt lgkmcnt(4)
	v_mfma_f32_32x32x16_bf16 v[18:33], v[240:243], v[244:247], v[18:33]
	ds_read_b128 v[224:227], v212 offset:8192
	v_mfma_f32_32x32x16_bf16 v[2:17], v[236:239], v[244:247], v[2:17]
	s_waitcnt vmcnt(0) lgkmcnt(0)
	s_barrier
	v_mfma_f32_32x32x16_bf16 v[82:97], v[220:223], v[232:235], v[82:97]
	s_add_u32 m0, s81, 0x0
	ds_read_b128 v[240:243], v211 offset:16384
	global_load_lds_dwordx4 v207, s[70:71]
	v_mfma_f32_32x32x16_bf16 v[66:81], v[216:219], v[232:235], v[66:81]
	s_add_u32 m0, s81, 0x1000
	ds_read_b128 v[252:255], v215 offset:24576
	global_load_lds_dwordx4 v206, s[70:71]
	v_mfma_f32_32x32x16_bf16 v[50:65], v[220:223], v[228:231], v[50:65]
	s_add_u32 m0, s81, 0x2000
	ds_read_b128 v[236:239], v211 offset:20480
	global_load_lds_dwordx4 v205, s[70:71]
	v_mfma_f32_32x32x16_bf16 v[34:49], v[216:219], v[228:231], v[34:49]
	s_add_u32 m0, s81, 0x3000
	ds_read_b128 v[248:251], v215 offset:28672
	global_load_lds_dwordx4 v204, s[70:71]
	v_mfma_f32_32x32x16_bf16 v[18:33], v[220:223], v[224:227], v[18:33]
	s_add_u32 m0, s81, 0x4000
	ds_read_b128 v[244:247], v215 offset:32768
	global_load_lds_dwordx4 v203, s[70:71]
	v_mfma_f32_32x32x16_bf16 v[2:17], v[216:219], v[224:227], v[2:17]
	s_waitcnt lgkmcnt(1)
	v_mfma_f32_32x32x16_bf16 v[82:97], v[240:243], v[252:255], v[82:97]
	ds_read_b128 v[220:223], v210 offset:16384
	s_add_u32 m0, s81, 0x5000
	s_nop 0
	global_load_lds_dwordx4 v202, s[70:71]
	v_mfma_f32_32x32x16_bf16 v[66:81], v[236:239], v[252:255], v[66:81]
	ds_read_b128 v[232:235], v214 offset:24576
	s_add_u32 m0, s82, 0x0
	s_nop 0
	global_load_lds_dwordx4 v207, s[72:73]
	v_mfma_f32_32x32x16_bf16 v[50:65], v[240:243], v[248:251], v[50:65]
	ds_read_b128 v[216:219], v210 offset:20480
	s_add_u32 m0, s82, 0x1000
	s_nop 0
	global_load_lds_dwordx4 v206, s[72:73]
	v_mfma_f32_32x32x16_bf16 v[34:49], v[236:239], v[248:251], v[34:49]
	ds_read_b128 v[228:231], v214 offset:28672
	s_add_u32 m0, s82, 0x2000
	s_nop 0
	global_load_lds_dwordx4 v205, s[72:73]
	s_waitcnt lgkmcnt(4)
	v_mfma_f32_32x32x16_bf16 v[18:33], v[240:243], v[244:247], v[18:33]
	ds_read_b128 v[224:227], v214 offset:32768
	v_mfma_f32_32x32x16_bf16 v[2:17], v[236:239], v[244:247], v[2:17]
	s_add_u32 m0, s82, 0x3000
	s_nop 0
	global_load_lds_dwordx4 v204, s[72:73]
	s_waitcnt lgkmcnt(1)
	v_mfma_f32_32x32x16_bf16 v[82:97], v[220:223], v[232:235], v[82:97]
	ds_read_b128 v[240:243], v209 offset:16384
	v_mfma_f32_32x32x16_bf16 v[66:81], v[216:219], v[232:235], v[66:81]
	ds_read_b128 v[252:255], v213 offset:24576
	v_mfma_f32_32x32x16_bf16 v[50:65], v[220:223], v[228:231], v[50:65]
	ds_read_b128 v[236:239], v209 offset:20480
	v_mfma_f32_32x32x16_bf16 v[34:49], v[216:219], v[228:231], v[34:49]
	ds_read_b128 v[248:251], v213 offset:28672
	s_waitcnt lgkmcnt(4)
	v_mfma_f32_32x32x16_bf16 v[18:33], v[220:223], v[224:227], v[18:33]
	ds_read_b128 v[244:247], v213 offset:32768
	v_mfma_f32_32x32x16_bf16 v[2:17], v[216:219], v[224:227], v[2:17]
	s_waitcnt lgkmcnt(1)
	v_mfma_f32_32x32x16_bf16 v[82:97], v[240:243], v[252:255], v[82:97]
	ds_read_b128 v[220:223], v208 offset:16384
	s_add_u32 s83, s79, s78
	s_add_u32 s83, s83, 3
	s_and_b32 s83, s83, 15
	v_mfma_f32_32x32x16_bf16 v[66:81], v[236:239], v[252:255], v[66:81]
	ds_read_b128 v[232:235], v212 offset:24576
	s_lshl_b32 s83, s83, 7
	s_add_u32 s70, s66, s83
	v_mfma_f32_32x32x16_bf16 v[50:65], v[240:243], v[248:251], v[50:65]
	ds_read_b128 v[216:219], v208 offset:20480
	s_addc_u32 s71, s67, 0
	s_add_u32 s72, s68, s83
	v_mfma_f32_32x32x16_bf16 v[34:49], v[236:239], v[248:251], v[34:49]
	ds_read_b128 v[228:231], v212 offset:28672
	s_addc_u32 s73, s69, 0
	s_add_u32 s81, s80, 0x6000
	s_add_u32 s82, s80, 0x10000
	s_waitcnt lgkmcnt(4)
	v_mfma_f32_32x32x16_bf16 v[18:33], v[240:243], v[244:247], v[18:33]
	ds_read_b128 v[224:227], v212 offset:32768
	v_mfma_f32_32x32x16_bf16 v[2:17], v[236:239], v[244:247], v[2:17]
	s_waitcnt vmcnt(0) lgkmcnt(0)
	s_barrier
	v_mfma_f32_32x32x16_bf16 v[82:97], v[220:223], v[232:235], v[82:97]
	s_add_u32 m0, s81, 0x0
	ds_read_b128 v[240:243], v211 offset:0
	global_load_lds_dwordx4 v207, s[70:71]
	v_mfma_f32_32x32x16_bf16 v[66:81], v[216:219], v[232:235], v[66:81]
	s_add_u32 m0, s81, 0x1000
	ds_read_b128 v[252:255], v215 offset:0
	global_load_lds_dwordx4 v206, s[70:71]
	v_mfma_f32_32x32x16_bf16 v[50:65], v[220:223], v[228:231], v[50:65]
	s_add_u32 m0, s81, 0x2000
	ds_read_b128 v[236:239], v211 offset:4096
	global_load_lds_dwordx4 v205, s[70:71]
	v_mfma_f32_32x32x16_bf16 v[34:49], v[216:219], v[228:231], v[34:49]
	s_add_u32 m0, s81, 0x3000
	ds_read_b128 v[248:251], v215 offset:4096
	global_load_lds_dwordx4 v204, s[70:71]
	v_mfma_f32_32x32x16_bf16 v[18:33], v[220:223], v[224:227], v[18:33]
	s_add_u32 m0, s81, 0x4000
	ds_read_b128 v[244:247], v215 offset:8192
	global_load_lds_dwordx4 v203, s[70:71]
	v_mfma_f32_32x32x16_bf16 v[2:17], v[216:219], v[224:227], v[2:17]
	s_add_u32 s78, s78, 2
	s_cmp_lt_u32 s78, 14
	s_cbranch_scc1 .Lgm_ph13_loop
	s_waitcnt lgkmcnt(1)
	v_mfma_f32_32x32x16_bf16 v[82:97], v[240:243], v[252:255], v[82:97]
	ds_read_b128 v[220:223], v210 offset:0
	s_add_u32 m0, s81, 0x5000
	s_nop 0
	global_load_lds_dwordx4 v202, s[70:71]
	v_mfma_f32_32x32x16_bf16 v[66:81], v[236:239], v[252:255], v[66:81]
	ds_read_b128 v[232:235], v214 offset:0
	s_add_u32 m0, s82, 0x0
	s_nop 0
	global_load_lds_dwordx4 v207, s[72:73]
	v_mfma_f32_32x32x16_bf16 v[50:65], v[240:243], v[248:251], v[50:65]
	ds_read_b128 v[216:219], v210 offset:4096
	s_add_u32 m0, s82, 0x1000
	s_nop 0
	global_load_lds_dwordx4 v206, s[72:73]
	v_mfma_f32_32x32x16_bf16 v[34:49], v[236:239], v[248:251], v[34:49]
	ds_read_b128 v[228:231], v214 offset:4096
	s_add_u32 m0, s82, 0x2000
	s_nop 0
	global_load_lds_dwordx4 v205, s[72:73]
	s_waitcnt lgkmcnt(4)
	v_mfma_f32_32x32x16_bf16 v[18:33], v[240:243], v[244:247], v[18:33]
	ds_read_b128 v[224:227], v214 offset:8192
	v_mfma_f32_32x32x16_bf16 v[2:17], v[236:239], v[244:247], v[2:17]
	s_add_u32 m0, s82, 0x3000
	s_nop 0
	global_load_lds_dwordx4 v204, s[72:73]
	s_waitcnt lgkmcnt(1)
	v_mfma_f32_32x32x16_bf16 v[82:97], v[220:223], v[232:235], v[82:97]
	ds_read_b128 v[240:243], v209 offset:0
	v_mfma_f32_32x32x16_bf16 v[66:81], v[216:219], v[232:235], v[66:81]
	ds_read_b128 v[252:255], v213 offset:0
	v_mfma_f32_32x32x16_bf16 v[50:65], v[220:223], v[228:231], v[50:65]
	ds_read_b128 v[236:239], v209 offset:4096
	v_mfma_f32_32x32x16_bf16 v[34:49], v[216:219], v[228:231], v[34:49]
	ds_read_b128 v[248:251], v213 offset:4096
	s_waitcnt lgkmcnt(4)
	v_mfma_f32_32x32x16_bf16 v[18:33], v[220:223], v[224:227], v[18:33]
	ds_read_b128 v[244:247], v213 offset:8192
	v_mfma_f32_32x32x16_bf16 v[2:17], v[216:219], v[224:227], v[2:17]
	s_waitcnt lgkmcnt(1)
	v_mfma_f32_32x32x16_bf16 v[82:97], v[240:243], v[252:255], v[82:97]
	ds_read_b128 v[220:223], v208 offset:0
	v_mfma_f32_32x32x16_bf16 v[66:81], v[236:239], v[252:255], v[66:81]
	ds_read_b128 v[232:235], v212 offset:0
	v_mfma_f32_32x32x16_bf16 v[50:65], v[240:243], v[248:251], v[50:65]
	ds_read_b128 v[216:219], v208 offset:4096
	v_mfma_f32_32x32x16_bf16 v[34:49], v[236:239], v[248:251], v[34:49]
	ds_read_b128 v[228:231], v212 offset:4096
	s_waitcnt lgkmcnt(4)
	v_mfma_f32_32x32x16_bf16 v[18:33], v[240:243], v[244:247], v[18:33]
	ds_read_b128 v[224:227], v212 offset:8192
	v_mfma_f32_32x32x16_bf16 v[2:17], v[236:239], v[244:247], v[2:17]
	s_waitcnt vmcnt(0) lgkmcnt(0)
	s_barrier
	v_mfma_f32_32x32x16_bf16 v[82:97], v[220:223], v[232:235], v[82:97]
	ds_read_b128 v[240:243], v211 offset:16384
	v_mfma_f32_32x32x16_bf16 v[66:81], v[216:219], v[232:235], v[66:81]
	ds_read_b128 v[252:255], v215 offset:24576
	v_mfma_f32_32x32x16_bf16 v[50:65], v[220:223], v[228:231], v[50:65]
	ds_read_b128 v[236:239], v211 offset:20480
	v_mfma_f32_32x32x16_bf16 v[34:49], v[216:219], v[228:231], v[34:49]
	ds_read_b128 v[248:251], v215 offset:28672
	v_mfma_f32_32x32x16_bf16 v[18:33], v[220:223], v[224:227], v[18:33]
	ds_read_b128 v[244:247], v215 offset:32768
	v_mfma_f32_32x32x16_bf16 v[2:17], v[216:219], v[224:227], v[2:17]
	s_waitcnt lgkmcnt(1)
	v_mfma_f32_32x32x16_bf16 v[82:97], v[240:243], v[252:255], v[82:97]
	ds_read_b128 v[220:223], v210 offset:16384
	v_mfma_f32_32x32x16_bf16 v[66:81], v[236:239], v[252:255], v[66:81]
	ds_read_b128 v[232:235], v214 offset:24576
	v_mfma_f32_32x32x16_bf16 v[50:65], v[240:243], v[248:251], v[50:65]
	ds_read_b128 v[216:219], v210 offset:20480
	v_mfma_f32_32x32x16_bf16 v[34:49], v[236:239], v[248:251], v[34:49]
	ds_read_b128 v[228:231], v214 offset:28672
	s_waitcnt lgkmcnt(4)
	v_mfma_f32_32x32x16_bf16 v[18:33], v[240:243], v[244:247], v[18:33]
	ds_read_b128 v[224:227], v214 offset:32768
	v_mfma_f32_32x32x16_bf16 v[2:17], v[236:239], v[244:247], v[2:17]
	s_waitcnt lgkmcnt(1)
	v_mfma_f32_32x32x16_bf16 v[82:97], v[220:223], v[232:235], v[82:97]
	ds_read_b128 v[240:243], v209 offset:16384
	v_mfma_f32_32x32x16_bf16 v[66:81], v[216:219], v[232:235], v[66:81]
	ds_read_b128 v[252:255], v213 offset:24576
	v_mfma_f32_32x32x16_bf16 v[50:65], v[220:223], v[228:231], v[50:65]
	ds_read_b128 v[236:239], v209 offset:20480
	v_mfma_f32_32x32x16_bf16 v[34:49], v[216:219], v[228:231], v[34:49]
	ds_read_b128 v[248:251], v213 offset:28672
	s_waitcnt lgkmcnt(4)
	v_mfma_f32_32x32x16_bf16 v[18:33], v[220:223], v[224:227], v[18:33]
	ds_read_b128 v[244:247], v213 offset:32768
	v_mfma_f32_32x32x16_bf16 v[2:17], v[216:219], v[224:227], v[2:17]
	s_waitcnt lgkmcnt(1)
	v_mfma_f32_32x32x16_bf16 v[82:97], v[240:243], v[252:255], v[82:97]
	ds_read_b128 v[220:223], v208 offset:16384
	v_mfma_f32_32x32x16_bf16 v[66:81], v[236:239], v[252:255], v[66:81]
	ds_read_b128 v[232:235], v212 offset:24576
	v_mfma_f32_32x32x16_bf16 v[50:65], v[240:243], v[248:251], v[50:65]
	ds_read_b128 v[216:219], v208 offset:20480
	v_mfma_f32_32x32x16_bf16 v[34:49], v[236:239], v[248:251], v[34:49]
	ds_read_b128 v[228:231], v212 offset:28672
	s_waitcnt lgkmcnt(4)
	v_mfma_f32_32x32x16_bf16 v[18:33], v[240:243], v[244:247], v[18:33]
	ds_read_b128 v[224:227], v212 offset:32768
	v_mfma_f32_32x32x16_bf16 v[2:17], v[236:239], v[244:247], v[2:17]
	s_waitcnt vmcnt(0) lgkmcnt(0)
	s_barrier
	v_mfma_f32_32x32x16_bf16 v[82:97], v[220:223], v[232:235], v[82:97]
	v_mfma_f32_32x32x16_bf16 v[66:81], v[216:219], v[232:235], v[66:81]
	v_mfma_f32_32x32x16_bf16 v[50:65], v[220:223], v[228:231], v[50:65]
	v_mfma_f32_32x32x16_bf16 v[34:49], v[216:219], v[228:231], v[34:49]
	v_mfma_f32_32x32x16_bf16 v[18:33], v[220:223], v[224:227], v[18:33]
	v_mfma_f32_32x32x16_bf16 v[2:17], v[216:219], v[224:227], v[2:17]
	s_nop 7
	s_nop 7
	s_and_b32 s5, s5, 0x1fffff8
	s_nop 4
	s_cmp_eq_u32 s5, 16
	s_nop 4
	s_cselect_b64 s[50:51], -1, 0
	s_nop 4
	s_cmpk_gt_u32 s4, 0x7ff
	s_nop 4
	s_cselect_b64 s[48:49], -1, 0
	s_nop 4
	s_cmpk_gt_u32 s4, 0xbff
	s_nop 4
	s_cselect_b64 s[46:47], -1, 0
	s_nop 4
	s_mov_b64 s[52:53], -1
	s_nop 4
	s_and_b64 vcc, exec, s[50:51]
	s_nop 4
	v_add_u32_e32 v109, s6, v119
	s_nop 4
	v_or_b32_e32 v100, s4, v127
	s_waitcnt lgkmcnt(0)
	s_nop 11
	ds_write_b128 v140, v[82:85]
	ds_write_b128 v140, v[86:89] offset:32
	ds_write_b128 v140, v[90:93] offset:64
	ds_write_b128 v140, v[94:97] offset:96
	s_nop 11
	ds_write_b128 v140, v[66:69] offset:128
	ds_write_b128 v140, v[70:73] offset:160
	ds_write_b128 v140, v[74:77] offset:192
	ds_write_b128 v140, v[78:81] offset:224
	s_waitcnt lgkmcnt(0)
	v_add_u32_e32 v112, v128, v100
	v_or_b32_e32 v100, v100, v131
	v_cmp_lt_i32_e64 s[6:7], s3, v100
	s_cbranch_vccz .LBB0_1278
	v_mov_b32_e32 v80, 0x880
	v_cmp_gt_i32_e64 s[52:53], s57, v109
	v_mov_b32_e32 v81, 0x990
	v_mov_b32_e32 v79, 0xaa0
	v_mov_b32_e32 v78, 0xbb0
	ds_read2_b32 v[70:71], v129 offset1:68
	ds_read2_b32 v[72:73], v129 offset0:136 offset1:204
	v_cndmask_b32_e64 v82, v141, v80, s[52:53]
	v_cndmask_b32_e64 v83, v142, v81, s[52:53]
	v_cndmask_b32_e64 v84, v143, v79, s[52:53]
	v_cndmask_b32_e64 v85, v144, v78, s[52:53]
	v_add_u32_e32 v66, 0xfffff000, v109
	v_ashrrev_i32_e32 v68, 8, v109
	v_add_u32_e32 v82, v129, v82
	v_add_u32_e32 v83, v129, v83
	v_add_u32_e32 v84, v129, v84
	v_add_u32_e32 v85, v129, v85
	v_lshrrev_b32_e32 v66, 11, v66
	v_and_b32_e32 v67, 0x7e0, v109
	v_ashrrev_i32_e32 v69, 31, v68
	ds_read_b32 v82, v82
	ds_read_b32 v83, v83
	ds_read_b32 v84, v84
	ds_read_b32 v85, v85
	v_add_u32_e32 v76, 0x100, v67
	v_mad_u64_u32 v[66:67], s[4:5], v66, s59, v[110:111]
	v_lshlrev_b64 v[68:69], 18, v[68:69]
	v_and_b32_e32 v77, 0xe0, v109
	v_cndmask_b32_e64 v75, v67, v69, s[52:53]
	v_cndmask_b32_e64 v74, v66, v68, s[52:53]
	v_cndmask_b32_e64 v86, v145, v147, s[52:53]
	v_cndmask_b32_e64 v87, v76, v77, s[52:53]
	s_waitcnt lgkmcnt(0)
	v_cvt_pk_bf16_f32 v70, v70, v71
	v_cvt_pk_bf16_f32 v71, v72, v73
	v_cvt_pk_bf16_f32 v72, v82, v83
	v_lshl_add_u64 v[74:75], v[74:75], 1, s[24:25]
	v_mad_u64_u32 v[82:83], s[4:5], v86, v112, 0
	v_lshl_add_u64 v[74:75], v[82:83], 1, v[74:75]
	v_lshlrev_b32_e32 v82, 1, v87
	v_mov_b32_e32 v83, v101
	v_cvt_pk_bf16_f32 v73, v84, v85
	v_lshl_add_u64 v[74:75], v[74:75], 0, v[82:83]
	global_store_dwordx4 v[74:75], v[70:73], off
	v_mov_b32_e32 v84, 0x1540
	v_mov_b32_e32 v83, 0x1650
	v_mov_b64_e32 v[70:71], 0x900
	v_mov_b64_e32 v[72:73], 0x900
	v_mov_b32_e32 v82, 0x1760
	v_mov_b32_e32 v71, 0x1870
	v_mov_b64_e32 v[74:75], v[66:67]
	v_mov_b32_e32 v73, v76
	s_and_saveexec_b64 s[4:5], s[52:53]
	s_cbranch_execz .LBB0_1275
	v_mov_b64_e32 v[72:73], 0x100
	v_mov_b32_e32 v78, 0x770
	v_mov_b32_e32 v79, 0x660
	v_mov_b32_e32 v81, 0x550
	v_mov_b32_e32 v80, 0x440
	v_mov_b32_e32 v84, 0x1980
	v_mov_b32_e32 v83, 0x1a90
	v_mov_b32_e32 v82, 0x1ba0
	v_mov_b32_e32 v71, 0x1cb0
	v_mov_b64_e32 v[74:75], v[68:69]
	v_mov_b32_e32 v73, v77

.LBB0_1859:
	s_ashr_i32 s10, s28, 31
	s_lshr_b32 s10, s10, 26
	s_add_i32 s10, s28, s10
	s_ashr_i32 s31, s10, 6
	s_and_b32 s10, s10, 0x3ffffc0
	s_sub_i32 s29, s28, s10
	s_mulk_i32 s29, 0xc0
	v_add_u32_e32 v2, s29, v108
	s_lshr_b32 s10, s29, 6
	s_lshl_b32 s30, s31, 7
	v_ashrrev_i32_e32 v3, 31, v2
	s_add_i32 s10, s10, s31
	v_lshlrev_b64 v[2:3], 11, v[2:3]
	v_or_b32_e32 v4, s30, v108
	s_lshl_b32 s31, s10, 6
	s_lshl_b32 s10, s10, 7
	v_ashrrev_i32_e32 v5, 31, v4
	v_lshl_add_u64 v[104:105], v[100:101], 0, v[2:3]
	s_and_b32 s10, s10, 0x780
	v_readfirstlane_b32 s34, v109
	v_lshlrev_b64 v[4:5], 11, v[4:5]
	v_lshl_add_u64 v[2:3], v[104:105], 0, s[10:11]
	s_mov_b32 m0, s34
	v_readfirstlane_b32 s34, v128
	v_lshl_add_u64 v[106:107], v[102:103], 0, v[4:5]
	s_waitcnt vmcnt(0)
	s_barrier
	s_load_dwordx2 s[66:67], s[0:1], 0x178
	s_load_dwordx2 s[68:69], s[0:1], 0x100
	v_and_b32_e32 v201, 0x3ff, v0
	v_readfirstlane_b32 s80, v0
	v_and_b32_e32 v200, 31, v201
	v_bfe_u32 v214, v201, 1, 3
	v_bfe_u32 v213, v201, 5, 1
	v_xor_b32_e32 v214, v214, v213
	v_lshlrev_b32_e32 v214, 4, v214
	s_and_b32 s80, s80, 0x3ff
	s_lshr_b32 s83, s80, 6
	s_lshl_b32 s80, s80, 4
	s_lshr_b32 s84, s83, 1
	s_and_b32 s83, s83, 1
	s_mul_i32 s84, s84, 0x3000
	s_lshl_b32 s83, s83, 13
	s_add_u32 s83, s83, 0xc000
	v_lshlrev_b32_e32 v200, 7, v200
	v_or_b32_e32 v200, v200, v214
	v_add_u32_e32 v215, s84, v200
	v_add_u32_e32 v211, s83, v200
	v_xor_b32_e32 v214, 0x20, v215
	v_xor_b32_e32 v210, 0x20, v211
	v_xor_b32_e32 v213, 0x40, v215
	v_xor_b32_e32 v209, 0x40, v211
	v_xor_b32_e32 v212, 0x60, v215
	v_xor_b32_e32 v208, 0x60, v211
	v_bfe_u32 v200, v201, 4, 3
	v_and_b32_e32 v206, 7, v201
	v_xor_b32_e32 v200, v200, v206
	v_lshlrev_b32_e32 v200, 4, v200
	v_lshrrev_b32_e32 v206, 3, v201
	v_lshl_or_b32 v207, v206, 11, v200
	v_add_u32_e32 v206, 0x10000, v207
	v_add_u32_e32 v205, 0x20000, v207
	v_add_u32_e32 v204, 0x30000, v207
	v_add_u32_e32 v203, 0x40000, v207
	v_add_u32_e32 v202, 0x50000, v207
	s_lshr_b32 s83, s28, 6
	s_and_b32 s84, s28, 63
	s_mov_b32 s79, 0
	s_mul_i32 s84, s84, 0x60000
	s_lshl_b32 s83, s83, 18
	s_waitcnt lgkmcnt(0)
	s_add_u32 s66, s66, s84
	s_addc_u32 s67, s67, 0
	s_add_u32 s68, s68, s83
	s_addc_u32 s69, s69, 0
	s_add_u32 s83, s79, 0
	s_and_b32 s83, s83, 15
	s_lshl_b32 s83, s83, 7
	s_add_u32 s70, s66, s83
	s_addc_u32 s71, s67, 0
	s_add_u32 s72, s68, s83
	s_addc_u32 s73, s69, 0
	s_add_u32 s81, s80, 0x0
	s_add_u32 s82, s80, 0xc000
	s_add_u32 m0, s81, 0x0
	s_nop 0
	global_load_lds_dwordx4 v207, s[70:71]
	s_add_u32 m0, s81, 0x1000
	s_nop 0
	global_load_lds_dwordx4 v206, s[70:71]
	s_add_u32 m0, s81, 0x2000
	s_nop 0
	global_load_lds_dwordx4 v205, s[70:71]
	s_add_u32 m0, s81, 0x3000
	s_nop 0
	global_load_lds_dwordx4 v204, s[70:71]
	s_add_u32 m0, s81, 0x4000
	s_nop 0
	global_load_lds_dwordx4 v203, s[70:71]
	s_add_u32 m0, s81, 0x5000
	s_nop 0
	global_load_lds_dwordx4 v202, s[70:71]
	s_add_u32 m0, s82, 0x0
	s_nop 0
	global_load_lds_dwordx4 v207, s[72:73]
	s_add_u32 m0, s82, 0x1000
	s_nop 0
	global_load_lds_dwordx4 v206, s[72:73]
	s_add_u32 m0, s82, 0x2000
	s_nop 0
	global_load_lds_dwordx4 v205, s[72:73]
	s_add_u32 m0, s82, 0x3000
	s_nop 0
	global_load_lds_dwordx4 v204, s[72:73]
	s_add_u32 s83, s79, 1
	s_and_b32 s83, s83, 15
	s_lshl_b32 s83, s83, 7
	s_add_u32 s70, s66, s83
	s_addc_u32 s71, s67, 0
	s_add_u32 s72, s68, s83
	s_addc_u32 s73, s69, 0
	s_add_u32 s81, s80, 0x6000
	s_add_u32 s82, s80, 0x10000
	s_add_u32 m0, s81, 0x0
	s_nop 0
	global_load_lds_dwordx4 v207, s[70:71]
	s_add_u32 m0, s81, 0x1000
	s_nop 0
	global_load_lds_dwordx4 v206, s[70:71]
	s_add_u32 m0, s81, 0x2000
	s_nop 0
	global_load_lds_dwordx4 v205, s[70:71]
	s_add_u32 m0, s81, 0x3000
	s_nop 0
	global_load_lds_dwordx4 v204, s[70:71]
	s_add_u32 m0, s81, 0x4000
	s_nop 0
	global_load_lds_dwordx4 v203, s[70:71]
	v_mov_b32_e32 v2, 0
	v_mov_b32_e32 v3, 0
	v_mov_b32_e32 v4, 0
	v_mov_b32_e32 v5, 0
	v_mov_b32_e32 v6, 0
	v_mov_b32_e32 v7, 0
	v_mov_b32_e32 v8, 0
	v_mov_b32_e32 v9, 0
	v_mov_b32_e32 v10, 0
	v_mov_b32_e32 v11, 0
	v_mov_b32_e32 v12, 0
	v_mov_b32_e32 v13, 0
	v_mov_b32_e32 v14, 0
	v_mov_b32_e32 v15, 0
	v_mov_b32_e32 v16, 0
	v_mov_b32_e32 v17, 0
	v_mov_b32_e32 v18, 0
	v_mov_b32_e32 v19, 0
	v_mov_b32_e32 v20, 0
	v_mov_b32_e32 v21, 0
	v_mov_b32_e32 v22, 0
	v_mov_b32_e32 v23, 0
	v_mov_b32_e32 v24, 0
	v_mov_b32_e32 v25, 0
	v_mov_b32_e32 v26, 0
	v_mov_b32_e32 v27, 0
	v_mov_b32_e32 v28, 0
	v_mov_b32_e32 v29, 0
	v_mov_b32_e32 v30, 0
	v_mov_b32_e32 v31, 0
	v_mov_b32_e32 v32, 0
	v_mov_b32_e32 v33, 0
	v_mov_b32_e32 v34, 0
	v_mov_b32_e32 v35, 0
	v_mov_b32_e32 v36, 0
	v_mov_b32_e32 v37, 0
	v_mov_b32_e32 v38, 0
	v_mov_b32_e32 v39, 0
	v_mov_b32_e32 v40, 0
	v_mov_b32_e32 v41, 0
	v_mov_b32_e32 v42, 0
	v_mov_b32_e32 v43, 0
	v_mov_b32_e32 v44, 0
	v_mov_b32_e32 v45, 0
	v_mov_b32_e32 v46, 0
	v_mov_b32_e32 v47, 0
	v_mov_b32_e32 v48, 0
	v_mov_b32_e32 v49, 0
	v_mov_b32_e32 v50, 0
	v_mov_b32_e32 v51, 0
	v_mov_b32_e32 v52, 0
	v_mov_b32_e32 v53, 0
	v_mov_b32_e32 v54, 0
	v_mov_b32_e32 v55, 0
	v_mov_b32_e32 v56, 0
	v_mov_b32_e32 v57, 0
	v_mov_b32_e32 v58, 0
	v_mov_b32_e32 v59, 0
	v_mov_b32_e32 v60, 0
	v_mov_b32_e32 v61, 0
	v_mov_b32_e32 v62, 0
	v_mov_b32_e32 v63, 0
	v_mov_b32_e32 v64, 0
	v_mov_b32_e32 v65, 0
	v_mov_b32_e32 v66, 0
	v_mov_b32_e32 v67, 0
	v_mov_b32_e32 v68, 0
	v_mov_b32_e32 v69, 0
	v_mov_b32_e32 v70, 0
	v_mov_b32_e32 v71, 0
	v_mov_b32_e32 v72, 0
	v_mov_b32_e32 v73, 0
	v_mov_b32_e32 v74, 0
	v_mov_b32_e32 v75, 0
	v_mov_b32_e32 v76, 0
	v_mov_b32_e32 v77, 0
	v_mov_b32_e32 v78, 0
	v_mov_b32_e32 v79, 0
	v_mov_b32_e32 v80, 0
	v_mov_b32_e32 v81, 0
	v_mov_b32_e32 v82, 0
	v_mov_b32_e32 v83, 0
	v_mov_b32_e32 v84, 0
	v_mov_b32_e32 v85, 0
	v_mov_b32_e32 v86, 0
	v_mov_b32_e32 v87, 0
	v_mov_b32_e32 v88, 0
	v_mov_b32_e32 v89, 0
	v_mov_b32_e32 v90, 0
	v_mov_b32_e32 v91, 0
	v_mov_b32_e32 v92, 0
	v_mov_b32_e32 v93, 0
	v_mov_b32_e32 v94, 0
	v_mov_b32_e32 v95, 0
	v_mov_b32_e32 v96, 0
	v_mov_b32_e32 v97, 0
	s_waitcnt vmcnt(5)
	s_barrier
	ds_read_b128 v[240:243], v211 offset:0
	ds_read_b128 v[252:255], v215 offset:0
	ds_read_b128 v[236:239], v211 offset:4096
	ds_read_b128 v[248:251], v215 offset:4096
	ds_read_b128 v[244:247], v215 offset:8192
	s_mov_b32 s78, 0

.LBB0_1992:
	s_ashr_i32 s4, s35, 31
	s_lshr_b32 s4, s4, 26
	s_add_i32 s4, s35, s4
	s_ashr_i32 s6, s4, 6
	s_and_b32 s4, s4, 0x3ffffc0
	s_sub_i32 s4, s35, s4
	s_mulk_i32 s4, 0xc0
	v_add_u32_e32 v2, s4, v112
	s_lshr_b32 s7, s4, 6
	s_lshl_b32 s5, s6, 7
	v_ashrrev_i32_e32 v3, 31, v2
	s_add_i32 s7, s7, s6
	v_lshlrev_b64 v[2:3], 11, v[2:3]
	v_or_b32_e32 v4, s5, v112
	s_lshl_b32 s6, s7, 6
	s_lshl_b32 s7, s7, 7
	v_ashrrev_i32_e32 v5, 31, v4
	v_lshl_add_u64 v[104:105], v[100:101], 0, v[2:3]
	s_and_b32 s14, s7, 0x780
	v_readfirstlane_b32 s7, v113
	v_lshlrev_b64 v[4:5], 11, v[4:5]
	v_lshl_add_u64 v[2:3], v[104:105], 0, s[14:15]
	s_mov_b32 m0, s7
	v_readfirstlane_b32 s7, v125
	v_lshl_add_u64 v[106:107], v[102:103], 0, v[4:5]
	s_waitcnt vmcnt(0)
	s_barrier
	s_load_dwordx2 s[66:67], s[0:1], 0x90
	s_load_dwordx2 s[68:69], s[0:1], 0xc0
	v_and_b32_e32 v201, 0x3ff, v0
	v_readfirstlane_b32 s80, v0
	v_and_b32_e32 v200, 31, v201
	v_bfe_u32 v214, v201, 1, 3
	v_bfe_u32 v213, v201, 5, 1
	v_xor_b32_e32 v214, v214, v213
	v_lshlrev_b32_e32 v214, 4, v214
	s_and_b32 s80, s80, 0x3ff
	s_lshr_b32 s83, s80, 6
	s_lshl_b32 s80, s80, 4
	s_lshr_b32 s84, s83, 1
	s_and_b32 s83, s83, 1
	s_mul_i32 s84, s84, 0x3000
	s_lshl_b32 s83, s83, 13
	s_add_u32 s83, s83, 0xc000
	v_lshlrev_b32_e32 v200, 7, v200
	v_or_b32_e32 v200, v200, v214
	v_add_u32_e32 v215, s84, v200
	v_add_u32_e32 v211, s83, v200
	v_xor_b32_e32 v214, 0x20, v215
	v_xor_b32_e32 v210, 0x20, v211
	v_xor_b32_e32 v213, 0x40, v215
	v_xor_b32_e32 v209, 0x40, v211
	v_xor_b32_e32 v212, 0x60, v215
	v_xor_b32_e32 v208, 0x60, v211
	v_bfe_u32 v200, v201, 4, 3
	v_and_b32_e32 v206, 7, v201
	v_xor_b32_e32 v200, v200, v206
	v_lshlrev_b32_e32 v200, 4, v200
	v_lshrrev_b32_e32 v206, 3, v201
	v_lshl_or_b32 v207, v206, 11, v200
	v_add_u32_e32 v206, 0x10000, v207
	v_add_u32_e32 v205, 0x20000, v207
	v_add_u32_e32 v204, 0x30000, v207
	v_add_u32_e32 v203, 0x40000, v207
	v_add_u32_e32 v202, 0x50000, v207
	s_lshr_b32 s83, s35, 6
	s_and_b32 s84, s35, 63
	s_mov_b32 s79, 0
	s_mul_i32 s84, s84, 0x60000
	s_lshl_b32 s83, s83, 18
	s_add_u32 s83, s83, 0x400000
	s_waitcnt lgkmcnt(0)
	s_add_u32 s66, s66, s84
	s_addc_u32 s67, s67, 0
	s_add_u32 s68, s68, s83
	s_addc_u32 s69, s69, 0
	s_add_u32 s83, s79, 0
	s_and_b32 s83, s83, 15
	s_lshl_b32 s83, s83, 7
	s_add_u32 s70, s66, s83
	s_addc_u32 s71, s67, 0
	s_add_u32 s72, s68, s83
	s_addc_u32 s73, s69, 0
	s_add_u32 s81, s80, 0x0
	s_add_u32 s82, s80, 0xc000
	s_add_u32 m0, s81, 0x0
	s_nop 0
	global_load_lds_dwordx4 v207, s[70:71]
	s_add_u32 m0, s81, 0x1000
	s_nop 0
	global_load_lds_dwordx4 v206, s[70:71]
	s_add_u32 m0, s81, 0x2000
	s_nop 0
	global_load_lds_dwordx4 v205, s[70:71]
	s_add_u32 m0, s81, 0x3000
	s_nop 0
	global_load_lds_dwordx4 v204, s[70:71]
	s_add_u32 m0, s81, 0x4000
	s_nop 0
	global_load_lds_dwordx4 v203, s[70:71]
	s_add_u32 m0, s81, 0x5000
	s_nop 0
	global_load_lds_dwordx4 v202, s[70:71]
	s_add_u32 m0, s82, 0x0
	s_nop 0
	global_load_lds_dwordx4 v207, s[72:73]
	s_add_u32 m0, s82, 0x1000
	s_nop 0
	global_load_lds_dwordx4 v206, s[72:73]
	s_add_u32 m0, s82, 0x2000
	s_nop 0
	global_load_lds_dwordx4 v205, s[72:73]
	s_add_u32 m0, s82, 0x3000
	s_nop 0
	global_load_lds_dwordx4 v204, s[72:73]
	s_add_u32 s83, s79, 1
	s_and_b32 s83, s83, 15
	s_lshl_b32 s83, s83, 7
	s_add_u32 s70, s66, s83
	s_addc_u32 s71, s67, 0
	s_add_u32 s72, s68, s83
	s_addc_u32 s73, s69, 0
	s_add_u32 s81, s80, 0x6000
	s_add_u32 s82, s80, 0x10000
	s_add_u32 m0, s81, 0x0
	s_nop 0
	global_load_lds_dwordx4 v207, s[70:71]
	s_add_u32 m0, s81, 0x1000
	s_nop 0
	global_load_lds_dwordx4 v206, s[70:71]
	s_add_u32 m0, s81, 0x2000
	s_nop 0
	global_load_lds_dwordx4 v205, s[70:71]
	s_add_u32 m0, s81, 0x3000
	s_nop 0
	global_load_lds_dwordx4 v204, s[70:71]
	s_add_u32 m0, s81, 0x4000
	s_nop 0
	global_load_lds_dwordx4 v203, s[70:71]
	v_mov_b32_e32 v2, 0
	v_mov_b32_e32 v3, 0
	v_mov_b32_e32 v4, 0
	v_mov_b32_e32 v5, 0
	v_mov_b32_e32 v6, 0
	v_mov_b32_e32 v7, 0
	v_mov_b32_e32 v8, 0
	v_mov_b32_e32 v9, 0
	v_mov_b32_e32 v10, 0
	v_mov_b32_e32 v11, 0
	v_mov_b32_e32 v12, 0
	v_mov_b32_e32 v13, 0
	v_mov_b32_e32 v14, 0
	v_mov_b32_e32 v15, 0
	v_mov_b32_e32 v16, 0
	v_mov_b32_e32 v17, 0
	v_mov_b32_e32 v18, 0
	v_mov_b32_e32 v19, 0
	v_mov_b32_e32 v20, 0
	v_mov_b32_e32 v21, 0
	v_mov_b32_e32 v22, 0
	v_mov_b32_e32 v23, 0
	v_mov_b32_e32 v24, 0
	v_mov_b32_e32 v25, 0
	v_mov_b32_e32 v26, 0
	v_mov_b32_e32 v27, 0
	v_mov_b32_e32 v28, 0
	v_mov_b32_e32 v29, 0
	v_mov_b32_e32 v30, 0
	v_mov_b32_e32 v31, 0
	v_mov_b32_e32 v32, 0
	v_mov_b32_e32 v33, 0
	v_mov_b32_e32 v34, 0
	v_mov_b32_e32 v35, 0
	v_mov_b32_e32 v36, 0
	v_mov_b32_e32 v37, 0
	v_mov_b32_e32 v38, 0
	v_mov_b32_e32 v39, 0
	v_mov_b32_e32 v40, 0
	v_mov_b32_e32 v41, 0
	v_mov_b32_e32 v42, 0
	v_mov_b32_e32 v43, 0
	v_mov_b32_e32 v44, 0
	v_mov_b32_e32 v45, 0
	v_mov_b32_e32 v46, 0
	v_mov_b32_e32 v47, 0
	v_mov_b32_e32 v48, 0
	v_mov_b32_e32 v49, 0
	v_mov_b32_e32 v50, 0
	v_mov_b32_e32 v51, 0
	v_mov_b32_e32 v52, 0
	v_mov_b32_e32 v53, 0
	v_mov_b32_e32 v54, 0
	v_mov_b32_e32 v55, 0
	v_mov_b32_e32 v56, 0
	v_mov_b32_e32 v57, 0
	v_mov_b32_e32 v58, 0
	v_mov_b32_e32 v59, 0
	v_mov_b32_e32 v60, 0
	v_mov_b32_e32 v61, 0
	v_mov_b32_e32 v62, 0
	v_mov_b32_e32 v63, 0
	v_mov_b32_e32 v64, 0
	v_mov_b32_e32 v65, 0
	v_mov_b32_e32 v66, 0
	v_mov_b32_e32 v67, 0
	v_mov_b32_e32 v68, 0
	v_mov_b32_e32 v69, 0
	v_mov_b32_e32 v70, 0
	v_mov_b32_e32 v71, 0
	v_mov_b32_e32 v72, 0
	v_mov_b32_e32 v73, 0
	v_mov_b32_e32 v74, 0
	v_mov_b32_e32 v75, 0
	v_mov_b32_e32 v76, 0
	v_mov_b32_e32 v77, 0
	v_mov_b32_e32 v78, 0
	v_mov_b32_e32 v79, 0
	v_mov_b32_e32 v80, 0
	v_mov_b32_e32 v81, 0
	v_mov_b32_e32 v82, 0
	v_mov_b32_e32 v83, 0
	v_mov_b32_e32 v84, 0
	v_mov_b32_e32 v85, 0
	v_mov_b32_e32 v86, 0
	v_mov_b32_e32 v87, 0
	v_mov_b32_e32 v88, 0
	v_mov_b32_e32 v89, 0
	v_mov_b32_e32 v90, 0
	v_mov_b32_e32 v91, 0
	v_mov_b32_e32 v92, 0
	v_mov_b32_e32 v93, 0
	v_mov_b32_e32 v94, 0
	v_mov_b32_e32 v95, 0
	v_mov_b32_e32 v96, 0
	v_mov_b32_e32 v97, 0
	s_waitcnt vmcnt(5)
	s_barrier
	ds_read_b128 v[240:243], v211 offset:0
	ds_read_b128 v[252:255], v215 offset:0
	ds_read_b128 v[236:239], v211 offset:4096
	ds_read_b128 v[248:251], v215 offset:4096
	ds_read_b128 v[244:247], v215 offset:8192
	s_mov_b32 s78, 0
.Lgm_ph17_loop:
	s_waitcnt lgkmcnt(1)
	v_mfma_f32_32x32x16_bf16 v[82:97], v[240:243], v[252:255], v[82:97]
	ds_read_b128 v[220:223], v210 offset:0
	s_add_u32 m0, s81, 0x5000
	s_nop 0
	global_load_lds_dwordx4 v202, s[70:71]
	v_mfma_f32_32x32x16_bf16 v[66:81], v[236:239], v[252:255], v[66:81]
	ds_read_b128 v[232:235], v214 offset:0
	s_add_u32 m0, s82, 0x0
	s_nop 0
	global_load_lds_dwordx4 v207, s[72:73]
	v_mfma_f32_32x32x16_bf16 v[50:65], v[240:243], v[248:251], v[50:65]
	ds_read_b128 v[216:219], v210 offset:4096
	s_add_u32 m0, s82, 0x1000
	s_nop 0
	global_load_lds_dwordx4 v206, s[72:73]
	v_mfma_f32_32x32x16_bf16 v[34:49], v[236:239], v[248:251], v[34:49]
	ds_read_b128 v[228:231], v214 offset:4096
	s_add_u32 m0, s82, 0x2000
	s_nop 0
	global_load_lds_dwordx4 v205, s[72:73]
	s_waitcnt lgkmcnt(4)
	v_mfma_f32_32x32x16_bf16 v[18:33], v[240:243], v[244:247], v[18:33]
	ds_read_b128 v[224:227], v214 offset:8192
	v_mfma_f32_32x32x16_bf16 v[2:17], v[236:239], v[244:247], v[2:17]
	s_add_u32 m0, s82, 0x3000
	s_nop 0
	global_load_lds_dwordx4 v204, s[72:73]
	s_waitcnt lgkmcnt(1)
	v_mfma_f32_32x32x16_bf16 v[82:97], v[220:223], v[232:235], v[82:97]
	ds_read_b128 v[240:243], v209 offset:0
	v_mfma_f32_32x32x16_bf16 v[66:81], v[216:219], v[232:235], v[66:81]
	ds_read_b128 v[252:255], v213 offset:0
	v_mfma_f32_32x32x16_bf16 v[50:65], v[220:223], v[228:231], v[50:65]
	ds_read_b128 v[236:239], v209 offset:4096
	v_mfma_f32_32x32x16_bf16 v[34:49], v[216:219], v[228:231], v[34:49]
	ds_read_b128 v[248:251], v213 offset:4096
	s_waitcnt lgkmcnt(4)
	v_mfma_f32_32x32x16_bf16 v[18:33], v[220:223], v[224:227], v[18:33]
	ds_read_b128 v[244:247], v213 offset:8192
	v_mfma_f32_32x32x16_bf16 v[2:17], v[216:219], v[224:227], v[2:17]
	s_waitcnt lgkmcnt(1)
	v_mfma_f32_32x32x16_bf16 v[82:97], v[240:243], v[252:255], v[82:97]
	ds_read_b128 v[220:223], v208 offset:0
	s_add_u32 s83, s79, s78
	s_add_u32 s83, s83, 2
	s_and_b32 s83, s83, 15
	v_mfma_f32_32x32x16_bf16 v[66:81], v[236:239], v[252:255], v[66:81]
	ds_read_b128 v[232:235], v212 offset:0
	s_lshl_b32 s83, s83, 7
	s_add_u32 s70, s66, s83
	v_mfma_f32_32x32x16_bf16 v[50:65], v[240:243], v[248:251], v[50:65]
	ds_read_b128 v[216:219], v208 offset:4096
	s_addc_u32 s71, s67, 0
	s_add_u32 s72, s68, s83
	v_mfma_f32_32x32x16_bf16 v[34:49], v[236:239], v[248:251], v[34:49]
	ds_read_b128 v[228:231], v212 offset:4096
	s_addc_u32 s73, s69, 0
	s_add_u32 s81, s80, 0x0
	s_add_u32 s82, s80, 0xc000
	s_waitcnt lgkmcnt(4)
	v_mfma_f32_32x32x16_bf16 v[18:33], v[240:243], v[244:247], v[18:33]
	ds_read_b128 v[224:227], v212 offset:8192
	v_mfma_f32_32x32x16_bf16 v[2:17], v[236:239], v[244:247], v[2:17]
	s_waitcnt vmcnt(0) lgkmcnt(0)
	s_barrier
	v_mfma_f32_32x32x16_bf16 v[82:97], v[220:223], v[232:235], v[82:97]
	s_add_u32 m0, s81, 0x0
	ds_read_b128 v[240:243], v211 offset:16384
	global_load_lds_dwordx4 v207, s[70:71]
	v_mfma_f32_32x32x16_bf16 v[66:81], v[216:219], v[232:235], v[66:81]
	s_add_u32 m0, s81, 0x1000
	ds_read_b128 v[252:255], v215 offset:24576
	global_load_lds_dwordx4 v206, s[70:71]
	v_mfma_f32_32x32x16_bf16 v[50:65], v[220:223], v[228:231], v[50:65]
	s_add_u32 m0, s81, 0x2000
	ds_read_b128 v[236:239], v211 offset:20480
	global_load_lds_dwordx4 v205, s[70:71]
	v_mfma_f32_32x32x16_bf16 v[34:49], v[216:219], v[228:231], v[34:49]
	s_add_u32 m0, s81, 0x3000
	ds_read_b128 v[248:251], v215 offset:28672
	global_load_lds_dwordx4 v204, s[70:71]
	v_mfma_f32_32x32x16_bf16 v[18:33], v[220:223], v[224:227], v[18:33]
	s_add_u32 m0, s81, 0x4000
	ds_read_b128 v[244:247], v215 offset:32768
	global_load_lds_dwordx4 v203, s[70:71]
	v_mfma_f32_32x32x16_bf16 v[2:17], v[216:219], v[224:227], v[2:17]
	s_waitcnt lgkmcnt(1)
	v_mfma_f32_32x32x16_bf16 v[82:97], v[240:243], v[252:255], v[82:97]
	ds_read_b128 v[220:223], v210 offset:16384
	s_add_u32 m0, s81, 0x5000
	s_nop 0
	global_load_lds_dwordx4 v202, s[70:71]
	v_mfma_f32_32x32x16_bf16 v[66:81], v[236:239], v[252:255], v[66:81]
	ds_read_b128 v[232:235], v214 offset:24576
	s_add_u32 m0, s82, 0x0
	s_nop 0
	global_load_lds_dwordx4 v207, s[72:73]
	v_mfma_f32_32x32x16_bf16 v[50:65], v[240:243], v[248:251], v[50:65]
	ds_read_b128 v[216:219], v210 offset:20480
	s_add_u32 m0, s82, 0x1000
	s_nop 0
	global_load_lds_dwordx4 v206, s[72:73]
	v_mfma_f32_32x32x16_bf16 v[34:49], v[236:239], v[248:251], v[34:49]
	ds_read_b128 v[228:231], v214 offset:28672
	s_add_u32 m0, s82, 0x2000
	s_nop 0
	global_load_lds_dwordx4 v205, s[72:73]
	s_waitcnt lgkmcnt(4)
	v_mfma_f32_32x32x16_bf16 v[18:33], v[240:243], v[244:247], v[18:33]
	ds_read_b128 v[224:227], v214 offset:32768
	v_mfma_f32_32x32x16_bf16 v[2:17], v[236:239], v[244:247], v[2:17]
	s_add_u32 m0, s82, 0x3000
	s_nop 0
	global_load_lds_dwordx4 v204, s[72:73]
	s_waitcnt lgkmcnt(1)
	v_mfma_f32_32x32x16_bf16 v[82:97], v[220:223], v[232:235], v[82:97]
	ds_read_b128 v[240:243], v209 offset:16384
	v_mfma_f32_32x32x16_bf16 v[66:81], v[216:219], v[232:235], v[66:81]
	ds_read_b128 v[252:255], v213 offset:24576
	v_mfma_f32_32x32x16_bf16 v[50:65], v[220:223], v[228:231], v[50:65]
	ds_read_b128 v[236:239], v209 offset:20480
	v_mfma_f32_32x32x16_bf16 v[34:49], v[216:219], v[228:231], v[34:49]
	ds_read_b128 v[248:251], v213 offset:28672
	s_waitcnt lgkmcnt(4)
	v_mfma_f32_32x32x16_bf16 v[18:33], v[220:223], v[224:227], v[18:33]
	ds_read_b128 v[244:247], v213 offset:32768
	v_mfma_f32_32x32x16_bf16 v[2:17], v[216:219], v[224:227], v[2:17]
	s_waitcnt lgkmcnt(1)
	v_mfma_f32_32x32x16_bf16 v[82:97], v[240:243], v[252:255], v[82:97]
	ds_read_b128 v[220:223], v208 offset:16384
	s_add_u32 s83, s79, s78
	s_add_u32 s83, s83, 3
	s_and_b32 s83, s83, 15
	v_mfma_f32_32x32x16_bf16 v[66:81], v[236:239], v[252:255], v[66:81]
	ds_read_b128 v[232:235], v212 offset:24576
	s_lshl_b32 s83, s83, 7
	s_add_u32 s70, s66, s83
	v_mfma_f32_32x32x16_bf16 v[50:65], v[240:243], v[248:251], v[50:65]
	ds_read_b128 v[216:219], v208 offset:20480
	s_addc_u32 s71, s67, 0
	s_add_u32 s72, s68, s83
	v_mfma_f32_32x32x16_bf16 v[34:49], v[236:239], v[248:251], v[34:49]
	ds_read_b128 v[228:231], v212 offset:28672
	s_addc_u32 s73, s69, 0
	s_add_u32 s81, s80, 0x6000
	s_add_u32 s82, s80, 0x10000
	s_waitcnt lgkmcnt(4)
	v_mfma_f32_32x32x16_bf16 v[18:33], v[240:243], v[244:247], v[18:33]
	ds_read_b128 v[224:227], v212 offset:32768
	v_mfma_f32_32x32x16_bf16 v[2:17], v[236:239], v[244:247], v[2:17]
	s_waitcnt vmcnt(0) lgkmcnt(0)
	s_barrier
	v_mfma_f32_32x32x16_bf16 v[82:97], v[220:223], v[232:235], v[82:97]
	s_add_u32 m0, s81, 0x0
	ds_read_b128 v[240:243], v211 offset:0
	global_load_lds_dwordx4 v207, s[70:71]
	v_mfma_f32_32x32x16_bf16 v[66:81], v[216:219], v[232:235], v[66:81]
	s_add_u32 m0, s81, 0x1000
	ds_read_b128 v[252:255], v215 offset:0
	global_load_lds_dwordx4 v206, s[70:71]
	v_mfma_f32_32x32x16_bf16 v[50:65], v[220:223], v[228:231], v[50:65]
	s_add_u32 m0, s81, 0x2000
	ds_read_b128 v[236:239], v211 offset:4096
	global_load_lds_dwordx4 v205, s[70:71]
	v_mfma_f32_32x32x16_bf16 v[34:49], v[216:219], v[228:231], v[34:49]
	s_add_u32 m0, s81, 0x3000
	ds_read_b128 v[248:251], v215 offset:4096
	global_load_lds_dwordx4 v204, s[70:71]
	v_mfma_f32_32x32x16_bf16 v[18:33], v[220:223], v[224:227], v[18:33]
	s_add_u32 m0, s81, 0x4000
	ds_read_b128 v[244:247], v215 offset:8192
	global_load_lds_dwordx4 v203, s[70:71]
	v_mfma_f32_32x32x16_bf16 v[2:17], v[216:219], v[224:227], v[2:17]
	s_add_u32 s78, s78, 2
	s_cmp_lt_u32 s78, 14
	s_cbranch_scc1 .Lgm_ph17_loop
	s_waitcnt lgkmcnt(1)
	v_mfma_f32_32x32x16_bf16 v[82:97], v[240:243], v[252:255], v[82:97]
	ds_read_b128 v[220:223], v210 offset:0
	s_add_u32 m0, s81, 0x5000
	s_nop 0
	global_load_lds_dwordx4 v202, s[70:71]
	v_mfma_f32_32x32x16_bf16 v[66:81], v[236:239], v[252:255], v[66:81]
	ds_read_b128 v[232:235], v214 offset:0
	s_add_u32 m0, s82, 0x0
	s_nop 0
	global_load_lds_dwordx4 v207, s[72:73]
	v_mfma_f32_32x32x16_bf16 v[50:65], v[240:243], v[248:251], v[50:65]
	ds_read_b128 v[216:219], v210 offset:4096
	s_add_u32 m0, s82, 0x1000
	s_nop 0
	global_load_lds_dwordx4 v206, s[72:73]
	v_mfma_f32_32x32x16_bf16 v[34:49], v[236:239], v[248:251], v[34:49]
	ds_read_b128 v[228:231], v214 offset:4096
	s_add_u32 m0, s82, 0x2000
	s_nop 0
	global_load_lds_dwordx4 v205, s[72:73]
	s_waitcnt lgkmcnt(4)
	v_mfma_f32_32x32x16_bf16 v[18:33], v[240:243], v[244:247], v[18:33]
	ds_read_b128 v[224:227], v214 offset:8192
	v_mfma_f32_32x32x16_bf16 v[2:17], v[236:239], v[244:247], v[2:17]
	s_add_u32 m0, s82, 0x3000
	s_nop 0
	global_load_lds_dwordx4 v204, s[72:73]
	s_waitcnt lgkmcnt(1)
	v_mfma_f32_32x32x16_bf16 v[82:97], v[220:223], v[232:235], v[82:97]
	ds_read_b128 v[240:243], v209 offset:0
	v_mfma_f32_32x32x16_bf16 v[66:81], v[216:219], v[232:235], v[66:81]
	ds_read_b128 v[252:255], v213 offset:0
	v_mfma_f32_32x32x16_bf16 v[50:65], v[220:223], v[228:231], v[50:65]
	ds_read_b128 v[236:239], v209 offset:4096
	v_mfma_f32_32x32x16_bf16 v[34:49], v[216:219], v[228:231], v[34:49]
	ds_read_b128 v[248:251], v213 offset:4096
	s_waitcnt lgkmcnt(4)
	v_mfma_f32_32x32x16_bf16 v[18:33], v[220:223], v[224:227], v[18:33]
	ds_read_b128 v[244:247], v213 offset:8192
	v_mfma_f32_32x32x16_bf16 v[2:17], v[216:219], v[224:227], v[2:17]
	s_waitcnt lgkmcnt(1)
	v_mfma_f32_32x32x16_bf16 v[82:97], v[240:243], v[252:255], v[82:97]
	ds_read_b128 v[220:223], v208 offset:0
	v_mfma_f32_32x32x16_bf16 v[66:81], v[236:239], v[252:255], v[66:81]
	ds_read_b128 v[232:235], v212 offset:0
	v_mfma_f32_32x32x16_bf16 v[50:65], v[240:243], v[248:251], v[50:65]
	ds_read_b128 v[216:219], v208 offset:4096
	v_mfma_f32_32x32x16_bf16 v[34:49], v[236:239], v[248:251], v[34:49]
	ds_read_b128 v[228:231], v212 offset:4096
	s_waitcnt lgkmcnt(4)
	v_mfma_f32_32x32x16_bf16 v[18:33], v[240:243], v[244:247], v[18:33]
	ds_read_b128 v[224:227], v212 offset:8192
	v_mfma_f32_32x32x16_bf16 v[2:17], v[236:239], v[244:247], v[2:17]
	s_waitcnt vmcnt(0) lgkmcnt(0)
	s_barrier
	v_mfma_f32_32x32x16_bf16 v[82:97], v[220:223], v[232:235], v[82:97]
	ds_read_b128 v[240:243], v211 offset:16384
	v_mfma_f32_32x32x16_bf16 v[66:81], v[216:219], v[232:235], v[66:81]
	ds_read_b128 v[252:255], v215 offset:24576
	v_mfma_f32_32x32x16_bf16 v[50:65], v[220:223], v[228:231], v[50:65]
	ds_read_b128 v[236:239], v211 offset:20480
	v_mfma_f32_32x32x16_bf16 v[34:49], v[216:219], v[228:231], v[34:49]
	ds_read_b128 v[248:251], v215 offset:28672
	v_mfma_f32_32x32x16_bf16 v[18:33], v[220:223], v[224:227], v[18:33]
	ds_read_b128 v[244:247], v215 offset:32768
	v_mfma_f32_32x32x16_bf16 v[2:17], v[216:219], v[224:227], v[2:17]
	s_waitcnt lgkmcnt(1)
	v_mfma_f32_32x32x16_bf16 v[82:97], v[240:243], v[252:255], v[82:97]
	ds_read_b128 v[220:223], v210 offset:16384
	v_mfma_f32_32x32x16_bf16 v[66:81], v[236:239], v[252:255], v[66:81]
	ds_read_b128 v[232:235], v214 offset:24576
	v_mfma_f32_32x32x16_bf16 v[50:65], v[240:243], v[248:251], v[50:65]
	ds_read_b128 v[216:219], v210 offset:20480
	v_mfma_f32_32x32x16_bf16 v[34:49], v[236:239], v[248:251], v[34:49]
	ds_read_b128 v[228:231], v214 offset:28672
	s_waitcnt lgkmcnt(4)
	v_mfma_f32_32x32x16_bf16 v[18:33], v[240:243], v[244:247], v[18:33]
	ds_read_b128 v[224:227], v214 offset:32768
	v_mfma_f32_32x32x16_bf16 v[2:17], v[236:239], v[244:247], v[2:17]
	s_waitcnt lgkmcnt(1)
	v_mfma_f32_32x32x16_bf16 v[82:97], v[220:223], v[232:235], v[82:97]
	ds_read_b128 v[240:243], v209 offset:16384
	v_mfma_f32_32x32x16_bf16 v[66:81], v[216:219], v[232:235], v[66:81]
	ds_read_b128 v[252:255], v213 offset:24576
	v_mfma_f32_32x32x16_bf16 v[50:65], v[220:223], v[228:231], v[50:65]
	ds_read_b128 v[236:239], v209 offset:20480
	v_mfma_f32_32x32x16_bf16 v[34:49], v[216:219], v[228:231], v[34:49]
	ds_read_b128 v[248:251], v213 offset:28672
	s_waitcnt lgkmcnt(4)
	v_mfma_f32_32x32x16_bf16 v[18:33], v[220:223], v[224:227], v[18:33]
	ds_read_b128 v[244:247], v213 offset:32768
	v_mfma_f32_32x32x16_bf16 v[2:17], v[216:219], v[224:227], v[2:17]
	s_waitcnt lgkmcnt(1)
	v_mfma_f32_32x32x16_bf16 v[82:97], v[240:243], v[252:255], v[82:97]
	ds_read_b128 v[220:223], v208 offset:16384
	v_mfma_f32_32x32x16_bf16 v[66:81], v[236:239], v[252:255], v[66:81]
	ds_read_b128 v[232:235], v212 offset:24576
	v_mfma_f32_32x32x16_bf16 v[50:65], v[240:243], v[248:251], v[50:65]
	ds_read_b128 v[216:219], v208 offset:20480
	v_mfma_f32_32x32x16_bf16 v[34:49], v[236:239], v[248:251], v[34:49]
	ds_read_b128 v[228:231], v212 offset:28672
	s_waitcnt lgkmcnt(4)
	v_mfma_f32_32x32x16_bf16 v[18:33], v[240:243], v[244:247], v[18:33]
	ds_read_b128 v[224:227], v212 offset:32768
	v_mfma_f32_32x32x16_bf16 v[2:17], v[236:239], v[244:247], v[2:17]
	s_waitcnt vmcnt(0) lgkmcnt(0)
	s_barrier
	v_mfma_f32_32x32x16_bf16 v[82:97], v[220:223], v[232:235], v[82:97]
	v_mfma_f32_32x32x16_bf16 v[66:81], v[216:219], v[232:235], v[66:81]
	v_mfma_f32_32x32x16_bf16 v[50:65], v[220:223], v[228:231], v[50:65]
	v_mfma_f32_32x32x16_bf16 v[34:49], v[216:219], v[228:231], v[34:49]
	v_mfma_f32_32x32x16_bf16 v[18:33], v[220:223], v[224:227], v[18:33]
	v_mfma_f32_32x32x16_bf16 v[2:17], v[216:219], v[224:227], v[2:17]
	s_nop 7
	s_nop 7
	v_add_u32_e32 v144, v116, v120
	s_nop 4
	v_add_u32_e32 v145, v116, v121
	s_nop 4
	v_add_u32_e32 v147, v116, v122
	s_nop 4
	v_or_b32_e32 v143, s5, v123
	s_nop 4
	v_cmp_lt_i32_e64 s[6:7], s3, v143
	s_nop 4
	v_add_u32_e32 v98, v118, v122
	s_nop 4
	s_waitcnt lgkmcnt(0)
	v_add_u32_e32 v106, s4, v115
	v_ashrrev_i32_e32 v107, 31, v106
	v_lshlrev_b64 v[110:111], 11, v[106:107]
	v_or_b32_e32 v104, v143, v124
	v_lshl_add_u64 v[108:109], s[10:11], 0, v[110:111]
	s_and_saveexec_b64 s[4:5], s[6:7]
	s_xor_b64 s[4:5], exec, s[4:5]
	s_cbranch_execz .LBB0_1996
	v_mul_f32_e32 v98, 0xbfb8aa3b, v82
	v_exp_f32_e32 v144, v98
	v_mul_f32_e32 v98, 0xbfb8aa3b, v83
	v_exp_f32_e32 v145, v98
	s_nop 0
	v_pk_add_f32 v[144:145], v[144:145], 1.0 op_sel_hi:[1,0]
	s_nop 0
	v_div_scale_f32 v98, s[30:31], v145, v145, v83
	v_rcp_f32_e32 v105, v98
	v_div_scale_f32 v107, vcc, v83, v145, v83
	v_fma_f32 v147, -v98, v105, 1.0
	v_fmac_f32_e32 v105, v147, v105
	v_mul_f32_e32 v147, v107, v105
	v_fma_f32 v149, -v98, v147, v107
	v_fmac_f32_e32 v147, v149, v105
	v_fma_f32 v98, -v98, v147, v107
	v_div_scale_f32 v107, s[30:31], v144, v144, v82
	v_rcp_f32_e32 v149, v107
	v_div_fmas_f32 v98, v98, v105, v147
	v_mul_f32_e32 v147, 0xbfb8aa3b, v84
	v_exp_f32_e32 v152, v147
	v_mul_f32_e32 v147, 0xbfb8aa3b, v85
	v_fma_f32 v105, -v107, v149, 1.0
	v_exp_f32_e32 v153, v147
	v_fmac_f32_e32 v149, v105, v149
	v_div_scale_f32 v105, vcc, v82, v144, v82
	v_div_fixup_f32 v98, v98, v145, v83
	v_mul_f32_e32 v145, v105, v149
	v_fma_f32 v147, -v107, v145, v105
	v_fmac_f32_e32 v145, v147, v149
	v_pk_add_f32 v[152:153], v[152:153], 1.0 op_sel_hi:[1,0]
	v_fma_f32 v105, -v107, v145, v105
	v_div_scale_f32 v107, s[30:31], v153, v153, v85
	v_rcp_f32_e32 v147, v107
	v_div_fmas_f32 v105, v105, v149, v145
	v_div_fixup_f32 v105, v105, v144, v82
	v_cvt_pk_bf16_f32 v144, v105, v98
	v_fma_f32 v98, -v107, v147, 1.0
	v_fmac_f32_e32 v147, v98, v147
	v_div_scale_f32 v98, vcc, v85, v153, v85
	v_mul_f32_e32 v105, v98, v147
	v_fma_f32 v145, -v107, v105, v98
	v_fmac_f32_e32 v105, v145, v147
	v_fma_f32 v98, -v107, v105, v98
	v_div_scale_f32 v107, s[30:31], v152, v152, v84
	v_rcp_f32_e32 v145, v107
	v_div_fmas_f32 v98, v98, v147, v105
	v_div_fixup_f32 v98, v98, v153, v85
	v_fma_f32 v105, -v107, v145, 1.0
	v_fmac_f32_e32 v145, v105, v145
	v_div_scale_f32 v105, vcc, v84, v152, v84
	v_mul_f32_e32 v147, v105, v145
	v_fma_f32 v149, -v107, v147, v105
	v_fmac_f32_e32 v147, v149, v145
	v_fma_f32 v105, -v107, v147, v105
	v_div_fmas_f32 v105, v105, v145, v147
	v_div_fixup_f32 v105, v105, v152, v84
	v_cvt_pk_bf16_f32 v145, v105, v98
	v_mov_b32_e32 v105, v99
	v_lshl_add_u64 v[152:153], v[104:105], 1, v[108:109]
	global_store_dwordx2 v[152:153], v[144:145], off offset:-2048

.LBB0_2331:
	s_ashr_i32 s10, s2, 31
	s_lshr_b32 s10, s10, 26
	s_add_i32 s10, s2, s10
	s_ashr_i32 s30, s10, 6
	s_and_b32 s10, s10, 0x3ffffc0
	s_sub_i32 s28, s2, s10
	s_mulk_i32 s28, 0xc0
	v_add_u32_e32 v2, s28, v108
	s_lshr_b32 s10, s28, 6
	s_lshl_b32 s29, s30, 7
	v_ashrrev_i32_e32 v3, 31, v2
	s_add_i32 s10, s10, s30
	v_lshlrev_b64 v[2:3], 11, v[2:3]
	v_or_b32_e32 v4, s29, v108
	s_lshl_b32 s30, s10, 6
	s_lshl_b32 s10, s10, 7
	v_ashrrev_i32_e32 v5, 31, v4
	v_lshl_add_u64 v[104:105], v[100:101], 0, v[2:3]
	s_and_b32 s10, s10, 0x780
	v_readfirstlane_b32 s31, v109
	v_lshlrev_b64 v[4:5], 11, v[4:5]
	v_lshl_add_u64 v[2:3], v[104:105], 0, s[10:11]
	s_mov_b32 m0, s31
	v_readfirstlane_b32 s31, v127
	v_lshl_add_u64 v[106:107], v[102:103], 0, v[4:5]
	s_waitcnt vmcnt(0)
	s_barrier
	s_load_dwordx2 s[66:67], s[0:1], 0x118
	s_load_dwordx2 s[68:69], s[0:1], 0xd0
	v_and_b32_e32 v201, 0x3ff, v0
	v_readfirstlane_b32 s80, v0
	v_and_b32_e32 v200, 31, v201
	v_bfe_u32 v214, v201, 1, 3
	v_bfe_u32 v213, v201, 5, 1
	v_xor_b32_e32 v214, v214, v213
	v_lshlrev_b32_e32 v214, 4, v214
	s_and_b32 s80, s80, 0x3ff
	s_lshr_b32 s83, s80, 6
	s_lshl_b32 s80, s80, 4
	s_lshr_b32 s84, s83, 1
	s_and_b32 s83, s83, 1
	s_mul_i32 s84, s84, 0x3000
	s_lshl_b32 s83, s83, 13
	s_add_u32 s83, s83, 0xc000
	v_lshlrev_b32_e32 v200, 7, v200
	v_or_b32_e32 v200, v200, v214
	v_add_u32_e32 v215, s84, v200
	v_add_u32_e32 v211, s83, v200
	v_xor_b32_e32 v214, 0x20, v215
	v_xor_b32_e32 v210, 0x20, v211
	v_xor_b32_e32 v213, 0x40, v215
	v_xor_b32_e32 v209, 0x40, v211
	v_xor_b32_e32 v212, 0x60, v215
	v_xor_b32_e32 v208, 0x60, v211
	v_bfe_u32 v200, v201, 4, 3
	v_and_b32_e32 v206, 7, v201
	v_xor_b32_e32 v200, v200, v206
	v_lshlrev_b32_e32 v200, 4, v200
	v_lshrrev_b32_e32 v206, 3, v201
	v_lshl_or_b32 v207, v206, 11, v200
	v_add_u32_e32 v206, 0x10000, v207
	v_add_u32_e32 v205, 0x20000, v207
	v_add_u32_e32 v204, 0x30000, v207
	v_add_u32_e32 v203, 0x40000, v207
	v_add_u32_e32 v202, 0x50000, v207
	s_lshr_b32 s83, s2, 6
	s_and_b32 s84, s2, 63
	s_mov_b32 s79, 0
	s_mul_i32 s84, s84, 0x60000
	s_lshl_b32 s83, s83, 18
	s_add_u32 s83, s83, 0x200000
	s_waitcnt lgkmcnt(0)
	s_add_u32 s66, s66, s84
	s_addc_u32 s67, s67, 0
	s_add_u32 s68, s68, s83
	s_addc_u32 s69, s69, 0
	s_add_u32 s83, s79, 0
	s_and_b32 s83, s83, 15
	s_lshl_b32 s83, s83, 7
	s_add_u32 s70, s66, s83
	s_addc_u32 s71, s67, 0
	s_add_u32 s72, s68, s83
	s_addc_u32 s73, s69, 0
	s_add_u32 s81, s80, 0x0
	s_add_u32 s82, s80, 0xc000
	s_add_u32 m0, s81, 0x0
	s_nop 0
	global_load_lds_dwordx4 v207, s[70:71]
	s_add_u32 m0, s81, 0x1000
	s_nop 0
	global_load_lds_dwordx4 v206, s[70:71]
	s_add_u32 m0, s81, 0x2000
	s_nop 0
	global_load_lds_dwordx4 v205, s[70:71]
	s_add_u32 m0, s81, 0x3000
	s_nop 0
	global_load_lds_dwordx4 v204, s[70:71]
	s_add_u32 m0, s81, 0x4000
	s_nop 0
	global_load_lds_dwordx4 v203, s[70:71]
	s_add_u32 m0, s81, 0x5000
	s_nop 0
	global_load_lds_dwordx4 v202, s[70:71]
	s_add_u32 m0, s82, 0x0
	s_nop 0
	global_load_lds_dwordx4 v207, s[72:73]
	s_add_u32 m0, s82, 0x1000
	s_nop 0
	global_load_lds_dwordx4 v206, s[72:73]
	s_add_u32 m0, s82, 0x2000
	s_nop 0
	global_load_lds_dwordx4 v205, s[72:73]
	s_add_u32 m0, s82, 0x3000
	s_nop 0
	global_load_lds_dwordx4 v204, s[72:73]
	s_add_u32 s83, s79, 1
	s_and_b32 s83, s83, 15
	s_lshl_b32 s83, s83, 7
	s_add_u32 s70, s66, s83
	s_addc_u32 s71, s67, 0
	s_add_u32 s72, s68, s83
	s_addc_u32 s73, s69, 0
	s_add_u32 s81, s80, 0x6000
	s_add_u32 s82, s80, 0x10000
	s_add_u32 m0, s81, 0x0
	s_nop 0
	global_load_lds_dwordx4 v207, s[70:71]
	s_add_u32 m0, s81, 0x1000
	s_nop 0
	global_load_lds_dwordx4 v206, s[70:71]
	s_add_u32 m0, s81, 0x2000
	s_nop 0
	global_load_lds_dwordx4 v205, s[70:71]
	s_add_u32 m0, s81, 0x3000
	s_nop 0
	global_load_lds_dwordx4 v204, s[70:71]
	s_add_u32 m0, s81, 0x4000
	s_nop 0
	global_load_lds_dwordx4 v203, s[70:71]
	v_mov_b32_e32 v2, 0
	v_mov_b32_e32 v3, 0
	v_mov_b32_e32 v4, 0
	v_mov_b32_e32 v5, 0
	v_mov_b32_e32 v6, 0
	v_mov_b32_e32 v7, 0
	v_mov_b32_e32 v8, 0
	v_mov_b32_e32 v9, 0
	v_mov_b32_e32 v10, 0
	v_mov_b32_e32 v11, 0
	v_mov_b32_e32 v12, 0
	v_mov_b32_e32 v13, 0
	v_mov_b32_e32 v14, 0
	v_mov_b32_e32 v15, 0
	v_mov_b32_e32 v16, 0
	v_mov_b32_e32 v17, 0
	v_mov_b32_e32 v18, 0
	v_mov_b32_e32 v19, 0
	v_mov_b32_e32 v20, 0
	v_mov_b32_e32 v21, 0
	v_mov_b32_e32 v22, 0
	v_mov_b32_e32 v23, 0
	v_mov_b32_e32 v24, 0
	v_mov_b32_e32 v25, 0
	v_mov_b32_e32 v26, 0
	v_mov_b32_e32 v27, 0
	v_mov_b32_e32 v28, 0
	v_mov_b32_e32 v29, 0
	v_mov_b32_e32 v30, 0
	v_mov_b32_e32 v31, 0
	v_mov_b32_e32 v32, 0
	v_mov_b32_e32 v33, 0
	v_mov_b32_e32 v34, 0
	v_mov_b32_e32 v35, 0
	v_mov_b32_e32 v36, 0
	v_mov_b32_e32 v37, 0
	v_mov_b32_e32 v38, 0
	v_mov_b32_e32 v39, 0
	v_mov_b32_e32 v40, 0
	v_mov_b32_e32 v41, 0
	v_mov_b32_e32 v42, 0
	v_mov_b32_e32 v43, 0
	v_mov_b32_e32 v44, 0
	v_mov_b32_e32 v45, 0
	v_mov_b32_e32 v46, 0
	v_mov_b32_e32 v47, 0
	v_mov_b32_e32 v48, 0
	v_mov_b32_e32 v49, 0
	v_mov_b32_e32 v50, 0
	v_mov_b32_e32 v51, 0
	v_mov_b32_e32 v52, 0
	v_mov_b32_e32 v53, 0
	v_mov_b32_e32 v54, 0
	v_mov_b32_e32 v55, 0
	v_mov_b32_e32 v56, 0
	v_mov_b32_e32 v57, 0
	v_mov_b32_e32 v58, 0
	v_mov_b32_e32 v59, 0
	v_mov_b32_e32 v60, 0
	v_mov_b32_e32 v61, 0
	v_mov_b32_e32 v62, 0
	v_mov_b32_e32 v63, 0
	v_mov_b32_e32 v64, 0
	v_mov_b32_e32 v65, 0
	v_mov_b32_e32 v66, 0
	v_mov_b32_e32 v67, 0
	v_mov_b32_e32 v68, 0
	v_mov_b32_e32 v69, 0
	v_mov_b32_e32 v70, 0
	v_mov_b32_e32 v71, 0
	v_mov_b32_e32 v72, 0
	v_mov_b32_e32 v73, 0
	v_mov_b32_e32 v74, 0
	v_mov_b32_e32 v75, 0
	v_mov_b32_e32 v76, 0
	v_mov_b32_e32 v77, 0
	v_mov_b32_e32 v78, 0
	v_mov_b32_e32 v79, 0
	v_mov_b32_e32 v80, 0
	v_mov_b32_e32 v81, 0
	v_mov_b32_e32 v82, 0
	v_mov_b32_e32 v83, 0
	v_mov_b32_e32 v84, 0
	v_mov_b32_e32 v85, 0
	v_mov_b32_e32 v86, 0
	v_mov_b32_e32 v87, 0
	v_mov_b32_e32 v88, 0
	v_mov_b32_e32 v89, 0
	v_mov_b32_e32 v90, 0
	v_mov_b32_e32 v91, 0
	v_mov_b32_e32 v92, 0
	v_mov_b32_e32 v93, 0
	v_mov_b32_e32 v94, 0
	v_mov_b32_e32 v95, 0
	v_mov_b32_e32 v96, 0
	v_mov_b32_e32 v97, 0
	s_waitcnt vmcnt(5)
	s_barrier
	ds_read_b128 v[240:243], v211 offset:0
	ds_read_b128 v[252:255], v215 offset:0
	ds_read_b128 v[236:239], v211 offset:4096
	ds_read_b128 v[248:251], v215 offset:4096
	ds_read_b128 v[244:247], v215 offset:8192
	s_mov_b32 s78, 0
.Lgm_ph20_loop:
	s_waitcnt lgkmcnt(1)
	v_mfma_f32_32x32x16_bf16 v[82:97], v[240:243], v[252:255], v[82:97]
	ds_read_b128 v[220:223], v210 offset:0
	s_add_u32 m0, s81, 0x5000
	s_nop 0
	global_load_lds_dwordx4 v202, s[70:71]
	v_mfma_f32_32x32x16_bf16 v[66:81], v[236:239], v[252:255], v[66:81]
	ds_read_b128 v[232:235], v214 offset:0
	s_add_u32 m0, s82, 0x0
	s_nop 0
	global_load_lds_dwordx4 v207, s[72:73]
	v_mfma_f32_32x32x16_bf16 v[50:65], v[240:243], v[248:251], v[50:65]
	ds_read_b128 v[216:219], v210 offset:4096
	s_add_u32 m0, s82, 0x1000
	s_nop 0
	global_load_lds_dwordx4 v206, s[72:73]
	v_mfma_f32_32x32x16_bf16 v[34:49], v[236:239], v[248:251], v[34:49]
	ds_read_b128 v[228:231], v214 offset:4096
	s_add_u32 m0, s82, 0x2000
	s_nop 0
	global_load_lds_dwordx4 v205, s[72:73]
	s_waitcnt lgkmcnt(4)
	v_mfma_f32_32x32x16_bf16 v[18:33], v[240:243], v[244:247], v[18:33]
	ds_read_b128 v[224:227], v214 offset:8192
	v_mfma_f32_32x32x16_bf16 v[2:17], v[236:239], v[244:247], v[2:17]
	s_add_u32 m0, s82, 0x3000
	s_nop 0
	global_load_lds_dwordx4 v204, s[72:73]
	s_waitcnt lgkmcnt(1)
	v_mfma_f32_32x32x16_bf16 v[82:97], v[220:223], v[232:235], v[82:97]
	ds_read_b128 v[240:243], v209 offset:0
	v_mfma_f32_32x32x16_bf16 v[66:81], v[216:219], v[232:235], v[66:81]
	ds_read_b128 v[252:255], v213 offset:0
	v_mfma_f32_32x32x16_bf16 v[50:65], v[220:223], v[228:231], v[50:65]
	ds_read_b128 v[236:239], v209 offset:4096
	v_mfma_f32_32x32x16_bf16 v[34:49], v[216:219], v[228:231], v[34:49]
	ds_read_b128 v[248:251], v213 offset:4096
	s_waitcnt lgkmcnt(4)
	v_mfma_f32_32x32x16_bf16 v[18:33], v[220:223], v[224:227], v[18:33]
	ds_read_b128 v[244:247], v213 offset:8192
	v_mfma_f32_32x32x16_bf16 v[2:17], v[216:219], v[224:227], v[2:17]
	s_waitcnt lgkmcnt(1)
	v_mfma_f32_32x32x16_bf16 v[82:97], v[240:243], v[252:255], v[82:97]
	ds_read_b128 v[220:223], v208 offset:0
	s_add_u32 s83, s79, s78
	s_add_u32 s83, s83, 2
	s_and_b32 s83, s83, 15
	v_mfma_f32_32x32x16_bf16 v[66:81], v[236:239], v[252:255], v[66:81]
	ds_read_b128 v[232:235], v212 offset:0
	s_lshl_b32 s83, s83, 7
	s_add_u32 s70, s66, s83
	v_mfma_f32_32x32x16_bf16 v[50:65], v[240:243], v[248:251], v[50:65]
	ds_read_b128 v[216:219], v208 offset:4096
	s_addc_u32 s71, s67, 0
	s_add_u32 s72, s68, s83
	v_mfma_f32_32x32x16_bf16 v[34:49], v[236:239], v[248:251], v[34:49]
	ds_read_b128 v[228:231], v212 offset:4096
	s_addc_u32 s73, s69, 0
	s_add_u32 s81, s80, 0x0
	s_add_u32 s82, s80, 0xc000
	s_waitcnt lgkmcnt(4)
	v_mfma_f32_32x32x16_bf16 v[18:33], v[240:243], v[244:247], v[18:33]
	ds_read_b128 v[224:227], v212 offset:8192
	v_mfma_f32_32x32x16_bf16 v[2:17], v[236:239], v[244:247], v[2:17]
	s_waitcnt vmcnt(0) lgkmcnt(0)
	s_barrier
	v_mfma_f32_32x32x16_bf16 v[82:97], v[220:223], v[232:235], v[82:97]
	s_add_u32 m0, s81, 0x0
	ds_read_b128 v[240:243], v211 offset:16384
	global_load_lds_dwordx4 v207, s[70:71]
	v_mfma_f32_32x32x16_bf16 v[66:81], v[216:219], v[232:235], v[66:81]
	s_add_u32 m0, s81, 0x1000
	ds_read_b128 v[252:255], v215 offset:24576
	global_load_lds_dwordx4 v206, s[70:71]
	v_mfma_f32_32x32x16_bf16 v[50:65], v[220:223], v[228:231], v[50:65]
	s_add_u32 m0, s81, 0x2000
	ds_read_b128 v[236:239], v211 offset:20480
	global_load_lds_dwordx4 v205, s[70:71]
	v_mfma_f32_32x32x16_bf16 v[34:49], v[216:219], v[228:231], v[34:49]
	s_add_u32 m0, s81, 0x3000
	ds_read_b128 v[248:251], v215 offset:28672
	global_load_lds_dwordx4 v204, s[70:71]
	v_mfma_f32_32x32x16_bf16 v[18:33], v[220:223], v[224:227], v[18:33]
	s_add_u32 m0, s81, 0x4000
	ds_read_b128 v[244:247], v215 offset:32768
	global_load_lds_dwordx4 v203, s[70:71]
	v_mfma_f32_32x32x16_bf16 v[2:17], v[216:219], v[224:227], v[2:17]
	s_waitcnt lgkmcnt(1)
	v_mfma_f32_32x32x16_bf16 v[82:97], v[240:243], v[252:255], v[82:97]
	ds_read_b128 v[220:223], v210 offset:16384
	s_add_u32 m0, s81, 0x5000
	s_nop 0
	global_load_lds_dwordx4 v202, s[70:71]
	v_mfma_f32_32x32x16_bf16 v[66:81], v[236:239], v[252:255], v[66:81]
	ds_read_b128 v[232:235], v214 offset:24576
	s_add_u32 m0, s82, 0x0
	s_nop 0
	global_load_lds_dwordx4 v207, s[72:73]
	v_mfma_f32_32x32x16_bf16 v[50:65], v[240:243], v[248:251], v[50:65]
	ds_read_b128 v[216:219], v210 offset:20480
	s_add_u32 m0, s82, 0x1000
	s_nop 0
	global_load_lds_dwordx4 v206, s[72:73]
	v_mfma_f32_32x32x16_bf16 v[34:49], v[236:239], v[248:251], v[34:49]
	ds_read_b128 v[228:231], v214 offset:28672
	s_add_u32 m0, s82, 0x2000
	s_nop 0
	global_load_lds_dwordx4 v205, s[72:73]
	s_waitcnt lgkmcnt(4)
	v_mfma_f32_32x32x16_bf16 v[18:33], v[240:243], v[244:247], v[18:33]
	ds_read_b128 v[224:227], v214 offset:32768
	v_mfma_f32_32x32x16_bf16 v[2:17], v[236:239], v[244:247], v[2:17]
	s_add_u32 m0, s82, 0x3000
	s_nop 0
	global_load_lds_dwordx4 v204, s[72:73]
	s_waitcnt lgkmcnt(1)
	v_mfma_f32_32x32x16_bf16 v[82:97], v[220:223], v[232:235], v[82:97]
	ds_read_b128 v[240:243], v209 offset:16384
	v_mfma_f32_32x32x16_bf16 v[66:81], v[216:219], v[232:235], v[66:81]
	ds_read_b128 v[252:255], v213 offset:24576
	v_mfma_f32_32x32x16_bf16 v[50:65], v[220:223], v[228:231], v[50:65]
	ds_read_b128 v[236:239], v209 offset:20480
	v_mfma_f32_32x32x16_bf16 v[34:49], v[216:219], v[228:231], v[34:49]
	ds_read_b128 v[248:251], v213 offset:28672
	s_waitcnt lgkmcnt(4)
	v_mfma_f32_32x32x16_bf16 v[18:33], v[220:223], v[224:227], v[18:33]
	ds_read_b128 v[244:247], v213 offset:32768
	v_mfma_f32_32x32x16_bf16 v[2:17], v[216:219], v[224:227], v[2:17]
	s_waitcnt lgkmcnt(1)
	v_mfma_f32_32x32x16_bf16 v[82:97], v[240:243], v[252:255], v[82:97]
	ds_read_b128 v[220:223], v208 offset:16384
	s_add_u32 s83, s79, s78
	s_add_u32 s83, s83, 3
	s_and_b32 s83, s83, 15
	v_mfma_f32_32x32x16_bf16 v[66:81], v[236:239], v[252:255], v[66:81]
	ds_read_b128 v[232:235], v212 offset:24576
	s_lshl_b32 s83, s83, 7
	s_add_u32 s70, s66, s83
	v_mfma_f32_32x32x16_bf16 v[50:65], v[240:243], v[248:251], v[50:65]
	ds_read_b128 v[216:219], v208 offset:20480
	s_addc_u32 s71, s67, 0
	s_add_u32 s72, s68, s83
	v_mfma_f32_32x32x16_bf16 v[34:49], v[236:239], v[248:251], v[34:49]
	ds_read_b128 v[228:231], v212 offset:28672
	s_addc_u32 s73, s69, 0
	s_add_u32 s81, s80, 0x6000
	s_add_u32 s82, s80, 0x10000
	s_waitcnt lgkmcnt(4)
	v_mfma_f32_32x32x16_bf16 v[18:33], v[240:243], v[244:247], v[18:33]
	ds_read_b128 v[224:227], v212 offset:32768
	v_mfma_f32_32x32x16_bf16 v[2:17], v[236:239], v[244:247], v[2:17]
	s_waitcnt vmcnt(0) lgkmcnt(0)
	s_barrier
	v_mfma_f32_32x32x16_bf16 v[82:97], v[220:223], v[232:235], v[82:97]
	s_add_u32 m0, s81, 0x0
	ds_read_b128 v[240:243], v211 offset:0
	global_load_lds_dwordx4 v207, s[70:71]
	v_mfma_f32_32x32x16_bf16 v[66:81], v[216:219], v[232:235], v[66:81]
	s_add_u32 m0, s81, 0x1000
	ds_read_b128 v[252:255], v215 offset:0
	global_load_lds_dwordx4 v206, s[70:71]
	v_mfma_f32_32x32x16_bf16 v[50:65], v[220:223], v[228:231], v[50:65]
	s_add_u32 m0, s81, 0x2000
	ds_read_b128 v[236:239], v211 offset:4096
	global_load_lds_dwordx4 v205, s[70:71]
	v_mfma_f32_32x32x16_bf16 v[34:49], v[216:219], v[228:231], v[34:49]
	s_add_u32 m0, s81, 0x3000
	ds_read_b128 v[248:251], v215 offset:4096
	global_load_lds_dwordx4 v204, s[70:71]
	v_mfma_f32_32x32x16_bf16 v[18:33], v[220:223], v[224:227], v[18:33]
	s_add_u32 m0, s81, 0x4000
	ds_read_b128 v[244:247], v215 offset:8192
	global_load_lds_dwordx4 v203, s[70:71]
	v_mfma_f32_32x32x16_bf16 v[2:17], v[216:219], v[224:227], v[2:17]
	s_add_u32 s78, s78, 2
	s_cmp_lt_u32 s78, 14
	s_cbranch_scc1 .Lgm_ph20_loop
	s_waitcnt lgkmcnt(1)
	v_mfma_f32_32x32x16_bf16 v[82:97], v[240:243], v[252:255], v[82:97]
	ds_read_b128 v[220:223], v210 offset:0
	s_add_u32 m0, s81, 0x5000
	s_nop 0
	global_load_lds_dwordx4 v202, s[70:71]
	v_mfma_f32_32x32x16_bf16 v[66:81], v[236:239], v[252:255], v[66:81]
	ds_read_b128 v[232:235], v214 offset:0
	s_add_u32 m0, s82, 0x0
	s_nop 0
	global_load_lds_dwordx4 v207, s[72:73]
	v_mfma_f32_32x32x16_bf16 v[50:65], v[240:243], v[248:251], v[50:65]
	ds_read_b128 v[216:219], v210 offset:4096
	s_add_u32 m0, s82, 0x1000
	s_nop 0
	global_load_lds_dwordx4 v206, s[72:73]
	v_mfma_f32_32x32x16_bf16 v[34:49], v[236:239], v[248:251], v[34:49]
	ds_read_b128 v[228:231], v214 offset:4096
	s_add_u32 m0, s82, 0x2000
	s_nop 0
	global_load_lds_dwordx4 v205, s[72:73]
	s_waitcnt lgkmcnt(4)
	v_mfma_f32_32x32x16_bf16 v[18:33], v[240:243], v[244:247], v[18:33]
	ds_read_b128 v[224:227], v214 offset:8192
	v_mfma_f32_32x32x16_bf16 v[2:17], v[236:239], v[244:247], v[2:17]
	s_add_u32 m0, s82, 0x3000
	s_nop 0
	global_load_lds_dwordx4 v204, s[72:73]
	s_waitcnt lgkmcnt(1)
	v_mfma_f32_32x32x16_bf16 v[82:97], v[220:223], v[232:235], v[82:97]
	ds_read_b128 v[240:243], v209 offset:0
	v_mfma_f32_32x32x16_bf16 v[66:81], v[216:219], v[232:235], v[66:81]
	ds_read_b128 v[252:255], v213 offset:0
	v_mfma_f32_32x32x16_bf16 v[50:65], v[220:223], v[228:231], v[50:65]
	ds_read_b128 v[236:239], v209 offset:4096
	v_mfma_f32_32x32x16_bf16 v[34:49], v[216:219], v[228:231], v[34:49]
	ds_read_b128 v[248:251], v213 offset:4096
	s_waitcnt lgkmcnt(4)
	v_mfma_f32_32x32x16_bf16 v[18:33], v[220:223], v[224:227], v[18:33]
	ds_read_b128 v[244:247], v213 offset:8192
	v_mfma_f32_32x32x16_bf16 v[2:17], v[216:219], v[224:227], v[2:17]
	s_waitcnt lgkmcnt(1)
	v_mfma_f32_32x32x16_bf16 v[82:97], v[240:243], v[252:255], v[82:97]
	ds_read_b128 v[220:223], v208 offset:0
	v_mfma_f32_32x32x16_bf16 v[66:81], v[236:239], v[252:255], v[66:81]
	ds_read_b128 v[232:235], v212 offset:0
	v_mfma_f32_32x32x16_bf16 v[50:65], v[240:243], v[248:251], v[50:65]
	ds_read_b128 v[216:219], v208 offset:4096
	v_mfma_f32_32x32x16_bf16 v[34:49], v[236:239], v[248:251], v[34:49]
	ds_read_b128 v[228:231], v212 offset:4096
	s_waitcnt lgkmcnt(4)
	v_mfma_f32_32x32x16_bf16 v[18:33], v[240:243], v[244:247], v[18:33]
	ds_read_b128 v[224:227], v212 offset:8192
	v_mfma_f32_32x32x16_bf16 v[2:17], v[236:239], v[244:247], v[2:17]
	s_waitcnt vmcnt(0) lgkmcnt(0)
	s_barrier
	v_mfma_f32_32x32x16_bf16 v[82:97], v[220:223], v[232:235], v[82:97]
	ds_read_b128 v[240:243], v211 offset:16384
	v_mfma_f32_32x32x16_bf16 v[66:81], v[216:219], v[232:235], v[66:81]
	ds_read_b128 v[252:255], v215 offset:24576
	v_mfma_f32_32x32x16_bf16 v[50:65], v[220:223], v[228:231], v[50:65]
	ds_read_b128 v[236:239], v211 offset:20480
	v_mfma_f32_32x32x16_bf16 v[34:49], v[216:219], v[228:231], v[34:49]
	ds_read_b128 v[248:251], v215 offset:28672
	v_mfma_f32_32x32x16_bf16 v[18:33], v[220:223], v[224:227], v[18:33]
	ds_read_b128 v[244:247], v215 offset:32768
	v_mfma_f32_32x32x16_bf16 v[2:17], v[216:219], v[224:227], v[2:17]
	s_waitcnt lgkmcnt(1)
	v_mfma_f32_32x32x16_bf16 v[82:97], v[240:243], v[252:255], v[82:97]
	ds_read_b128 v[220:223], v210 offset:16384
	v_mfma_f32_32x32x16_bf16 v[66:81], v[236:239], v[252:255], v[66:81]
	ds_read_b128 v[232:235], v214 offset:24576
	v_mfma_f32_32x32x16_bf16 v[50:65], v[240:243], v[248:251], v[50:65]
	ds_read_b128 v[216:219], v210 offset:20480
	v_mfma_f32_32x32x16_bf16 v[34:49], v[236:239], v[248:251], v[34:49]
	ds_read_b128 v[228:231], v214 offset:28672
	s_waitcnt lgkmcnt(4)
	v_mfma_f32_32x32x16_bf16 v[18:33], v[240:243], v[244:247], v[18:33]
	ds_read_b128 v[224:227], v214 offset:32768
	v_mfma_f32_32x32x16_bf16 v[2:17], v[236:239], v[244:247], v[2:17]
	s_waitcnt lgkmcnt(1)
	v_mfma_f32_32x32x16_bf16 v[82:97], v[220:223], v[232:235], v[82:97]
	ds_read_b128 v[240:243], v209 offset:16384
	v_mfma_f32_32x32x16_bf16 v[66:81], v[216:219], v[232:235], v[66:81]
	ds_read_b128 v[252:255], v213 offset:24576
	v_mfma_f32_32x32x16_bf16 v[50:65], v[220:223], v[228:231], v[50:65]
	ds_read_b128 v[236:239], v209 offset:20480
	v_mfma_f32_32x32x16_bf16 v[34:49], v[216:219], v[228:231], v[34:49]
	ds_read_b128 v[248:251], v213 offset:28672
	s_waitcnt lgkmcnt(4)
	v_mfma_f32_32x32x16_bf16 v[18:33], v[220:223], v[224:227], v[18:33]
	ds_read_b128 v[244:247], v213 offset:32768
	v_mfma_f32_32x32x16_bf16 v[2:17], v[216:219], v[224:227], v[2:17]
	s_waitcnt lgkmcnt(1)
	v_mfma_f32_32x32x16_bf16 v[82:97], v[240:243], v[252:255], v[82:97]
	ds_read_b128 v[220:223], v208 offset:16384
	v_mfma_f32_32x32x16_bf16 v[66:81], v[236:239], v[252:255], v[66:81]
	ds_read_b128 v[232:235], v212 offset:24576
	v_mfma_f32_32x32x16_bf16 v[50:65], v[240:243], v[248:251], v[50:65]
	ds_read_b128 v[216:219], v208 offset:20480
	v_mfma_f32_32x32x16_bf16 v[34:49], v[236:239], v[248:251], v[34:49]
	ds_read_b128 v[228:231], v212 offset:28672
	s_waitcnt lgkmcnt(4)
	v_mfma_f32_32x32x16_bf16 v[18:33], v[240:243], v[244:247], v[18:33]
	ds_read_b128 v[224:227], v212 offset:32768
	v_mfma_f32_32x32x16_bf16 v[2:17], v[236:239], v[244:247], v[2:17]
	s_waitcnt vmcnt(0) lgkmcnt(0)
	s_barrier
	v_mfma_f32_32x32x16_bf16 v[82:97], v[220:223], v[232:235], v[82:97]
	v_mfma_f32_32x32x16_bf16 v[66:81], v[216:219], v[232:235], v[66:81]
	v_mfma_f32_32x32x16_bf16 v[50:65], v[220:223], v[228:231], v[50:65]
	v_mfma_f32_32x32x16_bf16 v[34:49], v[216:219], v[228:231], v[34:49]
	v_mfma_f32_32x32x16_bf16 v[18:33], v[220:223], v[224:227], v[18:33]
	v_mfma_f32_32x32x16_bf16 v[2:17], v[216:219], v[224:227], v[2:17]
	s_nop 7
	s_nop 7
	s_waitcnt lgkmcnt(0)
	s_nop 10
	ds_write_b128 v145, v[82:85]
	ds_write_b128 v145, v[86:89] offset:32
	ds_write_b128 v145, v[90:93] offset:64
	ds_write_b128 v145, v[94:97] offset:96
	ds_write_b128 v145, v[66:69] offset:128
	ds_write_b128 v145, v[70:73] offset:160
	ds_write_b128 v145, v[74:77] offset:192
	ds_write_b128 v145, v[78:81] offset:224
	s_waitcnt lgkmcnt(0)
	v_add_u32_e32 v104, s28, v111
	v_or_b32_e32 v244, s29, v119
	v_lshlrev_b32_e32 v242, 2, v244
	v_add_u32_e32 v242, s3, v242
	v_lshlrev_b32_e32 v243, 1, v244
	v_mov_b32_e32 v240, v104
	v_add_u32_e32 v241, 0xfffff000, v240
	v_lshrrev_b32_e32 v241, 11, v241
	v_mad_u32_u24 v241, v241, s26, s26
	v_lshlrev_b32_e32 v241, 2, v241
	v_or_b32_e32 v232, v240, v1
	v_or_b32_e32 v233, v240, v120
	v_or_b32_e32 v234, v240, v121
	v_or_b32_e32 v235, v240, v122
	v_or_b32_e32 v236, v240, v123
	v_or_b32_e32 v237, v240, v124
	v_or_b32_e32 v238, v240, v125
	v_or_b32_e32 v239, v240, v126
	v_cmp_lt_i32_e64 s[82:83], s27, v232
	v_cmp_lt_i32_e64 s[84:85], s27, v233
	v_cmp_lt_i32_e64 s[86:87], s27, v234
	v_cmp_lt_i32_e64 s[88:89], s27, v235
	v_cmp_lt_i32_e64 s[90:91], s27, v236
	v_cmp_lt_i32_e64 s[92:93], s27, v237
	v_cmp_lt_i32_e64 s[94:95], s27, v238
	v_cmp_lt_i32_e64 s[96:97], s27, v239
	s_waitcnt lgkmcnt(0)
	v_cndmask_b32_e64 v200, 0, v241, s[82:83]
	v_cndmask_b32_e64 v204, 0, v241, s[84:85]
	v_cndmask_b32_e64 v208, 0, v241, s[86:87]
	v_cndmask_b32_e64 v212, 0, v241, s[88:89]
	v_cndmask_b32_e64 v216, 0, v241, s[90:91]
	v_cndmask_b32_e64 v220, 0, v241, s[92:93]
	v_cndmask_b32_e64 v224, 0, v241, s[94:95]
	v_cndmask_b32_e64 v228, 0, v241, s[96:97]
	v_add_u32_e32 v200, v200, v242
	v_add_u32_e32 v204, v204, v242
	v_add_u32_e32 v208, v208, v242
	v_add_u32_e32 v212, v212, v242
	v_add_u32_e32 v216, v216, v242
	v_add_u32_e32 v220, v220, v242
	v_add_u32_e32 v224, v224, v242
	v_add_u32_e32 v228, v228, v242
	ds_read_b128 v[82:85], v147
	global_load_dwordx4 v[200:203], v200, s[6:7]
	ds_read_b128 v[86:89], v147 offset:1088
	global_load_dwordx4 v[204:207], v204, s[6:7]
	ds_read_b128 v[90:93], v147 offset:2176
	global_load_dwordx4 v[208:211], v208, s[6:7]
	ds_read_b128 v[94:97], v147 offset:3264
	global_load_dwordx4 v[212:215], v212, s[6:7]
	ds_read_b128 v[66:69], v147 offset:4352
	global_load_dwordx4 v[216:219], v216, s[6:7]
	ds_read_b128 v[70:73], v147 offset:5440
	global_load_dwordx4 v[220:223], v220, s[6:7]
	ds_read_b128 v[74:77], v147 offset:6528
	global_load_dwordx4 v[224:227], v224, s[6:7]
	ds_read_b128 v[78:81], v147 offset:7616
	global_load_dwordx4 v[228:231], v228, s[6:7]
	v_lshl_add_u32 v232, v232, 11, v243
	v_lshl_add_u32 v233, v233, 11, v243
	v_lshl_add_u32 v234, v234, 11, v243
	v_lshl_add_u32 v235, v235, 11, v243
	v_lshl_add_u32 v236, v236, 11, v243
	v_lshl_add_u32 v237, v237, 11, v243
	v_lshl_add_u32 v238, v238, 11, v243
	v_lshl_add_u32 v239, v239, 11, v243
	s_waitcnt vmcnt(7) lgkmcnt(7)
	v_mul_f32_e32 v82, v82, v200
	v_mul_f32_e32 v83, v83, v201
	v_mul_f32_e32 v84, v84, v202
	v_mul_f32_e32 v85, v85, v203
	v_cvt_pk_bf16_f32 v82, v82, v83
	v_cvt_pk_bf16_f32 v83, v84, v85
	global_store_dwordx2 v232, v[82:83], s[4:5] sc1
	s_waitcnt vmcnt(7) lgkmcnt(6)
	v_mul_f32_e32 v86, v86, v204
	v_mul_f32_e32 v87, v87, v205
	v_mul_f32_e32 v88, v88, v206
	v_mul_f32_e32 v89, v89, v207
	v_cvt_pk_bf16_f32 v86, v86, v87
	v_cvt_pk_bf16_f32 v87, v88, v89
	global_store_dwordx2 v233, v[86:87], s[4:5] sc1
	s_waitcnt vmcnt(7) lgkmcnt(5)
	v_mul_f32_e32 v90, v90, v208
	v_mul_f32_e32 v91, v91, v209
	v_mul_f32_e32 v92, v92, v210
	v_mul_f32_e32 v93, v93, v211
	v_cvt_pk_bf16_f32 v90, v90, v91
	v_cvt_pk_bf16_f32 v91, v92, v93
	global_store_dwordx2 v234, v[90:91], s[4:5] sc1
	s_waitcnt vmcnt(7) lgkmcnt(4)
	v_mul_f32_e32 v94, v94, v212
	v_mul_f32_e32 v95, v95, v213
	v_mul_f32_e32 v96, v96, v214
	v_mul_f32_e32 v97, v97, v215
	v_cvt_pk_bf16_f32 v94, v94, v95
	v_cvt_pk_bf16_f32 v95, v96, v97
	global_store_dwordx2 v235, v[94:95], s[4:5] sc1
	s_waitcnt vmcnt(7) lgkmcnt(3)
	v_mul_f32_e32 v66, v66, v216
	v_mul_f32_e32 v67, v67, v217
	v_mul_f32_e32 v68, v68, v218
	v_mul_f32_e32 v69, v69, v219
	v_cvt_pk_bf16_f32 v66, v66, v67
	v_cvt_pk_bf16_f32 v67, v68, v69
	global_store_dwordx2 v236, v[66:67], s[4:5] sc1
	s_waitcnt vmcnt(7) lgkmcnt(2)
	v_mul_f32_e32 v70, v70, v220
	v_mul_f32_e32 v71, v71, v221
	v_mul_f32_e32 v72, v72, v222
	v_mul_f32_e32 v73, v73, v223
	v_cvt_pk_bf16_f32 v70, v70, v71
	v_cvt_pk_bf16_f32 v71, v72, v73
	global_store_dwordx2 v237, v[70:71], s[4:5] sc1
	s_waitcnt vmcnt(7) lgkmcnt(1)
	v_mul_f32_e32 v74, v74, v224
	v_mul_f32_e32 v75, v75, v225
	v_mul_f32_e32 v76, v76, v226
	v_mul_f32_e32 v77, v77, v227
	v_cvt_pk_bf16_f32 v74, v74, v75
	v_cvt_pk_bf16_f32 v75, v76, v77
	global_store_dwordx2 v238, v[74:75], s[4:5] sc1
	s_waitcnt vmcnt(7) lgkmcnt(0)
	v_mul_f32_e32 v78, v78, v228
	v_mul_f32_e32 v79, v79, v229
	v_mul_f32_e32 v80, v80, v230
	v_mul_f32_e32 v81, v81, v231
	v_cvt_pk_bf16_f32 v78, v78, v79
	v_cvt_pk_bf16_f32 v79, v80, v81
	global_store_dwordx2 v239, v[78:79], s[4:5] sc1
	ds_write_b128 v145, v[50:53]
	ds_write_b128 v145, v[54:57] offset:32
	ds_write_b128 v145, v[58:61] offset:64
	ds_write_b128 v145, v[62:65] offset:96
	ds_write_b128 v145, v[34:37] offset:128
	ds_write_b128 v145, v[38:41] offset:160
	ds_write_b128 v145, v[42:45] offset:192
	ds_write_b128 v145, v[46:49] offset:224
	v_add_u32_e32 v240, 0x20, v104
	v_add_u32_e32 v241, 0xfffff000, v240
	v_lshrrev_b32_e32 v241, 11, v241
	v_mad_u32_u24 v241, v241, s26, s26
	v_lshlrev_b32_e32 v241, 2, v241
	v_or_b32_e32 v232, v240, v1
	v_or_b32_e32 v233, v240, v120
	v_or_b32_e32 v234, v240, v121
	v_or_b32_e32 v235, v240, v122
	v_or_b32_e32 v236, v240, v123
	v_or_b32_e32 v237, v240, v124
	v_or_b32_e32 v238, v240, v125
	v_or_b32_e32 v239, v240, v126
	v_cmp_lt_i32_e64 s[82:83], s27, v232
	v_cmp_lt_i32_e64 s[84:85], s27, v233
	v_cmp_lt_i32_e64 s[86:87], s27, v234
	v_cmp_lt_i32_e64 s[88:89], s27, v235
	v_cmp_lt_i32_e64 s[90:91], s27, v236
	v_cmp_lt_i32_e64 s[92:93], s27, v237
	v_cmp_lt_i32_e64 s[94:95], s27, v238
	v_cmp_lt_i32_e64 s[96:97], s27, v239
	s_waitcnt lgkmcnt(0)
	v_cndmask_b32_e64 v200, 0, v241, s[82:83]
	v_cndmask_b32_e64 v204, 0, v241, s[84:85]
	v_cndmask_b32_e64 v208, 0, v241, s[86:87]
	v_cndmask_b32_e64 v212, 0, v241, s[88:89]
	v_cndmask_b32_e64 v216, 0, v241, s[90:91]
	v_cndmask_b32_e64 v220, 0, v241, s[92:93]
	v_cndmask_b32_e64 v224, 0, v241, s[94:95]
	v_cndmask_b32_e64 v228, 0, v241, s[96:97]
	v_add_u32_e32 v200, v200, v242
	v_add_u32_e32 v204, v204, v242
	v_add_u32_e32 v208, v208, v242
	v_add_u32_e32 v212, v212, v242
	v_add_u32_e32 v216, v216, v242
	v_add_u32_e32 v220, v220, v242
	v_add_u32_e32 v224, v224, v242
	v_add_u32_e32 v228, v228, v242
	ds_read_b128 v[50:53], v147
	global_load_dwordx4 v[200:203], v200, s[6:7]
	ds_read_b128 v[54:57], v147 offset:1088
	global_load_dwordx4 v[204:207], v204, s[6:7]
	ds_read_b128 v[58:61], v147 offset:2176
	global_load_dwordx4 v[208:211], v208, s[6:7]
	ds_read_b128 v[62:65], v147 offset:3264
	global_load_dwordx4 v[212:215], v212, s[6:7]
	ds_read_b128 v[34:37], v147 offset:4352
	global_load_dwordx4 v[216:219], v216, s[6:7]
	ds_read_b128 v[38:41], v147 offset:5440
	global_load_dwordx4 v[220:223], v220, s[6:7]
	ds_read_b128 v[42:45], v147 offset:6528
	global_load_dwordx4 v[224:227], v224, s[6:7]
	ds_read_b128 v[46:49], v147 offset:7616
	global_load_dwordx4 v[228:231], v228, s[6:7]
	v_lshl_add_u32 v232, v232, 11, v243
	v_lshl_add_u32 v233, v233, 11, v243
	v_lshl_add_u32 v234, v234, 11, v243
	v_lshl_add_u32 v235, v235, 11, v243
	v_lshl_add_u32 v236, v236, 11, v243
	v_lshl_add_u32 v237, v237, 11, v243
	v_lshl_add_u32 v238, v238, 11, v243
	v_lshl_add_u32 v239, v239, 11, v243
	s_waitcnt vmcnt(7) lgkmcnt(7)
	v_mul_f32_e32 v50, v50, v200
	v_mul_f32_e32 v51, v51, v201
	v_mul_f32_e32 v52, v52, v202
	v_mul_f32_e32 v53, v53, v203
	v_cvt_pk_bf16_f32 v50, v50, v51
	v_cvt_pk_bf16_f32 v51, v52, v53
	global_store_dwordx2 v232, v[50:51], s[4:5] sc1
	s_waitcnt vmcnt(7) lgkmcnt(6)
	v_mul_f32_e32 v54, v54, v204
	v_mul_f32_e32 v55, v55, v205
	v_mul_f32_e32 v56, v56, v206
	v_mul_f32_e32 v57, v57, v207
	v_cvt_pk_bf16_f32 v54, v54, v55
	v_cvt_pk_bf16_f32 v55, v56, v57
	global_store_dwordx2 v233, v[54:55], s[4:5] sc1
	s_waitcnt vmcnt(7) lgkmcnt(5)
	v_mul_f32_e32 v58, v58, v208
	v_mul_f32_e32 v59, v59, v209
	v_mul_f32_e32 v60, v60, v210
	v_mul_f32_e32 v61, v61, v211
	v_cvt_pk_bf16_f32 v58, v58, v59
	v_cvt_pk_bf16_f32 v59, v60, v61
	global_store_dwordx2 v234, v[58:59], s[4:5] sc1
	s_waitcnt vmcnt(7) lgkmcnt(4)
	v_mul_f32_e32 v62, v62, v212
	v_mul_f32_e32 v63, v63, v213
	v_mul_f32_e32 v64, v64, v214
	v_mul_f32_e32 v65, v65, v215
	v_cvt_pk_bf16_f32 v62, v62, v63
	v_cvt_pk_bf16_f32 v63, v64, v65
	global_store_dwordx2 v235, v[62:63], s[4:5] sc1
	s_waitcnt vmcnt(7) lgkmcnt(3)
	v_mul_f32_e32 v34, v34, v216
	v_mul_f32_e32 v35, v35, v217
	v_mul_f32_e32 v36, v36, v218
	v_mul_f32_e32 v37, v37, v219
	v_cvt_pk_bf16_f32 v34, v34, v35
	v_cvt_pk_bf16_f32 v35, v36, v37
	global_store_dwordx2 v236, v[34:35], s[4:5] sc1
	s_waitcnt vmcnt(7) lgkmcnt(2)
	v_mul_f32_e32 v38, v38, v220
	v_mul_f32_e32 v39, v39, v221
	v_mul_f32_e32 v40, v40, v222
	v_mul_f32_e32 v41, v41, v223
	v_cvt_pk_bf16_f32 v38, v38, v39
	v_cvt_pk_bf16_f32 v39, v40, v41
	global_store_dwordx2 v237, v[38:39], s[4:5] sc1
	s_waitcnt vmcnt(7) lgkmcnt(1)
	v_mul_f32_e32 v42, v42, v224
	v_mul_f32_e32 v43, v43, v225
	v_mul_f32_e32 v44, v44, v226
	v_mul_f32_e32 v45, v45, v227
	v_cvt_pk_bf16_f32 v42, v42, v43
	v_cvt_pk_bf16_f32 v43, v44, v45
	global_store_dwordx2 v238, v[42:43], s[4:5] sc1
	s_waitcnt vmcnt(7) lgkmcnt(0)
	v_mul_f32_e32 v46, v46, v228
	v_mul_f32_e32 v47, v47, v229
	v_mul_f32_e32 v48, v48, v230
	v_mul_f32_e32 v49, v49, v231
	v_cvt_pk_bf16_f32 v46, v46, v47
	v_cvt_pk_bf16_f32 v47, v48, v49
	global_store_dwordx2 v239, v[46:47], s[4:5] sc1
	ds_write_b128 v145, v[18:21]
	ds_write_b128 v145, v[22:25] offset:32
	ds_write_b128 v145, v[26:29] offset:64
	ds_write_b128 v145, v[30:33] offset:96
	ds_write_b128 v145, v[2:5] offset:128
	ds_write_b128 v145, v[6:9] offset:160
	ds_write_b128 v145, v[10:13] offset:192
	ds_write_b128 v145, v[14:17] offset:224
	v_add_u32_e32 v240, 0x40, v104
	v_add_u32_e32 v241, 0xfffff000, v240
	v_lshrrev_b32_e32 v241, 11, v241
	v_mad_u32_u24 v241, v241, s26, s26
	v_lshlrev_b32_e32 v241, 2, v241
	v_or_b32_e32 v232, v240, v1
	v_or_b32_e32 v233, v240, v120
	v_or_b32_e32 v234, v240, v121
	v_or_b32_e32 v235, v240, v122
	v_or_b32_e32 v236, v240, v123
	v_or_b32_e32 v237, v240, v124
	v_or_b32_e32 v238, v240, v125
	v_or_b32_e32 v239, v240, v126
	v_cmp_lt_i32_e64 s[82:83], s27, v232
	v_cmp_lt_i32_e64 s[84:85], s27, v233
	v_cmp_lt_i32_e64 s[86:87], s27, v234
	v_cmp_lt_i32_e64 s[88:89], s27, v235
	v_cmp_lt_i32_e64 s[90:91], s27, v236
	v_cmp_lt_i32_e64 s[92:93], s27, v237
	v_cmp_lt_i32_e64 s[94:95], s27, v238
	v_cmp_lt_i32_e64 s[96:97], s27, v239
	s_waitcnt lgkmcnt(0)
	v_cndmask_b32_e64 v200, 0, v241, s[82:83]
	v_cndmask_b32_e64 v204, 0, v241, s[84:85]
	v_cndmask_b32_e64 v208, 0, v241, s[86:87]
	v_cndmask_b32_e64 v212, 0, v241, s[88:89]
	v_cndmask_b32_e64 v216, 0, v241, s[90:91]
	v_cndmask_b32_e64 v220, 0, v241, s[92:93]
	v_cndmask_b32_e64 v224, 0, v241, s[94:95]
	v_cndmask_b32_e64 v228, 0, v241, s[96:97]
	v_add_u32_e32 v200, v200, v242
	v_add_u32_e32 v204, v204, v242
	v_add_u32_e32 v208, v208, v242
	v_add_u32_e32 v212, v212, v242
	v_add_u32_e32 v216, v216, v242
	v_add_u32_e32 v220, v220, v242
	v_add_u32_e32 v224, v224, v242
	v_add_u32_e32 v228, v228, v242
	ds_read_b128 v[18:21], v147
	global_load_dwordx4 v[200:203], v200, s[6:7]
	ds_read_b128 v[22:25], v147 offset:1088
	global_load_dwordx4 v[204:207], v204, s[6:7]
	ds_read_b128 v[26:29], v147 offset:2176
	global_load_dwordx4 v[208:211], v208, s[6:7]
	ds_read_b128 v[30:33], v147 offset:3264
	global_load_dwordx4 v[212:215], v212, s[6:7]
	ds_read_b128 v[2:5], v147 offset:4352
	global_load_dwordx4 v[216:219], v216, s[6:7]
	ds_read_b128 v[6:9], v147 offset:5440
	global_load_dwordx4 v[220:223], v220, s[6:7]
	ds_read_b128 v[10:13], v147 offset:6528
	global_load_dwordx4 v[224:227], v224, s[6:7]
	ds_read_b128 v[14:17], v147 offset:7616
	global_load_dwordx4 v[228:231], v228, s[6:7]
	v_lshl_add_u32 v232, v232, 11, v243
	v_lshl_add_u32 v233, v233, 11, v243
	v_lshl_add_u32 v234, v234, 11, v243
	v_lshl_add_u32 v235, v235, 11, v243
	v_lshl_add_u32 v236, v236, 11, v243
	v_lshl_add_u32 v237, v237, 11, v243
	v_lshl_add_u32 v238, v238, 11, v243
	v_lshl_add_u32 v239, v239, 11, v243
	s_waitcnt vmcnt(7) lgkmcnt(7)
	v_mul_f32_e32 v18, v18, v200
	v_mul_f32_e32 v19, v19, v201
	v_mul_f32_e32 v20, v20, v202
	v_mul_f32_e32 v21, v21, v203
	v_cvt_pk_bf16_f32 v18, v18, v19
	v_cvt_pk_bf16_f32 v19, v20, v21
	global_store_dwordx2 v232, v[18:19], s[4:5] sc1
	s_waitcnt vmcnt(7) lgkmcnt(6)
	v_mul_f32_e32 v22, v22, v204
	v_mul_f32_e32 v23, v23, v205
	v_mul_f32_e32 v24, v24, v206
	v_mul_f32_e32 v25, v25, v207
	v_cvt_pk_bf16_f32 v22, v22, v23
	v_cvt_pk_bf16_f32 v23, v24, v25
	global_store_dwordx2 v233, v[22:23], s[4:5] sc1
	s_waitcnt vmcnt(7) lgkmcnt(5)
	v_mul_f32_e32 v26, v26, v208
	v_mul_f32_e32 v27, v27, v209
	v_mul_f32_e32 v28, v28, v210
	v_mul_f32_e32 v29, v29, v211
	v_cvt_pk_bf16_f32 v26, v26, v27
	v_cvt_pk_bf16_f32 v27, v28, v29
	global_store_dwordx2 v234, v[26:27], s[4:5] sc1
	s_waitcnt vmcnt(7) lgkmcnt(4)
	v_mul_f32_e32 v30, v30, v212
	v_mul_f32_e32 v31, v31, v213
	v_mul_f32_e32 v32, v32, v214
	v_mul_f32_e32 v33, v33, v215
	v_cvt_pk_bf16_f32 v30, v30, v31
	v_cvt_pk_bf16_f32 v31, v32, v33
	global_store_dwordx2 v235, v[30:31], s[4:5] sc1
	s_waitcnt vmcnt(7) lgkmcnt(3)
	v_mul_f32_e32 v2, v2, v216
	v_mul_f32_e32 v3, v3, v217
	v_mul_f32_e32 v4, v4, v218
	v_mul_f32_e32 v5, v5, v219
	v_cvt_pk_bf16_f32 v2, v2, v3
	v_cvt_pk_bf16_f32 v3, v4, v5
	global_store_dwordx2 v236, v[2:3], s[4:5] sc1
	s_waitcnt vmcnt(7) lgkmcnt(2)
	v_mul_f32_e32 v6, v6, v220
	v_mul_f32_e32 v7, v7, v221
	v_mul_f32_e32 v8, v8, v222
	v_mul_f32_e32 v9, v9, v223
	v_cvt_pk_bf16_f32 v6, v6, v7
	v_cvt_pk_bf16_f32 v7, v8, v9
	global_store_dwordx2 v237, v[6:7], s[4:5] sc1
	s_waitcnt vmcnt(7) lgkmcnt(1)
	v_mul_f32_e32 v10, v10, v224
	v_mul_f32_e32 v11, v11, v225
	v_mul_f32_e32 v12, v12, v226
	v_mul_f32_e32 v13, v13, v227
	v_cvt_pk_bf16_f32 v10, v10, v11
	v_cvt_pk_bf16_f32 v11, v12, v13
	global_store_dwordx2 v238, v[10:11], s[4:5] sc1
	s_waitcnt vmcnt(7) lgkmcnt(0)
	v_mul_f32_e32 v14, v14, v228
	v_mul_f32_e32 v15, v15, v229
	v_mul_f32_e32 v16, v16, v230
	v_mul_f32_e32 v17, v17, v231
	v_cvt_pk_bf16_f32 v14, v14, v15
	v_cvt_pk_bf16_f32 v15, v16, v17
	global_store_dwordx2 v239, v[14:15], s[4:5] sc1
	s_waitcnt lgkmcnt(0)
	s_load_dword s10, s[8:9], 0x0
	s_waitcnt lgkmcnt(0)
	s_add_i32 s2, s10, s2
	s_cmpk_lt_i32 s2, 0x200
	s_cbranch_scc1 .LBB0_2331
